# W_in log-forget epilogue: the never-firing denormal / inf guards of logf(1+exp(-|a|)) (argument in [1,2]) deleted, 18 % fewer instructions on the phase's critical workgroups
# speedup vs baseline: 1.0125x; 1.0074x over previous
; __device__ __forceinline__ float silu_f(float x) { return x * __builtin_amdgcn_rcpf(1.f + __expf(-x)); }
; __device__ __forceinline__ v4u pack8(const f32x4 a, const f32x4 b) { v4u w; w.x = cvt_pk_bf16(a[0], a[1]); w.y = cvt_pk_bf16(a[2], a[3]); w.z = cvt_pk_bf16(b[0], b[1]); w.w = cvt_pk_bf16(b[2], b[3]); return w; }
;     __device__ __forceinline__ void operator()(const f32x4 (&acc)[2][2][4][2], const pg8::Unit& u, int wr, int wc, int fr, int fq) const {
;     ...
;         if (grp == 0) { WIN_LOOP( _Pragma("unroll") for (int i = 0; i < 4; ++i) { a[i] = silu_f(a[i]); b[i] = silu_f(b[i]); } *(v4u*)(QO + (size_t)row * DM + c) = pack8(a, b); ) }
;         else if (grp == 3) { WIN_LOOP( _Pragma("unroll") for (int i = 0; i < 4; ++i) { a[i] = silu_f(a[i]); b[i] = silu_f(b[i]); } *(v4u*)(GH + (size_t)row * 512 + c) = pack8(a, b); ) }
;         else if (grp == 1) {
;             f32x4 l0[2], l1[2];
; #pragma unroll
;             for (int bj = 0; bj < 2; ++bj) { l0[bj] = *(const f32x4*)(lb + cb + bj * 128); l1[bj] = *(const f32x4*)(lb + cb + bj * 128 + 4); }
;             WIN_LOOP( _Pragma("unroll") for (int i = 0; i < 4; ++i) { const float s0 = fminf(a[i], 0.f) - __logf(1.f + __expf(-fabsf(a[i]))), s1 = fminf(b[i], 0.f) - __logf(1.f + __expf(-fabsf(b[i]))); const float la = l0[bj][i], lbv = l1[bj][i];
;                     a[i] = la > 0.f ? __logf(la + (1.f - la) * __expf(s0)) : s0; b[i] = lbv > 0.f ? __logf(lbv + (1.f - lbv) * __expf(s1)) : s1; }
;                 *(f32x4*)(LF + (size_t)row * 512 + c) = a; *(f32x4*)(LF + (size_t)row * 512 + c + 4) = b; __builtin_amdgcn_sched_barrier(0); ) }
.LBB0_414:
	s_andn2_b64 vcc, exec, s[8:9]
	s_cbranch_vccnz .LBB0_416
	v_ashrrev_i32_e32 v167, 31, v166
	v_lshlrev_b64 v[128:129], 6, v[166:167]
	v_lshl_add_u64 v[128:129], v[160:161], 0, v[128:129]
	s_nop 0
	v_readlane_b32 s8, v255, 35
	v_lshlrev_b32_e32 v192, 2, v176
	v_readlane_b32 s9, v255, 36
	v_and_b32_e32 v133, 64, v215
	v_xor_b32_e32 v132, 16, v215
	v_lshl_add_u64 v[144:145], s[8:9], 0, v[192:193]
	flat_load_dwordx4 v[140:143], v[144:145]
	flat_load_dwordx4 v[136:139], v[144:145] offset:16
	v_add_u32_e32 v134, 64, v133
	v_cmp_lt_i32_e32 vcc, v132, v134
	v_lshlrev_b64 v[146:147], 11, v[166:167]
	v_readlane_b32 s50, v255, 45
	v_cndmask_b32_e32 v132, v215, v132, vcc
	v_lshlrev_b32_e32 v169, 2, v132
	v_readlane_b32 s51, v255, 46
	s_mov_b32 s95, s28
	s_mov_b32 s91, s29
	v_lshl_add_u64 v[170:171], s[50:51], 0, v[146:147]
	v_lshl_add_u64 v[170:171], v[170:171], 0, v[192:193]
	s_waitcnt vmcnt(0) lgkmcnt(0)
	s_nop 3
	v_xor_b32_e32 v130, 32, v215
	s_nop 1
	v_cmp_lt_i32_e32 vcc, v130, v134
	v_sub_f32_e32 v190, 1.0, v140
	v_sub_f32_e32 v191, 1.0, v136
	v_cndmask_b32_e32 v130, v215, v130, vcc
	v_lshlrev_b32_e32 v202, 2, v130
	s_waitcnt lgkmcnt(0)
	s_nop 1
	flat_load_dwordx4 v[132:135], v[144:145] offset:512
	flat_load_dwordx4 v[128:131], v[144:145] offset:528
	v_sub_f32_e32 v188, 1.0, v141
	v_cmp_lt_f32_e64 s[38:39], 0, v140
	v_cmp_lt_f32_e64 s[36:37], 0, v136
	s_waitcnt lgkmcnt(0)
	s_nop 1
	v_mov_b32_e32 v168, v250
	v_sub_f32_e32 v189, 1.0, v137
	v_cmp_lt_f32_e64 s[34:35], 0, v141
	v_cmp_lt_f32_e64 s[30:31], 0, v137
	v_pk_mul_f32 v[144:145], v[60:61], v[168:169] op_sel_hi:[1,0]
	v_pk_mul_f32 v[148:149], v[56:57], v[168:169] op_sel_hi:[1,0]
	v_min_f32_e32 v167, 0, v144
	v_mul_f32_e64 v144, |v144|, s57
	v_min_f32_e32 v177, 0, v148
	v_mul_f32_e64 v148, |v148|, s57
	v_exp_f32_e32 v144, v144
	v_exp_f32_e32 v148, v148
	v_min_f32_e32 v179, 0, v149
	v_mul_f32_e64 v149, |v149|, s57
	v_add_f32_e32 v144, 1.0, v144
	v_exp_f32_e32 v149, v149
	v_add_f32_e32 v148, 1.0, v148
	v_min_f32_e32 v178, 0, v145
	v_mul_f32_e64 v145, |v145|, s57
	v_exp_f32_e32 v145, v145
	v_log_f32_e32 v144, v144
	v_add_f32_e32 v149, 1.0, v149
	v_log_f32_e32 v148, v148
	v_add_f32_e32 v145, 1.0, v145
	v_mul_f32_e32 v183, 0x3f317217, v144
	v_mul_f32_e32 v184, 0x3f317217, v148
	v_fma_f32 v183, v144, s52, -v183
	v_fma_f32 v184, v148, s52, -v184
	v_fmac_f32_e32 v183, 0x3377d1cf, v144
	v_fmac_f32_e32 v184, 0x3377d1cf, v148
	v_fmac_f32_e32 v183, 0x3f317217, v144
	v_log_f32_e32 v145, v145
	v_fmac_f32_e32 v184, 0x3f317217, v148
	v_mov_b32_e32 v144, v183
	v_log_f32_e32 v149, v149
	v_mov_b32_e32 v148, v184
	v_sub_f32_e32 v144, v167, v144
	v_sub_f32_e32 v167, v177, v148
	v_mul_f32_e32 v148, 0x3fb8aa3b, v144
	v_mul_f32_e32 v185, 0x3f317217, v145
	v_mul_f32_e32 v177, 0x3fb8aa3b, v167
	v_exp_f32_e32 v148, v148
	v_mul_f32_e32 v186, 0x3f317217, v149
	v_fma_f32 v185, v145, s52, -v185
	v_exp_f32_e32 v177, v177
	v_fma_f32 v186, v149, s52, -v186
	v_fmac_f32_e32 v185, 0x3377d1cf, v145
	v_fmac_f32_e32 v186, 0x3377d1cf, v149
	v_fmac_f32_e32 v185, 0x3f317217, v145
	v_fmac_f32_e32 v186, 0x3f317217, v149
	v_fma_f32 v148, v190, v148, v140
	v_mov_b32_e32 v145, v185
	v_fma_f32 v177, v191, v177, v136
	v_cmp_gt_f32_e64 s[10:11], s97, v177
	v_mov_b32_e32 v149, v186
	v_cmp_gt_f32_e64 s[8:9], s97, v148
	v_cndmask_b32_e64 v181, 0, 32, s[10:11]
	v_ldexp_f32 v177, v177, v181
	v_cndmask_b32_e64 v180, 0, 32, s[8:9]
	v_ldexp_f32 v148, v148, v180
	v_log_f32_e32 v148, v148
	v_log_f32_e32 v177, v177
	v_sub_f32_e32 v145, v178, v145
	v_mul_f32_e32 v178, 0x3fb8aa3b, v145
	v_mul_f32_e32 v182, 0x3f317217, v148
	v_exp_f32_e32 v178, v178
	v_mul_f32_e32 v183, 0x3f317217, v177
	v_fma_f32 v182, v148, s52, -v182
	v_fma_f32 v183, v177, s52, -v183
	v_fmac_f32_e32 v182, 0x3377d1cf, v148
	v_cndmask_b32_e64 v180, 0, v216, s[8:9]
	v_fmac_f32_e32 v183, 0x3377d1cf, v177
	v_fmac_f32_e32 v182, 0x3f317217, v148
	v_cmp_lt_f32_e64 s[8:9], |v148|, s53
	v_fmac_f32_e32 v183, 0x3f317217, v177
	v_fma_f32 v178, v188, v178, v141
	v_cndmask_b32_e64 v148, v148, v182, s[8:9]
	v_cmp_lt_f32_e64 s[8:9], |v177|, s53
	v_cndmask_b32_e64 v181, 0, v216, s[10:11]
	v_sub_f32_e32 v148, v148, v180
	v_cndmask_b32_e64 v177, v177, v183, s[8:9]
	v_sub_f32_e32 v177, v177, v181
	v_cmp_gt_f32_e64 s[8:9], s97, v178
	v_cndmask_b32_e64 v148, v144, v148, s[38:39]
	v_cndmask_b32_e64 v144, v167, v177, s[36:37]
	v_cndmask_b32_e64 v167, 0, 32, s[8:9]
	v_ldexp_f32 v167, v178, v167
	v_log_f32_e32 v167, v167
	v_sub_f32_e32 v177, v179, v149
	v_mul_f32_e32 v178, 0x3fb8aa3b, v177
	v_exp_f32_e32 v178, v178
	v_mul_f32_e32 v149, 0x3f317217, v167
	v_fma_f32 v149, v167, s52, -v149
	v_fmac_f32_e32 v149, 0x3377d1cf, v167
	v_fmac_f32_e32 v149, 0x3f317217, v167
	v_cmp_lt_f32_e64 vcc, |v167|, s53
	v_fma_f32 v178, v189, v178, v137
	v_pk_mul_f32 v[150:151], v[62:63], v[168:169] op_sel_hi:[1,0]
	v_cndmask_b32_e32 v149, v167, v149, vcc
	v_cmp_gt_f32_e32 vcc, s97, v178
	v_cndmask_b32_e64 v167, 0, v216, s[8:9]
	v_sub_f32_e32 v149, v149, v167
	v_cndmask_b32_e64 v179, 0, 32, vcc
	v_ldexp_f32 v178, v178, v179
	v_log_f32_e32 v178, v178
	v_mul_f32_e64 v167, |v150|, s57
	v_exp_f32_e32 v167, v167
	v_cndmask_b32_e64 v149, v145, v149, s[34:35]
	v_mul_f32_e32 v145, 0x3f317217, v178
	v_fma_f32 v145, v178, s52, -v145
	v_fmac_f32_e32 v145, 0x3377d1cf, v178
	v_fmac_f32_e32 v145, 0x3f317217, v178
	v_cmp_lt_f32_e64 s[8:9], |v178|, s53
	v_add_f32_e32 v167, 1.0, v167
	v_pk_mul_f32 v[146:147], v[58:59], v[168:169] op_sel_hi:[1,0]
	v_cndmask_b32_e64 v145, v178, v145, s[8:9]
	v_cndmask_b32_e32 v178, 0, v216, vcc
	v_sub_f32_e32 v145, v145, v178
	v_cndmask_b32_e64 v145, v177, v145, s[30:31]
	v_log_f32_e32 v167, v167
; __device__ __forceinline__ float silu_f(float x) { return x * __builtin_amdgcn_rcpf(1.f + __expf(-x)); }
; __device__ __forceinline__ v4u pack8(const f32x4 a, const f32x4 b) { v4u w; w.x = cvt_pk_bf16(a[0], a[1]); w.y = cvt_pk_bf16(a[2], a[3]); w.z = cvt_pk_bf16(b[0], b[1]); w.w = cvt_pk_bf16(b[2], b[3]); return w; }
;     __device__ __forceinline__ void operator()(const f32x4 (&acc)[2][2][4][2], const pg8::Unit& u, int wr, int wc, int fr, int fq) const {
;     ...
;         if (grp == 0) { WIN_LOOP( _Pragma("unroll") for (int i = 0; i < 4; ++i) { a[i] = silu_f(a[i]); b[i] = silu_f(b[i]); } *(v4u*)(QO + (size_t)row * DM + c) = pack8(a, b); ) }
;         else if (grp == 3) { WIN_LOOP( _Pragma("unroll") for (int i = 0; i < 4; ++i) { a[i] = silu_f(a[i]); b[i] = silu_f(b[i]); } *(v4u*)(GH + (size_t)row * 512 + c) = pack8(a, b); ) }
;         else if (grp == 1) {
;             f32x4 l0[2], l1[2];
; #pragma unroll
;             for (int bj = 0; bj < 2; ++bj) { l0[bj] = *(const f32x4*)(lb + cb + bj * 128); l1[bj] = *(const f32x4*)(lb + cb + bj * 128 + 4); }
;             WIN_LOOP( _Pragma("unroll") for (int i = 0; i < 4; ++i) { const float s0 = fminf(a[i], 0.f) - __logf(1.f + __expf(-fabsf(a[i]))), s1 = fminf(b[i], 0.f) - __logf(1.f + __expf(-fabsf(b[i]))); const float la = l0[bj][i], lbv = l1[bj][i];
;                     a[i] = la > 0.f ? __logf(la + (1.f - la) * __expf(s0)) : s0; b[i] = lbv > 0.f ? __logf(lbv + (1.f - lbv) * __expf(s1)) : s1; }
;                 *(f32x4*)(LF + (size_t)row * 512 + c) = a; *(f32x4*)(LF + (size_t)row * 512 + c + 4) = b; __builtin_amdgcn_sched_barrier(0); ) }
	v_mul_f32_e64 v178, |v146|, s57
	v_exp_f32_e32 v178, v178
	v_min_f32_e32 v150, 0, v150
	v_mul_f32_e32 v177, 0x3f317217, v167
	v_fma_f32 v177, v167, s52, -v177
	v_fmac_f32_e32 v177, 0x3377d1cf, v167
	v_fmac_f32_e32 v177, 0x3f317217, v167
	v_add_f32_e32 v178, 1.0, v178
	v_sub_f32_e32 v187, 1.0, v142
	v_mov_b32_e32 v167, v177
	v_sub_f32_e32 v150, v150, v167
	v_log_f32_e32 v178, v178
	v_mul_f32_e32 v177, 0x3fb8aa3b, v150
	v_exp_f32_e32 v177, v177
	v_min_f32_e32 v146, 0, v146
	v_mul_f32_e32 v167, 0x3f317217, v178
	v_fma_f32 v167, v178, s52, -v167
	v_fmac_f32_e32 v167, 0x3377d1cf, v178
	v_fmac_f32_e32 v167, 0x3f317217, v178
	v_fma_f32 v177, v187, v177, v142
	v_sub_f32_e32 v186, 1.0, v138
	v_mov_b32_e32 v167, v167
	v_cmp_gt_f32_e64 s[8:9], s97, v177
	v_cmp_lt_f32_e64 s[28:29], 0, v142
	v_cmp_lt_f32_e64 s[26:27], 0, v138
	v_cndmask_b32_e64 v178, 0, 32, s[8:9]
	v_ldexp_f32 v177, v177, v178
	v_log_f32_e32 v177, v177
	v_sub_f32_e32 v146, v146, v167
	v_mul_f32_e32 v178, 0x3fb8aa3b, v146
	v_exp_f32_e32 v178, v178
	v_mul_f32_e32 v167, 0x3f317217, v177
	v_fma_f32 v167, v177, s52, -v167
	v_fmac_f32_e32 v167, 0x3377d1cf, v177
	v_fmac_f32_e32 v167, 0x3f317217, v177
	v_cmp_lt_f32_e64 vcc, |v177|, s53
	v_fma_f32 v178, v186, v178, v138
	v_sub_f32_e32 v185, 1.0, v143
	v_cndmask_b32_e32 v167, v177, v167, vcc
	v_cmp_gt_f32_e32 vcc, s97, v178
	v_cndmask_b32_e64 v177, 0, v216, s[8:9]
	v_sub_f32_e32 v167, v167, v177
	v_cndmask_b32_e64 v179, 0, 32, vcc
	v_ldexp_f32 v178, v178, v179
	v_log_f32_e32 v178, v178
	v_mul_f32_e64 v177, |v151|, s57
	v_exp_f32_e32 v177, v177
	v_cndmask_b32_e64 v150, v150, v167, s[28:29]
	v_mul_f32_e32 v167, 0x3f317217, v178
	v_fma_f32 v167, v178, s52, -v167
	v_fmac_f32_e32 v167, 0x3377d1cf, v178
	v_fmac_f32_e32 v167, 0x3f317217, v178
	v_cmp_lt_f32_e64 s[8:9], |v178|, s53
	v_add_f32_e32 v177, 1.0, v177
	v_min_f32_e32 v151, 0, v151
	v_cndmask_b32_e64 v167, v178, v167, s[8:9]
	v_cndmask_b32_e32 v178, 0, v216, vcc
	v_sub_f32_e32 v167, v167, v178
	v_cndmask_b32_e64 v146, v146, v167, s[26:27]
	v_log_f32_e32 v177, v177
	v_mul_f32_e64 v178, |v147|, s57
	v_exp_f32_e32 v178, v178
	v_min_f32_e32 v147, 0, v147
	v_mul_f32_e32 v167, 0x3f317217, v177
	v_fma_f32 v167, v177, s52, -v167
	v_fmac_f32_e32 v167, 0x3377d1cf, v177
	v_fmac_f32_e32 v167, 0x3f317217, v177
	v_add_f32_e32 v178, 1.0, v178
	v_sub_f32_e32 v184, 1.0, v139
	v_mov_b32_e32 v167, v167
	v_sub_f32_e32 v151, v151, v167
	v_log_f32_e32 v178, v178
	v_mul_f32_e32 v177, 0x3fb8aa3b, v151
	v_exp_f32_e32 v177, v177
	v_cmp_lt_f32_e64 s[24:25], 0, v143
	v_mul_f32_e32 v167, 0x3f317217, v178
	v_fma_f32 v167, v178, s52, -v167
	v_fmac_f32_e32 v167, 0x3377d1cf, v178
	v_fmac_f32_e32 v167, 0x3f317217, v178
	v_fma_f32 v177, v185, v177, v143
	v_cmp_lt_f32_e64 s[22:23], 0, v139
	v_mov_b32_e32 v167, v167
	v_cmp_gt_f32_e64 s[8:9], s97, v177
	s_nop 1
	v_cndmask_b32_e64 v178, 0, 32, s[8:9]
	v_ldexp_f32 v177, v177, v178
	v_log_f32_e32 v177, v177
	v_sub_f32_e32 v147, v147, v167
	v_mul_f32_e32 v178, 0x3fb8aa3b, v147
	v_exp_f32_e32 v178, v178
	v_mul_f32_e32 v167, 0x3f317217, v177
	v_fma_f32 v167, v177, s52, -v167
	v_fmac_f32_e32 v167, 0x3377d1cf, v177
	v_fmac_f32_e32 v167, 0x3f317217, v177
	v_cmp_lt_f32_e64 vcc, |v177|, s53
	v_fma_f32 v178, v184, v178, v139
	s_nop 0
	v_cndmask_b32_e32 v167, v177, v167, vcc
	v_cmp_gt_f32_e32 vcc, s97, v178
	v_cndmask_b32_e64 v177, 0, v216, s[8:9]
	v_sub_f32_e32 v167, v167, v177
	v_cndmask_b32_e64 v179, 0, 32, vcc
	v_ldexp_f32 v178, v178, v179
	v_log_f32_e32 v178, v178
	v_cndmask_b32_e64 v151, v151, v167, s[24:25]
	v_cndmask_b32_e32 v177, 0, v216, vcc
	v_mul_f32_e32 v167, 0x3f317217, v178
	v_fma_f32 v167, v178, s52, -v167
	v_fmac_f32_e32 v167, 0x3377d1cf, v178
	v_fmac_f32_e32 v167, 0x3f317217, v178
	v_cmp_lt_f32_e64 s[8:9], |v178|, s53
	s_nop 1
	v_cndmask_b32_e64 v167, v178, v167, s[8:9]
	v_sub_f32_e32 v167, v167, v177
	v_cndmask_b32_e64 v147, v147, v167, s[22:23]
	global_store_dwordx4 v[170:171], v[148:151], off
	global_store_dwordx4 v[170:171], v[144:147], off offset:16
	s_nop 1
	v_pk_mul_f32 v[144:145], v[124:125], v[168:169] op_sel_hi:[1,0]
	v_pk_mul_f32 v[150:151], v[126:127], v[168:169] op_sel_hi:[1,0]
	v_mul_f32_e64 v146, |v144|, s57
	v_exp_f32_e32 v148, v146
	v_pk_mul_f32 v[146:147], v[122:123], v[168:169] op_sel_hi:[1,0]
	v_min_f32_e32 v144, 0, v144
	s_waitcnt vmcnt(0)
; __device__ __forceinline__ float silu_f(float x) { return x * __builtin_amdgcn_rcpf(1.f + __expf(-x)); }
; __device__ __forceinline__ v4u pack8(const f32x4 a, const f32x4 b) { v4u w; w.x = cvt_pk_bf16(a[0], a[1]); w.y = cvt_pk_bf16(a[2], a[3]); w.z = cvt_pk_bf16(b[0], b[1]); w.w = cvt_pk_bf16(b[2], b[3]); return w; }
;     __device__ __forceinline__ void operator()(const f32x4 (&acc)[2][2][4][2], const pg8::Unit& u, int wr, int wc, int fr, int fq) const {
;     ...
;         if (grp == 0) { WIN_LOOP( _Pragma("unroll") for (int i = 0; i < 4; ++i) { a[i] = silu_f(a[i]); b[i] = silu_f(b[i]); } *(v4u*)(QO + (size_t)row * DM + c) = pack8(a, b); ) }
;         else if (grp == 3) { WIN_LOOP( _Pragma("unroll") for (int i = 0; i < 4; ++i) { a[i] = silu_f(a[i]); b[i] = silu_f(b[i]); } *(v4u*)(GH + (size_t)row * 512 + c) = pack8(a, b); ) }
;         else if (grp == 1) {
;             f32x4 l0[2], l1[2];
; #pragma unroll
;             for (int bj = 0; bj < 2; ++bj) { l0[bj] = *(const f32x4*)(lb + cb + bj * 128); l1[bj] = *(const f32x4*)(lb + cb + bj * 128 + 4); }
;             WIN_LOOP( _Pragma("unroll") for (int i = 0; i < 4; ++i) { const float s0 = fminf(a[i], 0.f) - __logf(1.f + __expf(-fabsf(a[i]))), s1 = fminf(b[i], 0.f) - __logf(1.f + __expf(-fabsf(b[i]))); const float la = l0[bj][i], lbv = l1[bj][i];
;                     a[i] = la > 0.f ? __logf(la + (1.f - la) * __expf(s0)) : s0; b[i] = lbv > 0.f ? __logf(lbv + (1.f - lbv) * __expf(s1)) : s1; }
;                 *(f32x4*)(LF + (size_t)row * 512 + c) = a; *(f32x4*)(LF + (size_t)row * 512 + c + 4) = b; __builtin_amdgcn_sched_barrier(0); ) }
	v_sub_f32_e32 v183, 1.0, v132
	v_add_f32_e32 v148, 1.0, v148
	v_sub_f32_e32 v182, 1.0, v128
	v_cmp_lt_f32_e64 s[20:21], 0, v132
	v_log_f32_e32 v167, v148
	v_pk_mul_f32 v[148:149], v[120:121], v[168:169] op_sel_hi:[1,0]
	v_cmp_lt_f32_e64 s[18:19], 0, v128
	v_mul_f32_e64 v168, |v148|, s57
	v_exp_f32_e32 v168, v168
	v_mul_f32_e32 v177, 0x3f317217, v167
	v_fma_f32 v177, v167, s52, -v177
	v_fmac_f32_e32 v177, 0x3377d1cf, v167
	v_fmac_f32_e32 v177, 0x3f317217, v167
	v_add_f32_e32 v168, 1.0, v168
	v_min_f32_e32 v148, 0, v148
	v_mov_b32_e32 v167, v177
	v_sub_f32_e32 v144, v144, v167
	v_log_f32_e32 v168, v168
	v_mul_f32_e32 v177, 0x3fb8aa3b, v144
	v_exp_f32_e32 v177, v177
	v_sub_f32_e32 v181, 1.0, v133
	v_mul_f32_e32 v167, 0x3f317217, v168
	v_fma_f32 v167, v168, s52, -v167
	v_fmac_f32_e32 v167, 0x3377d1cf, v168
	v_fmac_f32_e32 v167, 0x3f317217, v168
	v_sub_f32_e32 v180, 1.0, v129
	v_cmp_lt_f32_e64 s[16:17], 0, v133
	v_mov_b32_e32 v167, v167
	v_fma_f32 v168, v183, v177, v132
	v_cmp_gt_f32_e64 s[8:9], s97, v168
	v_cmp_lt_f32_e64 s[14:15], 0, v129
	v_sub_f32_e32 v179, 1.0, v134
	v_cndmask_b32_e64 v177, 0, 32, s[8:9]
	v_ldexp_f32 v168, v168, v177
	v_log_f32_e32 v168, v168
	v_sub_f32_e32 v148, v148, v167
	v_mul_f32_e32 v177, 0x3fb8aa3b, v148
	v_exp_f32_e32 v177, v177
	v_mul_f32_e32 v167, 0x3f317217, v168
	v_fma_f32 v167, v168, s52, -v167
	v_fmac_f32_e32 v167, 0x3377d1cf, v168
	v_fmac_f32_e32 v167, 0x3f317217, v168
	v_cmp_lt_f32_e64 vcc, |v168|, s53
	v_fma_f32 v177, v182, v177, v128
	v_cmp_lt_f32_e64 s[12:13], 0, v134
	v_cndmask_b32_e32 v167, v168, v167, vcc
	v_cmp_gt_f32_e32 vcc, s97, v177
	v_cndmask_b32_e64 v168, 0, v216, s[8:9]
	v_sub_f32_e32 v167, v167, v168
	v_cndmask_b32_e64 v178, 0, 32, vcc
	v_ldexp_f32 v177, v177, v178
	v_log_f32_e32 v177, v177
	v_mul_f32_e64 v168, |v145|, s57
	v_exp_f32_e32 v168, v168
	v_cndmask_b32_e64 v144, v144, v167, s[20:21]
	v_mul_f32_e32 v167, 0x3f317217, v177
	v_fma_f32 v167, v177, s52, -v167
	v_fmac_f32_e32 v167, 0x3377d1cf, v177
	v_fmac_f32_e32 v167, 0x3f317217, v177
	v_cmp_lt_f32_e64 s[8:9], |v177|, s53
	v_add_f32_e32 v168, 1.0, v168
	v_min_f32_e32 v145, 0, v145
	v_cndmask_b32_e64 v167, v177, v167, s[8:9]
	v_cndmask_b32_e32 v177, 0, v216, vcc
	v_sub_f32_e32 v167, v167, v177
	v_cndmask_b32_e64 v148, v148, v167, s[18:19]
	v_log_f32_e32 v168, v168
	v_mul_f32_e64 v177, |v149|, s57
	v_exp_f32_e32 v177, v177
	v_min_f32_e32 v149, 0, v149
	v_mul_f32_e32 v167, 0x3f317217, v168
	v_fma_f32 v167, v168, s52, -v167
	v_fmac_f32_e32 v167, 0x3377d1cf, v168
	v_fmac_f32_e32 v167, 0x3f317217, v168
	v_add_f32_e32 v177, 1.0, v177
	v_cmp_lt_f32_e64 s[10:11], 0, v130
	v_mov_b32_e32 v167, v167
	v_sub_f32_e32 v145, v145, v167
	v_log_f32_e32 v177, v177
	v_mul_f32_e32 v168, 0x3fb8aa3b, v145
	v_exp_f32_e32 v168, v168
	s_mov_b32 s2, s40
	v_mul_f32_e32 v167, 0x3f317217, v177
	v_fma_f32 v167, v177, s52, -v167
	v_fmac_f32_e32 v167, 0x3377d1cf, v177
	v_fmac_f32_e32 v167, 0x3f317217, v177
	v_fma_f32 v168, v181, v168, v133
	s_nop 0
	v_mov_b32_e32 v167, v167
	v_cmp_gt_f32_e64 s[8:9], s97, v168
	s_nop 1
	v_cndmask_b32_e64 v177, 0, 32, s[8:9]
	v_ldexp_f32 v168, v168, v177
	v_log_f32_e32 v168, v168
	v_sub_f32_e32 v149, v149, v167
	v_mul_f32_e32 v177, 0x3fb8aa3b, v149
	v_exp_f32_e32 v177, v177
	v_mul_f32_e32 v167, 0x3f317217, v168
	v_fma_f32 v167, v168, s52, -v167
	v_fmac_f32_e32 v167, 0x3377d1cf, v168
	v_fmac_f32_e32 v167, 0x3f317217, v168
	v_cmp_lt_f32_e64 vcc, |v168|, s53
	v_fma_f32 v177, v180, v177, v129
	s_nop 0
	v_cndmask_b32_e32 v167, v168, v167, vcc
	v_cmp_gt_f32_e32 vcc, s97, v177
	v_cndmask_b32_e64 v168, 0, v216, s[8:9]
	v_sub_f32_e32 v167, v167, v168
	v_cndmask_b32_e64 v178, 0, 32, vcc
	v_ldexp_f32 v177, v177, v178
	v_log_f32_e32 v177, v177
	v_mul_f32_e64 v168, |v150|, s57
	v_exp_f32_e32 v168, v168
	v_cndmask_b32_e64 v145, v145, v167, s[16:17]
	v_mul_f32_e32 v167, 0x3f317217, v177
	v_fma_f32 v167, v177, s52, -v167
	v_fmac_f32_e32 v167, 0x3377d1cf, v177
	v_fmac_f32_e32 v167, 0x3f317217, v177
	v_cmp_lt_f32_e64 s[8:9], |v177|, s53
	v_add_f32_e32 v168, 1.0, v168
	v_min_f32_e32 v150, 0, v150
	v_cndmask_b32_e64 v167, v177, v167, s[8:9]
	v_cndmask_b32_e32 v177, 0, v216, vcc
	v_sub_f32_e32 v167, v167, v177
	v_cndmask_b32_e64 v149, v149, v167, s[14:15]
	v_log_f32_e32 v168, v168
	v_mul_f32_e64 v177, |v146|, s57
	v_exp_f32_e32 v177, v177
	v_min_f32_e32 v146, 0, v146
	v_mul_f32_e32 v167, 0x3f317217, v168
	v_fma_f32 v167, v168, s52, -v167
	v_fmac_f32_e32 v167, 0x3377d1cf, v168
	v_fmac_f32_e32 v167, 0x3f317217, v168
	v_add_f32_e32 v177, 1.0, v177
	s_nop 0
	v_mov_b32_e32 v167, v167
	v_sub_f32_e32 v150, v150, v167
	v_log_f32_e32 v177, v177
	v_mul_f32_e32 v168, 0x3fb8aa3b, v150
	v_exp_f32_e32 v168, v168
	v_sub_f32_e32 v178, 1.0, v130
	v_mul_f32_e32 v167, 0x3f317217, v177
	v_fma_f32 v167, v177, s52, -v167
	v_fmac_f32_e32 v167, 0x3377d1cf, v177
	v_fmac_f32_e32 v167, 0x3f317217, v177
	v_fma_f32 v168, v179, v168, v134
	s_nop 0
	v_mov_b32_e32 v167, v167
	v_cmp_gt_f32_e64 s[8:9], s97, v168
	s_nop 1
	v_cndmask_b32_e64 v177, 0, 32, s[8:9]
	v_ldexp_f32 v168, v168, v177
	v_log_f32_e32 v168, v168
	v_sub_f32_e32 v167, v146, v167
	v_mul_f32_e32 v177, 0x3fb8aa3b, v167
	v_exp_f32_e32 v177, v177
	v_mul_f32_e32 v146, 0x3f317217, v168
	v_fma_f32 v146, v168, s52, -v146
	v_fmac_f32_e32 v146, 0x3377d1cf, v168
	v_fmac_f32_e32 v146, 0x3f317217, v168
	v_cmp_lt_f32_e64 vcc, |v168|, s53
	v_fma_f32 v177, v178, v177, v130
	s_nop 0
	v_cndmask_b32_e32 v146, v168, v146, vcc
	v_cmp_gt_f32_e32 vcc, s97, v177
	v_cndmask_b32_e64 v168, 0, v216, s[8:9]
	v_sub_f32_e32 v146, v146, v168
	v_cndmask_b32_e64 v194, 0, 32, vcc
	v_ldexp_f32 v177, v177, v194
	v_log_f32_e32 v177, v177
	v_mul_f32_e64 v168, |v151|, s57
; __device__ __forceinline__ float silu_f(float x) { return x * __builtin_amdgcn_rcpf(1.f + __expf(-x)); }
; __device__ __forceinline__ v4u pack8(const f32x4 a, const f32x4 b) { v4u w; w.x = cvt_pk_bf16(a[0], a[1]); w.y = cvt_pk_bf16(a[2], a[3]); w.z = cvt_pk_bf16(b[0], b[1]); w.w = cvt_pk_bf16(b[2], b[3]); return w; }
;     __device__ __forceinline__ void operator()(const f32x4 (&acc)[2][2][4][2], const pg8::Unit& u, int wr, int wc, int fr, int fq) const {
;     ...
;         if (grp == 0) { WIN_LOOP( _Pragma("unroll") for (int i = 0; i < 4; ++i) { a[i] = silu_f(a[i]); b[i] = silu_f(b[i]); } *(v4u*)(QO + (size_t)row * DM + c) = pack8(a, b); ) }
;         else if (grp == 3) { WIN_LOOP( _Pragma("unroll") for (int i = 0; i < 4; ++i) { a[i] = silu_f(a[i]); b[i] = silu_f(b[i]); } *(v4u*)(GH + (size_t)row * 512 + c) = pack8(a, b); ) }
;         else if (grp == 1) {
;             f32x4 l0[2], l1[2];
; #pragma unroll
;             for (int bj = 0; bj < 2; ++bj) { l0[bj] = *(const f32x4*)(lb + cb + bj * 128); l1[bj] = *(const f32x4*)(lb + cb + bj * 128 + 4); }
;             WIN_LOOP( _Pragma("unroll") for (int i = 0; i < 4; ++i) { const float s0 = fminf(a[i], 0.f) - __logf(1.f + __expf(-fabsf(a[i]))), s1 = fminf(b[i], 0.f) - __logf(1.f + __expf(-fabsf(b[i]))); const float la = l0[bj][i], lbv = l1[bj][i];
;                     a[i] = la > 0.f ? __logf(la + (1.f - la) * __expf(s0)) : s0; b[i] = lbv > 0.f ? __logf(lbv + (1.f - lbv) * __expf(s1)) : s1; }
;                 *(f32x4*)(LF + (size_t)row * 512 + c) = a; *(f32x4*)(LF + (size_t)row * 512 + c + 4) = b; __builtin_amdgcn_sched_barrier(0); ) }
	v_exp_f32_e32 v168, v168
	v_cndmask_b32_e64 v146, v150, v146, s[12:13]
	v_mul_f32_e32 v150, 0x3f317217, v177
	v_fma_f32 v150, v177, s52, -v150
	v_fmac_f32_e32 v150, 0x3377d1cf, v177
	v_fmac_f32_e32 v150, 0x3f317217, v177
	v_cmp_lt_f32_e64 s[8:9], |v177|, s53
	v_add_f32_e32 v168, 1.0, v168
	v_min_f32_e32 v151, 0, v151
	v_cndmask_b32_e64 v150, v177, v150, s[8:9]
	v_cndmask_b32_e32 v177, 0, v216, vcc
	v_sub_f32_e32 v150, v150, v177
	v_cndmask_b32_e64 v150, v167, v150, s[10:11]
	v_log_f32_e32 v168, v168
	v_mul_f32_e64 v177, |v147|, s57
	v_exp_f32_e32 v177, v177
	v_min_f32_e32 v147, 0, v147
	v_mul_f32_e32 v167, 0x3f317217, v168
	v_fma_f32 v167, v168, s52, -v167
	v_fmac_f32_e32 v167, 0x3377d1cf, v168
	v_fmac_f32_e32 v167, 0x3f317217, v168
	v_add_f32_e32 v177, 1.0, v177
	s_nop 0
	v_mov_b32_e32 v167, v167
	v_sub_f32_e32 v151, v151, v167
	v_log_f32_e32 v177, v177
	v_mul_f32_e32 v168, 0x3fb8aa3b, v151
	v_exp_f32_e32 v168, v168
	v_mul_f32_e32 v167, 0x3f317217, v177
	v_fma_f32 v167, v177, s52, -v167
	v_fmac_f32_e32 v167, 0x3377d1cf, v177
	v_fmac_f32_e32 v167, 0x3f317217, v177
	v_mov_b32_e32 v167, v167
	v_sub_f32_e32 v177, 1.0, v135
	v_fma_f32 v168, v177, v168, v135
	v_cmp_gt_f32_e64 s[8:9], s97, v168
	s_nop 1
	v_cndmask_b32_e64 v194, 0, 32, s[8:9]
	v_ldexp_f32 v168, v168, v194
	v_log_f32_e32 v168, v168
	v_sub_f32_e32 v194, v147, v167
	v_mul_f32_e32 v167, 0x3fb8aa3b, v194
	v_exp_f32_e32 v195, v167
	v_mul_f32_e32 v147, 0x3f317217, v168
	v_fma_f32 v147, v168, s52, -v147
	v_fmac_f32_e32 v147, 0x3377d1cf, v168
	v_sub_f32_e32 v167, 1.0, v131
	v_fmac_f32_e32 v147, 0x3f317217, v168
	v_cmp_lt_f32_e64 vcc, |v168|, s53
	v_fma_f32 v195, v167, v195, v131
	s_nop 0
	v_cndmask_b32_e32 v147, v168, v147, vcc
	v_cmp_gt_f32_e32 vcc, s97, v195
	v_cndmask_b32_e64 v168, 0, v216, s[8:9]
	v_sub_f32_e32 v147, v147, v168
	v_cndmask_b32_e64 v204, 0, 32, vcc
	v_ldexp_f32 v195, v195, v204
	v_log_f32_e32 v195, v195
	v_cmp_lt_f32_e64 s[8:9], 0, v135
	v_cndmask_b32_e32 v168, 0, v216, vcc
	v_cmp_lt_f32_e32 vcc, 0, v131
	v_cndmask_b32_e64 v147, v151, v147, s[8:9]
	v_mul_f32_e32 v151, 0x3f317217, v195
	v_fma_f32 v151, v195, s52, -v151
	v_fmac_f32_e32 v151, 0x3377d1cf, v195
	v_fmac_f32_e32 v151, 0x3f317217, v195
	v_cmp_lt_f32_e64 s[40:41], |v195|, s53
	s_nop 1
	v_cndmask_b32_e64 v151, v195, v151, s[40:41]
	v_sub_f32_e32 v151, v151, v168
	v_cndmask_b32_e32 v151, v194, v151, vcc
	global_store_dwordx4 v[170:171], v[144:147], off offset:512
	global_store_dwordx4 v[170:171], v[148:151], off offset:528
	s_nop 1
	v_or_b32_e32 v148, 16, v166
	v_ashrrev_i32_e32 v149, 31, v148
	v_lshlrev_b64 v[144:145], 6, v[148:149]
	v_lshl_add_u64 v[144:145], v[160:161], 0, v[144:145]
	s_nop 0
	s_waitcnt lgkmcnt(0)
	s_nop 3
	s_nop 0
	s_nop 1
	s_waitcnt lgkmcnt(0)
	s_nop 1
	s_waitcnt lgkmcnt(0)
	s_nop 1
	v_mov_b32_e32 v168, v251
	v_lshlrev_b64 v[144:145], 11, v[148:149]
	v_lshl_add_u64 v[170:171], s[50:51], 0, v[144:145]
	v_lshl_add_u64 v[170:171], v[170:171], 0, v[192:193]
	v_pk_mul_f32 v[148:149], v[52:53], v[168:169] op_sel_hi:[1,0]
	v_pk_mul_f32 v[144:145], v[48:49], v[168:169] op_sel_hi:[1,0]
	v_min_f32_e32 v194, 0, v148
	v_mul_f32_e64 v148, |v148|, s57
	v_exp_f32_e32 v148, v148
	v_pk_mul_f32 v[150:151], v[54:55], v[168:169] op_sel_hi:[1,0]
	v_pk_mul_f32 v[146:147], v[50:51], v[168:169] op_sel_hi:[1,0]
	v_add_f32_e32 v148, 1.0, v148
	v_log_f32_e32 v148, v148
	s_nop 0
	v_mul_f32_e32 v195, 0x3f317217, v148
	v_fma_f32 v195, v148, s52, -v195
	v_fmac_f32_e32 v195, 0x3377d1cf, v148
	v_fmac_f32_e32 v195, 0x3f317217, v148
	v_mov_b32_e32 v148, v195
	v_sub_f32_e32 v148, v194, v148
	v_min_f32_e32 v194, 0, v144
	v_mul_f32_e64 v144, |v144|, s57
	v_exp_f32_e32 v144, v144
	s_nop 0
	v_add_f32_e32 v144, 1.0, v144
	v_log_f32_e32 v144, v144
	s_nop 0
	v_mul_f32_e32 v195, 0x3f317217, v144
	v_fma_f32 v195, v144, s52, -v195
	v_fmac_f32_e32 v195, 0x3377d1cf, v144
	v_fmac_f32_e32 v195, 0x3f317217, v144
	v_mov_b32_e32 v144, v195
	v_sub_f32_e32 v194, v194, v144
	v_mul_f32_e32 v144, 0x3fb8aa3b, v148
	v_exp_f32_e32 v144, v144
	s_nop 0
	v_fma_f32 v144, v190, v144, v140
	v_cmp_gt_f32_e64 s[40:41], s97, v144
	s_nop 1
	v_cndmask_b32_e64 v195, 0, 32, s[40:41]
	v_ldexp_f32 v144, v144, v195
	v_log_f32_e32 v144, v144
	s_nop 0
	v_mul_f32_e32 v195, 0x3f317217, v144
	v_fma_f32 v195, v144, s52, -v195
	v_fmac_f32_e32 v195, 0x3377d1cf, v144
	v_fmac_f32_e32 v195, 0x3f317217, v144
	v_cmp_lt_f32_e64 s[42:43], |v144|, s53
	s_nop 1
	v_cndmask_b32_e64 v144, v144, v195, s[42:43]
	v_cndmask_b32_e64 v195, 0, v216, s[40:41]
	v_sub_f32_e32 v144, v144, v195
	v_cndmask_b32_e64 v144, v148, v144, s[38:39]
	v_mul_f32_e32 v148, 0x3fb8aa3b, v194
	v_exp_f32_e32 v148, v148
	s_nop 0
	v_fma_f32 v148, v191, v148, v136
	v_cmp_gt_f32_e64 s[40:41], s97, v148
	s_nop 1
	v_cndmask_b32_e64 v195, 0, 32, s[40:41]
	v_ldexp_f32 v148, v148, v195
	v_log_f32_e32 v148, v148
	s_nop 0
	v_mul_f32_e32 v195, 0x3f317217, v148
	v_fma_f32 v195, v148, s52, -v195
	v_fmac_f32_e32 v195, 0x3377d1cf, v148
	v_fmac_f32_e32 v195, 0x3f317217, v148
	v_cmp_lt_f32_e64 s[42:43], |v148|, s53
	s_nop 1
	v_cndmask_b32_e64 v148, v148, v195, s[42:43]
	v_cndmask_b32_e64 v195, 0, v216, s[40:41]
	v_sub_f32_e32 v148, v148, v195
	v_cndmask_b32_e64 v148, v194, v148, s[36:37]
	v_min_f32_e32 v194, 0, v149
	v_mul_f32_e64 v149, |v149|, s57
	v_exp_f32_e32 v149, v149
	s_nop 0
	v_add_f32_e32 v149, 1.0, v149
	v_log_f32_e32 v149, v149
	s_nop 0
	v_mul_f32_e32 v195, 0x3f317217, v149
	v_fma_f32 v195, v149, s52, -v195
	v_fmac_f32_e32 v195, 0x3377d1cf, v149
	v_fmac_f32_e32 v195, 0x3f317217, v149
	v_mov_b32_e32 v149, v195
	v_sub_f32_e32 v149, v194, v149
	v_min_f32_e32 v194, 0, v145
	v_mul_f32_e64 v145, |v145|, s57
	v_exp_f32_e32 v145, v145
; __device__ __forceinline__ float silu_f(float x) { return x * __builtin_amdgcn_rcpf(1.f + __expf(-x)); }
; __device__ __forceinline__ v4u pack8(const f32x4 a, const f32x4 b) { v4u w; w.x = cvt_pk_bf16(a[0], a[1]); w.y = cvt_pk_bf16(a[2], a[3]); w.z = cvt_pk_bf16(b[0], b[1]); w.w = cvt_pk_bf16(b[2], b[3]); return w; }
;     __device__ __forceinline__ void operator()(const f32x4 (&acc)[2][2][4][2], const pg8::Unit& u, int wr, int wc, int fr, int fq) const {
;     ...
;         if (grp == 0) { WIN_LOOP( _Pragma("unroll") for (int i = 0; i < 4; ++i) { a[i] = silu_f(a[i]); b[i] = silu_f(b[i]); } *(v4u*)(QO + (size_t)row * DM + c) = pack8(a, b); ) }
;         else if (grp == 3) { WIN_LOOP( _Pragma("unroll") for (int i = 0; i < 4; ++i) { a[i] = silu_f(a[i]); b[i] = silu_f(b[i]); } *(v4u*)(GH + (size_t)row * 512 + c) = pack8(a, b); ) }
;         else if (grp == 1) {
;             f32x4 l0[2], l1[2];
; #pragma unroll
;             for (int bj = 0; bj < 2; ++bj) { l0[bj] = *(const f32x4*)(lb + cb + bj * 128); l1[bj] = *(const f32x4*)(lb + cb + bj * 128 + 4); }
;             WIN_LOOP( _Pragma("unroll") for (int i = 0; i < 4; ++i) { const float s0 = fminf(a[i], 0.f) - __logf(1.f + __expf(-fabsf(a[i]))), s1 = fminf(b[i], 0.f) - __logf(1.f + __expf(-fabsf(b[i]))); const float la = l0[bj][i], lbv = l1[bj][i];
;                     a[i] = la > 0.f ? __logf(la + (1.f - la) * __expf(s0)) : s0; b[i] = lbv > 0.f ? __logf(lbv + (1.f - lbv) * __expf(s1)) : s1; }
;                 *(f32x4*)(LF + (size_t)row * 512 + c) = a; *(f32x4*)(LF + (size_t)row * 512 + c + 4) = b; __builtin_amdgcn_sched_barrier(0); ) }
	s_nop 0
	v_add_f32_e32 v145, 1.0, v145
	v_log_f32_e32 v145, v145
	s_nop 0
	v_mul_f32_e32 v195, 0x3f317217, v145
	v_fma_f32 v195, v145, s52, -v195
	v_fmac_f32_e32 v195, 0x3377d1cf, v145
	v_fmac_f32_e32 v195, 0x3f317217, v145
	v_mov_b32_e32 v145, v195
	v_sub_f32_e32 v194, v194, v145
	v_mul_f32_e32 v145, 0x3fb8aa3b, v149
	v_exp_f32_e32 v145, v145
	s_nop 0
	v_fma_f32 v145, v188, v145, v141
	v_cmp_gt_f32_e64 s[40:41], s97, v145
	s_nop 1
	v_cndmask_b32_e64 v195, 0, 32, s[40:41]
	v_ldexp_f32 v145, v145, v195
	v_log_f32_e32 v145, v145
	s_nop 0
	v_mul_f32_e32 v195, 0x3f317217, v145
	v_fma_f32 v195, v145, s52, -v195
	v_fmac_f32_e32 v195, 0x3377d1cf, v145
	v_fmac_f32_e32 v195, 0x3f317217, v145
	v_cmp_lt_f32_e64 s[42:43], |v145|, s53
	s_nop 1
	v_cndmask_b32_e64 v145, v145, v195, s[42:43]
	v_cndmask_b32_e64 v195, 0, v216, s[40:41]
	v_sub_f32_e32 v145, v145, v195
	v_cndmask_b32_e64 v145, v149, v145, s[34:35]
	v_mul_f32_e32 v149, 0x3fb8aa3b, v194
	v_exp_f32_e32 v149, v149
	s_nop 0
	v_fma_f32 v149, v189, v149, v137
	v_cmp_gt_f32_e64 s[40:41], s97, v149
	s_nop 1
	v_cndmask_b32_e64 v195, 0, 32, s[40:41]
	v_ldexp_f32 v149, v149, v195
	v_log_f32_e32 v149, v149
	s_nop 0
	v_mul_f32_e32 v195, 0x3f317217, v149
	v_fma_f32 v195, v149, s52, -v195
	v_fmac_f32_e32 v195, 0x3377d1cf, v149
	v_fmac_f32_e32 v195, 0x3f317217, v149
	v_cmp_lt_f32_e64 s[42:43], |v149|, s53
	s_nop 1
	v_cndmask_b32_e64 v149, v149, v195, s[42:43]
	v_cndmask_b32_e64 v195, 0, v216, s[40:41]
	v_sub_f32_e32 v149, v149, v195
	v_cndmask_b32_e64 v149, v194, v149, s[30:31]
	v_min_f32_e32 v194, 0, v150
	v_mul_f32_e64 v150, |v150|, s57
	v_exp_f32_e32 v150, v150
	s_nop 0
	v_add_f32_e32 v150, 1.0, v150
	v_log_f32_e32 v150, v150
	s_nop 0
	v_mul_f32_e32 v195, 0x3f317217, v150
	v_fma_f32 v195, v150, s52, -v195
	v_fmac_f32_e32 v195, 0x3377d1cf, v150
	v_fmac_f32_e32 v195, 0x3f317217, v150
	v_mov_b32_e32 v150, v195
	v_sub_f32_e32 v150, v194, v150
	v_min_f32_e32 v194, 0, v146
	v_mul_f32_e64 v146, |v146|, s57
	v_exp_f32_e32 v146, v146
	s_nop 0
	v_add_f32_e32 v146, 1.0, v146
	v_log_f32_e32 v146, v146
	s_nop 0
	v_mul_f32_e32 v195, 0x3f317217, v146
	v_fma_f32 v195, v146, s52, -v195
	v_fmac_f32_e32 v195, 0x3377d1cf, v146
	v_fmac_f32_e32 v195, 0x3f317217, v146
	v_mov_b32_e32 v146, v195
	v_sub_f32_e32 v194, v194, v146
	v_mul_f32_e32 v146, 0x3fb8aa3b, v150
	v_exp_f32_e32 v146, v146
	s_nop 0
	v_fma_f32 v146, v187, v146, v142
	v_cmp_gt_f32_e64 s[40:41], s97, v146
	s_nop 1
	v_cndmask_b32_e64 v195, 0, 32, s[40:41]
	v_ldexp_f32 v146, v146, v195
	v_log_f32_e32 v146, v146
	s_nop 0
	v_mul_f32_e32 v195, 0x3f317217, v146
	v_fma_f32 v195, v146, s52, -v195
	v_fmac_f32_e32 v195, 0x3377d1cf, v146
	v_fmac_f32_e32 v195, 0x3f317217, v146
	v_cmp_lt_f32_e64 s[42:43], |v146|, s53
	s_nop 1
	v_cndmask_b32_e64 v146, v146, v195, s[42:43]
	v_cndmask_b32_e64 v195, 0, v216, s[40:41]
	v_sub_f32_e32 v146, v146, v195
	v_cndmask_b32_e64 v146, v150, v146, s[28:29]
	v_mul_f32_e32 v150, 0x3fb8aa3b, v194
	v_exp_f32_e32 v150, v150
	s_nop 0
	v_fma_f32 v150, v186, v150, v138
	v_cmp_gt_f32_e64 s[40:41], s97, v150
	s_nop 1
	v_cndmask_b32_e64 v195, 0, 32, s[40:41]
	v_ldexp_f32 v150, v150, v195
	v_log_f32_e32 v150, v150
	s_nop 0
	v_mul_f32_e32 v195, 0x3f317217, v150
	v_fma_f32 v195, v150, s52, -v195
	v_fmac_f32_e32 v195, 0x3377d1cf, v150
	v_fmac_f32_e32 v195, 0x3f317217, v150
	v_cmp_lt_f32_e64 s[42:43], |v150|, s53
	s_nop 1
	v_cndmask_b32_e64 v150, v150, v195, s[42:43]
	v_cndmask_b32_e64 v195, 0, v216, s[40:41]
	v_sub_f32_e32 v150, v150, v195
	v_cndmask_b32_e64 v150, v194, v150, s[26:27]
	v_min_f32_e32 v194, 0, v151
	v_mul_f32_e64 v151, |v151|, s57
	v_exp_f32_e32 v151, v151
	s_nop 0
	v_add_f32_e32 v151, 1.0, v151
	v_log_f32_e32 v151, v151
	s_nop 0
	v_mul_f32_e32 v195, 0x3f317217, v151
	v_fma_f32 v195, v151, s52, -v195
	v_fmac_f32_e32 v195, 0x3377d1cf, v151
	v_fmac_f32_e32 v195, 0x3f317217, v151
	v_mov_b32_e32 v151, v195
	v_sub_f32_e32 v151, v194, v151
	v_min_f32_e32 v194, 0, v147
	v_mul_f32_e64 v147, |v147|, s57
	v_exp_f32_e32 v147, v147
	s_nop 0
	v_add_f32_e32 v147, 1.0, v147
	v_log_f32_e32 v147, v147
	s_nop 0
	v_mul_f32_e32 v195, 0x3f317217, v147
	v_fma_f32 v195, v147, s52, -v195
	v_fmac_f32_e32 v195, 0x3377d1cf, v147
	v_fmac_f32_e32 v195, 0x3f317217, v147
	v_mov_b32_e32 v147, v195
	v_sub_f32_e32 v194, v194, v147
	v_mul_f32_e32 v147, 0x3fb8aa3b, v151
	v_exp_f32_e32 v147, v147
	s_nop 0
	v_fma_f32 v147, v185, v147, v143
	v_cmp_gt_f32_e64 s[40:41], s97, v147
	s_nop 1
	v_cndmask_b32_e64 v195, 0, 32, s[40:41]
	v_ldexp_f32 v147, v147, v195
	v_log_f32_e32 v147, v147
	s_nop 0
	v_mul_f32_e32 v195, 0x3f317217, v147
	v_fma_f32 v195, v147, s52, -v195
	v_fmac_f32_e32 v195, 0x3377d1cf, v147
	v_fmac_f32_e32 v195, 0x3f317217, v147
	v_cmp_lt_f32_e64 s[42:43], |v147|, s53
	s_nop 1
	v_cndmask_b32_e64 v147, v147, v195, s[42:43]
	v_cndmask_b32_e64 v195, 0, v216, s[40:41]
	v_sub_f32_e32 v147, v147, v195
	v_cndmask_b32_e64 v147, v151, v147, s[24:25]
	v_mul_f32_e32 v151, 0x3fb8aa3b, v194
	v_exp_f32_e32 v151, v151
	s_nop 0
	v_fma_f32 v151, v184, v151, v139
	v_cmp_gt_f32_e64 s[40:41], s97, v151
	s_nop 1
	v_cndmask_b32_e64 v195, 0, 32, s[40:41]
	v_ldexp_f32 v151, v151, v195
	v_log_f32_e32 v151, v151
	s_nop 0
	v_mul_f32_e32 v195, 0x3f317217, v151
	v_fma_f32 v195, v151, s52, -v195
	v_fmac_f32_e32 v195, 0x3377d1cf, v151
	v_fmac_f32_e32 v195, 0x3f317217, v151
	v_cmp_lt_f32_e64 s[42:43], |v151|, s53
	s_nop 1
	v_cndmask_b32_e64 v151, v151, v195, s[42:43]
	v_cndmask_b32_e64 v195, 0, v216, s[40:41]
	v_sub_f32_e32 v151, v151, v195
	v_cndmask_b32_e64 v151, v194, v151, s[22:23]
	global_store_dwordx4 v[170:171], v[144:147], off
	global_store_dwordx4 v[170:171], v[148:151], off offset:16
	s_nop 1
; __device__ __forceinline__ float silu_f(float x) { return x * __builtin_amdgcn_rcpf(1.f + __expf(-x)); }
; __device__ __forceinline__ v4u pack8(const f32x4 a, const f32x4 b) { v4u w; w.x = cvt_pk_bf16(a[0], a[1]); w.y = cvt_pk_bf16(a[2], a[3]); w.z = cvt_pk_bf16(b[0], b[1]); w.w = cvt_pk_bf16(b[2], b[3]); return w; }
;     __device__ __forceinline__ void operator()(const f32x4 (&acc)[2][2][4][2], const pg8::Unit& u, int wr, int wc, int fr, int fq) const {
;     ...
;         if (grp == 0) { WIN_LOOP( _Pragma("unroll") for (int i = 0; i < 4; ++i) { a[i] = silu_f(a[i]); b[i] = silu_f(b[i]); } *(v4u*)(QO + (size_t)row * DM + c) = pack8(a, b); ) }
;         else if (grp == 3) { WIN_LOOP( _Pragma("unroll") for (int i = 0; i < 4; ++i) { a[i] = silu_f(a[i]); b[i] = silu_f(b[i]); } *(v4u*)(GH + (size_t)row * 512 + c) = pack8(a, b); ) }
;         else if (grp == 1) {
;             f32x4 l0[2], l1[2];
; #pragma unroll
;             for (int bj = 0; bj < 2; ++bj) { l0[bj] = *(const f32x4*)(lb + cb + bj * 128); l1[bj] = *(const f32x4*)(lb + cb + bj * 128 + 4); }
;             WIN_LOOP( _Pragma("unroll") for (int i = 0; i < 4; ++i) { const float s0 = fminf(a[i], 0.f) - __logf(1.f + __expf(-fabsf(a[i]))), s1 = fminf(b[i], 0.f) - __logf(1.f + __expf(-fabsf(b[i]))); const float la = l0[bj][i], lbv = l1[bj][i];
;                     a[i] = la > 0.f ? __logf(la + (1.f - la) * __expf(s0)) : s0; b[i] = lbv > 0.f ? __logf(lbv + (1.f - lbv) * __expf(s1)) : s1; }
;                 *(f32x4*)(LF + (size_t)row * 512 + c) = a; *(f32x4*)(LF + (size_t)row * 512 + c + 4) = b; __builtin_amdgcn_sched_barrier(0); ) }
	v_pk_mul_f32 v[148:149], v[116:117], v[168:169] op_sel_hi:[1,0]
	v_pk_mul_f32 v[150:151], v[118:119], v[168:169] op_sel_hi:[1,0]
	v_pk_mul_f32 v[146:147], v[114:115], v[168:169] op_sel_hi:[1,0]
	v_pk_mul_f32 v[144:145], v[112:113], v[168:169] op_sel_hi:[1,0]
	v_min_f32_e32 v168, 0, v148
	v_mul_f32_e64 v148, |v148|, s57
	v_exp_f32_e32 v148, v148
	s_nop 0
	v_add_f32_e32 v148, 1.0, v148
	v_log_f32_e32 v148, v148
	s_nop 0
	v_mul_f32_e32 v194, 0x3f317217, v148
	v_fma_f32 v194, v148, s52, -v194
	v_fmac_f32_e32 v194, 0x3377d1cf, v148
	v_fmac_f32_e32 v194, 0x3f317217, v148
	v_mov_b32_e32 v148, v194
	v_sub_f32_e32 v148, v168, v148
	v_min_f32_e32 v168, 0, v144
	v_mul_f32_e64 v144, |v144|, s57
	v_exp_f32_e32 v144, v144
	s_nop 0
	v_add_f32_e32 v144, 1.0, v144
	v_log_f32_e32 v144, v144
	s_nop 0
	v_mul_f32_e32 v194, 0x3f317217, v144
	v_fma_f32 v194, v144, s52, -v194
	v_fmac_f32_e32 v194, 0x3377d1cf, v144
	v_fmac_f32_e32 v194, 0x3f317217, v144
	v_mov_b32_e32 v144, v194
	v_sub_f32_e32 v168, v168, v144
	v_mul_f32_e32 v144, 0x3fb8aa3b, v148
	v_exp_f32_e32 v144, v144
	s_nop 0
	v_fma_f32 v144, v183, v144, v132
	v_cmp_gt_f32_e64 s[40:41], s97, v144
	s_nop 1
	v_cndmask_b32_e64 v194, 0, 32, s[40:41]
	v_ldexp_f32 v144, v144, v194
	v_log_f32_e32 v144, v144
	s_nop 0
	v_mul_f32_e32 v194, 0x3f317217, v144
	v_fma_f32 v194, v144, s52, -v194
	v_fmac_f32_e32 v194, 0x3377d1cf, v144
	v_fmac_f32_e32 v194, 0x3f317217, v144
	v_cmp_lt_f32_e64 s[42:43], |v144|, s53
	s_nop 1
	v_cndmask_b32_e64 v144, v144, v194, s[42:43]
	v_cndmask_b32_e64 v194, 0, v216, s[40:41]
	v_sub_f32_e32 v144, v144, v194
	v_cndmask_b32_e64 v144, v148, v144, s[20:21]
	v_mul_f32_e32 v148, 0x3fb8aa3b, v168
	v_exp_f32_e32 v148, v148
	s_nop 0
	v_fma_f32 v148, v182, v148, v128
	v_cmp_gt_f32_e64 s[40:41], s97, v148
	s_nop 1
	v_cndmask_b32_e64 v194, 0, 32, s[40:41]
	v_ldexp_f32 v148, v148, v194
	v_log_f32_e32 v148, v148
	s_nop 0
	v_mul_f32_e32 v194, 0x3f317217, v148
	v_fma_f32 v194, v148, s52, -v194
	v_fmac_f32_e32 v194, 0x3377d1cf, v148
	v_fmac_f32_e32 v194, 0x3f317217, v148
	v_cmp_lt_f32_e64 s[42:43], |v148|, s53
	s_nop 1
	v_cndmask_b32_e64 v148, v148, v194, s[42:43]
	v_cndmask_b32_e64 v194, 0, v216, s[40:41]
	v_sub_f32_e32 v148, v148, v194
	v_cndmask_b32_e64 v148, v168, v148, s[18:19]
	v_min_f32_e32 v168, 0, v149
	v_mul_f32_e64 v149, |v149|, s57
	v_exp_f32_e32 v149, v149
	s_nop 0
	v_add_f32_e32 v149, 1.0, v149
	v_log_f32_e32 v149, v149
	s_nop 0
	v_mul_f32_e32 v194, 0x3f317217, v149
	v_fma_f32 v194, v149, s52, -v194
	v_fmac_f32_e32 v194, 0x3377d1cf, v149
	v_fmac_f32_e32 v194, 0x3f317217, v149
	v_mov_b32_e32 v149, v194
	v_sub_f32_e32 v149, v168, v149
	v_min_f32_e32 v168, 0, v145
	v_mul_f32_e64 v145, |v145|, s57
	v_exp_f32_e32 v145, v145
	s_nop 0
	v_add_f32_e32 v145, 1.0, v145
	v_log_f32_e32 v145, v145
	s_nop 0
	v_mul_f32_e32 v194, 0x3f317217, v145
	v_fma_f32 v194, v145, s52, -v194
	v_fmac_f32_e32 v194, 0x3377d1cf, v145
	v_fmac_f32_e32 v194, 0x3f317217, v145
	v_mov_b32_e32 v145, v194
	v_sub_f32_e32 v168, v168, v145
	v_mul_f32_e32 v145, 0x3fb8aa3b, v149
	v_exp_f32_e32 v145, v145
	s_nop 0
	v_fma_f32 v145, v181, v145, v133
	v_cmp_gt_f32_e64 s[40:41], s97, v145
	s_nop 1
	v_cndmask_b32_e64 v194, 0, 32, s[40:41]
	v_ldexp_f32 v145, v145, v194
	v_log_f32_e32 v145, v145
	s_nop 0
	v_mul_f32_e32 v194, 0x3f317217, v145
	v_fma_f32 v194, v145, s52, -v194
	v_fmac_f32_e32 v194, 0x3377d1cf, v145
	v_fmac_f32_e32 v194, 0x3f317217, v145
	v_cmp_lt_f32_e64 s[42:43], |v145|, s53
	s_nop 1
	v_cndmask_b32_e64 v145, v145, v194, s[42:43]
	v_cndmask_b32_e64 v194, 0, v216, s[40:41]
	v_sub_f32_e32 v145, v145, v194
	v_cndmask_b32_e64 v145, v149, v145, s[16:17]
	v_mul_f32_e32 v149, 0x3fb8aa3b, v168
	v_exp_f32_e32 v149, v149
	s_nop 0
	v_fma_f32 v149, v180, v149, v129
	v_cmp_gt_f32_e64 s[40:41], s97, v149
	s_nop 1
	v_cndmask_b32_e64 v194, 0, 32, s[40:41]
	v_ldexp_f32 v149, v149, v194
	v_log_f32_e32 v149, v149
	s_nop 0
	v_mul_f32_e32 v194, 0x3f317217, v149
	v_fma_f32 v194, v149, s52, -v194
	v_fmac_f32_e32 v194, 0x3377d1cf, v149
	v_fmac_f32_e32 v194, 0x3f317217, v149
	v_cmp_lt_f32_e64 s[42:43], |v149|, s53
	s_nop 1
	v_cndmask_b32_e64 v149, v149, v194, s[42:43]
	v_cndmask_b32_e64 v194, 0, v216, s[40:41]
	v_sub_f32_e32 v149, v149, v194
	v_cndmask_b32_e64 v149, v168, v149, s[14:15]
	v_min_f32_e32 v168, 0, v150
	v_mul_f32_e64 v150, |v150|, s57
	v_exp_f32_e32 v150, v150
	s_nop 0
	v_add_f32_e32 v150, 1.0, v150
	v_log_f32_e32 v150, v150
	s_nop 0
	v_mul_f32_e32 v194, 0x3f317217, v150
	v_fma_f32 v194, v150, s52, -v194
	v_fmac_f32_e32 v194, 0x3377d1cf, v150
	v_fmac_f32_e32 v194, 0x3f317217, v150
	v_mov_b32_e32 v150, v194
	v_sub_f32_e32 v150, v168, v150
	v_min_f32_e32 v168, 0, v146
	v_mul_f32_e64 v146, |v146|, s57
	v_exp_f32_e32 v146, v146
	s_nop 0
	v_add_f32_e32 v146, 1.0, v146
	v_log_f32_e32 v146, v146
	s_nop 0
	v_mul_f32_e32 v194, 0x3f317217, v146
	v_fma_f32 v194, v146, s52, -v194
	v_fmac_f32_e32 v194, 0x3377d1cf, v146
	v_fmac_f32_e32 v194, 0x3f317217, v146
	v_mov_b32_e32 v146, v194
	v_sub_f32_e32 v168, v168, v146
	v_mul_f32_e32 v146, 0x3fb8aa3b, v150
	v_exp_f32_e32 v146, v146
	s_nop 0
	v_fma_f32 v146, v179, v146, v134
	v_cmp_gt_f32_e64 s[40:41], s97, v146
	s_nop 1
	v_cndmask_b32_e64 v194, 0, 32, s[40:41]
	v_ldexp_f32 v146, v146, v194
	v_log_f32_e32 v146, v146
	s_nop 0
	v_mul_f32_e32 v194, 0x3f317217, v146
	v_fma_f32 v194, v146, s52, -v194
	v_fmac_f32_e32 v194, 0x3377d1cf, v146
	v_fmac_f32_e32 v194, 0x3f317217, v146
	v_cmp_lt_f32_e64 s[42:43], |v146|, s53
	s_nop 1
	v_cndmask_b32_e64 v146, v146, v194, s[42:43]
	v_cndmask_b32_e64 v194, 0, v216, s[40:41]
	v_sub_f32_e32 v146, v146, v194
	v_cndmask_b32_e64 v146, v150, v146, s[12:13]
	v_mul_f32_e32 v150, 0x3fb8aa3b, v168
; __device__ __forceinline__ float silu_f(float x) { return x * __builtin_amdgcn_rcpf(1.f + __expf(-x)); }
; __device__ __forceinline__ v4u pack8(const f32x4 a, const f32x4 b) { v4u w; w.x = cvt_pk_bf16(a[0], a[1]); w.y = cvt_pk_bf16(a[2], a[3]); w.z = cvt_pk_bf16(b[0], b[1]); w.w = cvt_pk_bf16(b[2], b[3]); return w; }
;     __device__ __forceinline__ void operator()(const f32x4 (&acc)[2][2][4][2], const pg8::Unit& u, int wr, int wc, int fr, int fq) const {
;     ...
;         if (grp == 0) { WIN_LOOP( _Pragma("unroll") for (int i = 0; i < 4; ++i) { a[i] = silu_f(a[i]); b[i] = silu_f(b[i]); } *(v4u*)(QO + (size_t)row * DM + c) = pack8(a, b); ) }
;         else if (grp == 3) { WIN_LOOP( _Pragma("unroll") for (int i = 0; i < 4; ++i) { a[i] = silu_f(a[i]); b[i] = silu_f(b[i]); } *(v4u*)(GH + (size_t)row * 512 + c) = pack8(a, b); ) }
;         else if (grp == 1) {
;             f32x4 l0[2], l1[2];
; #pragma unroll
;             for (int bj = 0; bj < 2; ++bj) { l0[bj] = *(const f32x4*)(lb + cb + bj * 128); l1[bj] = *(const f32x4*)(lb + cb + bj * 128 + 4); }
;             WIN_LOOP( _Pragma("unroll") for (int i = 0; i < 4; ++i) { const float s0 = fminf(a[i], 0.f) - __logf(1.f + __expf(-fabsf(a[i]))), s1 = fminf(b[i], 0.f) - __logf(1.f + __expf(-fabsf(b[i]))); const float la = l0[bj][i], lbv = l1[bj][i];
;                     a[i] = la > 0.f ? __logf(la + (1.f - la) * __expf(s0)) : s0; b[i] = lbv > 0.f ? __logf(lbv + (1.f - lbv) * __expf(s1)) : s1; }
;                 *(f32x4*)(LF + (size_t)row * 512 + c) = a; *(f32x4*)(LF + (size_t)row * 512 + c + 4) = b; __builtin_amdgcn_sched_barrier(0); ) }
	v_exp_f32_e32 v150, v150
	s_nop 0
	v_fma_f32 v150, v178, v150, v130
	v_cmp_gt_f32_e64 s[40:41], s97, v150
	s_nop 1
	v_cndmask_b32_e64 v194, 0, 32, s[40:41]
	v_ldexp_f32 v150, v150, v194
	v_log_f32_e32 v150, v150
	s_nop 0
	v_mul_f32_e32 v194, 0x3f317217, v150
	v_fma_f32 v194, v150, s52, -v194
	v_fmac_f32_e32 v194, 0x3377d1cf, v150
	v_fmac_f32_e32 v194, 0x3f317217, v150
	v_cmp_lt_f32_e64 s[42:43], |v150|, s53
	s_nop 1
	v_cndmask_b32_e64 v150, v150, v194, s[42:43]
	v_cndmask_b32_e64 v194, 0, v216, s[40:41]
	v_sub_f32_e32 v150, v150, v194
	v_cndmask_b32_e64 v150, v168, v150, s[10:11]
	v_min_f32_e32 v168, 0, v151
	v_mul_f32_e64 v151, |v151|, s57
	v_exp_f32_e32 v151, v151
	s_nop 0
	v_add_f32_e32 v151, 1.0, v151
	v_log_f32_e32 v151, v151
	s_nop 0
	v_mul_f32_e32 v194, 0x3f317217, v151
	v_fma_f32 v194, v151, s52, -v194
	v_fmac_f32_e32 v194, 0x3377d1cf, v151
	v_fmac_f32_e32 v194, 0x3f317217, v151
	v_mov_b32_e32 v151, v194
	v_sub_f32_e32 v151, v168, v151
	v_min_f32_e32 v168, 0, v147
	v_mul_f32_e64 v147, |v147|, s57
	v_exp_f32_e32 v147, v147
	s_nop 0
	v_add_f32_e32 v147, 1.0, v147
	v_log_f32_e32 v147, v147
	s_nop 0
	v_mul_f32_e32 v194, 0x3f317217, v147
	v_fma_f32 v194, v147, s52, -v194
	v_fmac_f32_e32 v194, 0x3377d1cf, v147
	v_fmac_f32_e32 v194, 0x3f317217, v147
	v_mov_b32_e32 v147, v194
	v_sub_f32_e32 v168, v168, v147
	v_mul_f32_e32 v147, 0x3fb8aa3b, v151
	v_exp_f32_e32 v147, v147
	s_nop 0
	v_fma_f32 v147, v177, v147, v135
	v_cmp_gt_f32_e64 s[40:41], s97, v147
	s_nop 1
	v_cndmask_b32_e64 v194, 0, 32, s[40:41]
	v_ldexp_f32 v147, v147, v194
	v_log_f32_e32 v147, v147
	s_nop 0
	v_mul_f32_e32 v194, 0x3f317217, v147
	v_fma_f32 v194, v147, s52, -v194
	v_fmac_f32_e32 v194, 0x3377d1cf, v147
	v_fmac_f32_e32 v194, 0x3f317217, v147
	v_cmp_lt_f32_e64 s[42:43], |v147|, s53
	s_nop 1
	v_cndmask_b32_e64 v147, v147, v194, s[42:43]
	v_cndmask_b32_e64 v194, 0, v216, s[40:41]
	v_sub_f32_e32 v147, v147, v194
	v_cndmask_b32_e64 v147, v151, v147, s[8:9]
	v_mul_f32_e32 v151, 0x3fb8aa3b, v168
	v_exp_f32_e32 v151, v151
	s_nop 0
	v_fma_f32 v151, v167, v151, v131
	v_cmp_gt_f32_e64 s[40:41], s97, v151
	s_nop 1
	v_cndmask_b32_e64 v194, 0, 32, s[40:41]
	v_ldexp_f32 v151, v151, v194
	v_log_f32_e32 v151, v151
	s_nop 0
	v_mul_f32_e32 v194, 0x3f317217, v151
	v_fma_f32 v194, v151, s52, -v194
	v_fmac_f32_e32 v194, 0x3377d1cf, v151
	v_fmac_f32_e32 v194, 0x3f317217, v151
	v_cmp_lt_f32_e64 s[42:43], |v151|, s53
	s_nop 1
	v_cndmask_b32_e64 v151, v151, v194, s[42:43]
	v_cndmask_b32_e64 v194, 0, v216, s[40:41]
	v_sub_f32_e32 v151, v151, v194
	v_cndmask_b32_e32 v151, v168, v151, vcc
	global_store_dwordx4 v[170:171], v[144:147], off offset:512
	global_store_dwordx4 v[170:171], v[148:151], off offset:528
	s_nop 1
	v_or_b32_e32 v148, 32, v166
	v_ashrrev_i32_e32 v149, 31, v148
	v_lshlrev_b64 v[144:145], 6, v[148:149]
	v_lshl_add_u64 v[144:145], v[160:161], 0, v[144:145]
	s_nop 0
	s_waitcnt lgkmcnt(0)
	s_nop 3
	s_nop 0
	s_nop 1
	s_waitcnt lgkmcnt(0)
	s_nop 1
	s_waitcnt lgkmcnt(0)
	s_nop 1
	v_mov_b32_e32 v168, v252
	v_lshlrev_b64 v[144:145], 11, v[148:149]
	v_lshl_add_u64 v[170:171], s[50:51], 0, v[144:145]
	v_lshl_add_u64 v[170:171], v[170:171], 0, v[192:193]
	v_pk_mul_f32 v[148:149], v[44:45], v[168:169] op_sel_hi:[1,0]
	v_pk_mul_f32 v[144:145], v[40:41], v[168:169] op_sel_hi:[1,0]
	v_min_f32_e32 v194, 0, v148
	v_mul_f32_e64 v148, |v148|, s57
	v_exp_f32_e32 v148, v148
	v_pk_mul_f32 v[150:151], v[46:47], v[168:169] op_sel_hi:[1,0]
	v_pk_mul_f32 v[146:147], v[42:43], v[168:169] op_sel_hi:[1,0]
	v_add_f32_e32 v148, 1.0, v148
	v_log_f32_e32 v148, v148
	s_nop 0
	v_mul_f32_e32 v195, 0x3f317217, v148
	v_fma_f32 v195, v148, s52, -v195
	v_fmac_f32_e32 v195, 0x3377d1cf, v148
	v_fmac_f32_e32 v195, 0x3f317217, v148
	v_mov_b32_e32 v148, v195
	v_sub_f32_e32 v148, v194, v148
	v_min_f32_e32 v194, 0, v144
	v_mul_f32_e64 v144, |v144|, s57
	v_exp_f32_e32 v144, v144
	s_nop 0
	v_add_f32_e32 v144, 1.0, v144
	v_log_f32_e32 v144, v144
	s_nop 0
	v_mul_f32_e32 v195, 0x3f317217, v144
	v_fma_f32 v195, v144, s52, -v195
	v_fmac_f32_e32 v195, 0x3377d1cf, v144
	v_fmac_f32_e32 v195, 0x3f317217, v144
	v_mov_b32_e32 v144, v195
	v_sub_f32_e32 v194, v194, v144
	v_mul_f32_e32 v144, 0x3fb8aa3b, v148
	v_exp_f32_e32 v144, v144
	s_nop 0
	v_fma_f32 v144, v190, v144, v140
	v_cmp_gt_f32_e64 s[40:41], s97, v144
	s_nop 1
	v_cndmask_b32_e64 v195, 0, 32, s[40:41]
	v_ldexp_f32 v144, v144, v195
	v_log_f32_e32 v144, v144
	s_nop 0
	v_mul_f32_e32 v195, 0x3f317217, v144
	v_fma_f32 v195, v144, s52, -v195
	v_fmac_f32_e32 v195, 0x3377d1cf, v144
	v_fmac_f32_e32 v195, 0x3f317217, v144
	v_cmp_lt_f32_e64 s[42:43], |v144|, s53
	s_nop 1
	v_cndmask_b32_e64 v144, v144, v195, s[42:43]
	v_cndmask_b32_e64 v195, 0, v216, s[40:41]
	v_sub_f32_e32 v144, v144, v195
	v_cndmask_b32_e64 v144, v148, v144, s[38:39]
	v_mul_f32_e32 v148, 0x3fb8aa3b, v194
	v_exp_f32_e32 v148, v148
	s_nop 0
	v_fma_f32 v148, v191, v148, v136
	v_cmp_gt_f32_e64 s[40:41], s97, v148
	s_nop 1
	v_cndmask_b32_e64 v195, 0, 32, s[40:41]
	v_ldexp_f32 v148, v148, v195
	v_log_f32_e32 v148, v148
	s_nop 0
	v_mul_f32_e32 v195, 0x3f317217, v148
	v_fma_f32 v195, v148, s52, -v195
	v_fmac_f32_e32 v195, 0x3377d1cf, v148
	v_fmac_f32_e32 v195, 0x3f317217, v148
	v_cmp_lt_f32_e64 s[42:43], |v148|, s53
	s_nop 1
	v_cndmask_b32_e64 v148, v148, v195, s[42:43]
	v_cndmask_b32_e64 v195, 0, v216, s[40:41]
	v_sub_f32_e32 v148, v148, v195
	v_cndmask_b32_e64 v148, v194, v148, s[36:37]
	v_min_f32_e32 v194, 0, v149
	v_mul_f32_e64 v149, |v149|, s57
	v_exp_f32_e32 v149, v149
	s_nop 0
	v_add_f32_e32 v149, 1.0, v149
	v_log_f32_e32 v149, v149
	s_nop 0
	v_mul_f32_e32 v195, 0x3f317217, v149
	v_fma_f32 v195, v149, s52, -v195
; __device__ __forceinline__ float silu_f(float x) { return x * __builtin_amdgcn_rcpf(1.f + __expf(-x)); }
; __device__ __forceinline__ v4u pack8(const f32x4 a, const f32x4 b) { v4u w; w.x = cvt_pk_bf16(a[0], a[1]); w.y = cvt_pk_bf16(a[2], a[3]); w.z = cvt_pk_bf16(b[0], b[1]); w.w = cvt_pk_bf16(b[2], b[3]); return w; }
;     __device__ __forceinline__ void operator()(const f32x4 (&acc)[2][2][4][2], const pg8::Unit& u, int wr, int wc, int fr, int fq) const {
;     ...
;         if (grp == 0) { WIN_LOOP( _Pragma("unroll") for (int i = 0; i < 4; ++i) { a[i] = silu_f(a[i]); b[i] = silu_f(b[i]); } *(v4u*)(QO + (size_t)row * DM + c) = pack8(a, b); ) }
;         else if (grp == 3) { WIN_LOOP( _Pragma("unroll") for (int i = 0; i < 4; ++i) { a[i] = silu_f(a[i]); b[i] = silu_f(b[i]); } *(v4u*)(GH + (size_t)row * 512 + c) = pack8(a, b); ) }
;         else if (grp == 1) {
;             f32x4 l0[2], l1[2];
; #pragma unroll
;             for (int bj = 0; bj < 2; ++bj) { l0[bj] = *(const f32x4*)(lb + cb + bj * 128); l1[bj] = *(const f32x4*)(lb + cb + bj * 128 + 4); }
;             WIN_LOOP( _Pragma("unroll") for (int i = 0; i < 4; ++i) { const float s0 = fminf(a[i], 0.f) - __logf(1.f + __expf(-fabsf(a[i]))), s1 = fminf(b[i], 0.f) - __logf(1.f + __expf(-fabsf(b[i]))); const float la = l0[bj][i], lbv = l1[bj][i];
;                     a[i] = la > 0.f ? __logf(la + (1.f - la) * __expf(s0)) : s0; b[i] = lbv > 0.f ? __logf(lbv + (1.f - lbv) * __expf(s1)) : s1; }
;                 *(f32x4*)(LF + (size_t)row * 512 + c) = a; *(f32x4*)(LF + (size_t)row * 512 + c + 4) = b; __builtin_amdgcn_sched_barrier(0); ) }
	v_fmac_f32_e32 v195, 0x3377d1cf, v149
	v_fmac_f32_e32 v195, 0x3f317217, v149
	v_mov_b32_e32 v149, v195
	v_sub_f32_e32 v149, v194, v149
	v_min_f32_e32 v194, 0, v145
	v_mul_f32_e64 v145, |v145|, s57
	v_exp_f32_e32 v145, v145
	s_nop 0
	v_add_f32_e32 v145, 1.0, v145
	v_log_f32_e32 v145, v145
	s_nop 0
	v_mul_f32_e32 v195, 0x3f317217, v145
	v_fma_f32 v195, v145, s52, -v195
	v_fmac_f32_e32 v195, 0x3377d1cf, v145
	v_fmac_f32_e32 v195, 0x3f317217, v145
	v_mov_b32_e32 v145, v195
	v_sub_f32_e32 v194, v194, v145
	v_mul_f32_e32 v145, 0x3fb8aa3b, v149
	v_exp_f32_e32 v145, v145
	s_nop 0
	v_fma_f32 v145, v188, v145, v141
	v_cmp_gt_f32_e64 s[40:41], s97, v145
	s_nop 1
	v_cndmask_b32_e64 v195, 0, 32, s[40:41]
	v_ldexp_f32 v145, v145, v195
	v_log_f32_e32 v145, v145
	s_nop 0
	v_mul_f32_e32 v195, 0x3f317217, v145
	v_fma_f32 v195, v145, s52, -v195
	v_fmac_f32_e32 v195, 0x3377d1cf, v145
	v_fmac_f32_e32 v195, 0x3f317217, v145
	v_cmp_lt_f32_e64 s[42:43], |v145|, s53
	s_nop 1
	v_cndmask_b32_e64 v145, v145, v195, s[42:43]
	v_cndmask_b32_e64 v195, 0, v216, s[40:41]
	v_sub_f32_e32 v145, v145, v195
	v_cndmask_b32_e64 v145, v149, v145, s[34:35]
	v_mul_f32_e32 v149, 0x3fb8aa3b, v194
	v_exp_f32_e32 v149, v149
	s_nop 0
	v_fma_f32 v149, v189, v149, v137
	v_cmp_gt_f32_e64 s[40:41], s97, v149
	s_nop 1
	v_cndmask_b32_e64 v195, 0, 32, s[40:41]
	v_ldexp_f32 v149, v149, v195
	v_log_f32_e32 v149, v149
	s_nop 0
	v_mul_f32_e32 v195, 0x3f317217, v149
	v_fma_f32 v195, v149, s52, -v195
	v_fmac_f32_e32 v195, 0x3377d1cf, v149
	v_fmac_f32_e32 v195, 0x3f317217, v149
	v_cmp_lt_f32_e64 s[42:43], |v149|, s53
	s_nop 1
	v_cndmask_b32_e64 v149, v149, v195, s[42:43]
	v_cndmask_b32_e64 v195, 0, v216, s[40:41]
	v_sub_f32_e32 v149, v149, v195
	v_cndmask_b32_e64 v149, v194, v149, s[30:31]
	v_min_f32_e32 v194, 0, v150
	v_mul_f32_e64 v150, |v150|, s57
	v_exp_f32_e32 v150, v150
	s_nop 0
	v_add_f32_e32 v150, 1.0, v150
	v_log_f32_e32 v150, v150
	s_nop 0
	v_mul_f32_e32 v195, 0x3f317217, v150
	v_fma_f32 v195, v150, s52, -v195
	v_fmac_f32_e32 v195, 0x3377d1cf, v150
	v_fmac_f32_e32 v195, 0x3f317217, v150
	v_mov_b32_e32 v150, v195
	v_sub_f32_e32 v150, v194, v150
	v_min_f32_e32 v194, 0, v146
	v_mul_f32_e64 v146, |v146|, s57
	v_exp_f32_e32 v146, v146
	s_nop 0
	v_add_f32_e32 v146, 1.0, v146
	v_log_f32_e32 v146, v146
	s_nop 0
	v_mul_f32_e32 v195, 0x3f317217, v146
	v_fma_f32 v195, v146, s52, -v195
	v_fmac_f32_e32 v195, 0x3377d1cf, v146
	v_fmac_f32_e32 v195, 0x3f317217, v146
	v_mov_b32_e32 v146, v195
	v_sub_f32_e32 v194, v194, v146
	v_mul_f32_e32 v146, 0x3fb8aa3b, v150
	v_exp_f32_e32 v146, v146
	s_nop 0
	v_fma_f32 v146, v187, v146, v142
	v_cmp_gt_f32_e64 s[40:41], s97, v146
	s_nop 1
	v_cndmask_b32_e64 v195, 0, 32, s[40:41]
	v_ldexp_f32 v146, v146, v195
	v_log_f32_e32 v146, v146
	s_nop 0
	v_mul_f32_e32 v195, 0x3f317217, v146
	v_fma_f32 v195, v146, s52, -v195
	v_fmac_f32_e32 v195, 0x3377d1cf, v146
	v_fmac_f32_e32 v195, 0x3f317217, v146
	v_cmp_lt_f32_e64 s[42:43], |v146|, s53
	s_nop 1
	v_cndmask_b32_e64 v146, v146, v195, s[42:43]
	v_cndmask_b32_e64 v195, 0, v216, s[40:41]
	v_sub_f32_e32 v146, v146, v195
	v_cndmask_b32_e64 v146, v150, v146, s[28:29]
	v_mul_f32_e32 v150, 0x3fb8aa3b, v194
	v_exp_f32_e32 v150, v150
	s_nop 0
	v_fma_f32 v150, v186, v150, v138
	v_cmp_gt_f32_e64 s[40:41], s97, v150
	s_nop 1
	v_cndmask_b32_e64 v195, 0, 32, s[40:41]
	v_ldexp_f32 v150, v150, v195
	v_log_f32_e32 v150, v150
	s_nop 0
	v_mul_f32_e32 v195, 0x3f317217, v150
	v_fma_f32 v195, v150, s52, -v195
	v_fmac_f32_e32 v195, 0x3377d1cf, v150
	v_fmac_f32_e32 v195, 0x3f317217, v150
	v_cmp_lt_f32_e64 s[42:43], |v150|, s53
	s_nop 1
	v_cndmask_b32_e64 v150, v150, v195, s[42:43]
	v_cndmask_b32_e64 v195, 0, v216, s[40:41]
	v_sub_f32_e32 v150, v150, v195
	v_cndmask_b32_e64 v150, v194, v150, s[26:27]
	v_min_f32_e32 v194, 0, v151
	v_mul_f32_e64 v151, |v151|, s57
	v_exp_f32_e32 v151, v151
	s_nop 0
	v_add_f32_e32 v151, 1.0, v151
	v_log_f32_e32 v151, v151
	s_nop 0
	v_mul_f32_e32 v195, 0x3f317217, v151
	v_fma_f32 v195, v151, s52, -v195
	v_fmac_f32_e32 v195, 0x3377d1cf, v151
	v_fmac_f32_e32 v195, 0x3f317217, v151
	v_mov_b32_e32 v151, v195
	v_sub_f32_e32 v151, v194, v151
	v_min_f32_e32 v194, 0, v147
	v_mul_f32_e64 v147, |v147|, s57
	v_exp_f32_e32 v147, v147
	s_nop 0
	v_add_f32_e32 v147, 1.0, v147
	v_log_f32_e32 v147, v147
	s_nop 0
	v_mul_f32_e32 v195, 0x3f317217, v147
	v_fma_f32 v195, v147, s52, -v195
	v_fmac_f32_e32 v195, 0x3377d1cf, v147
	v_fmac_f32_e32 v195, 0x3f317217, v147
	v_mov_b32_e32 v147, v195
	v_sub_f32_e32 v194, v194, v147
	v_mul_f32_e32 v147, 0x3fb8aa3b, v151
	v_exp_f32_e32 v147, v147
	s_nop 0
	v_fma_f32 v147, v185, v147, v143
	v_cmp_gt_f32_e64 s[40:41], s97, v147
	s_nop 1
	v_cndmask_b32_e64 v195, 0, 32, s[40:41]
	v_ldexp_f32 v147, v147, v195
	v_log_f32_e32 v147, v147
	s_nop 0
	v_mul_f32_e32 v195, 0x3f317217, v147
	v_fma_f32 v195, v147, s52, -v195
	v_fmac_f32_e32 v195, 0x3377d1cf, v147
	v_fmac_f32_e32 v195, 0x3f317217, v147
	v_cmp_lt_f32_e64 s[42:43], |v147|, s53
	s_nop 1
	v_cndmask_b32_e64 v147, v147, v195, s[42:43]
	v_cndmask_b32_e64 v195, 0, v216, s[40:41]
	v_sub_f32_e32 v147, v147, v195
	v_cndmask_b32_e64 v147, v151, v147, s[24:25]
	v_mul_f32_e32 v151, 0x3fb8aa3b, v194
	v_exp_f32_e32 v151, v151
	s_nop 0
	v_fma_f32 v151, v184, v151, v139
	v_cmp_gt_f32_e64 s[40:41], s97, v151
	s_nop 1
	v_cndmask_b32_e64 v195, 0, 32, s[40:41]
	v_ldexp_f32 v151, v151, v195
	v_log_f32_e32 v151, v151
	s_nop 0
	v_mul_f32_e32 v195, 0x3f317217, v151
	v_fma_f32 v195, v151, s52, -v195
	v_fmac_f32_e32 v195, 0x3377d1cf, v151
	v_fmac_f32_e32 v195, 0x3f317217, v151
	v_cmp_lt_f32_e64 s[42:43], |v151|, s53
	s_nop 1
	v_cndmask_b32_e64 v151, v151, v195, s[42:43]
; __device__ __forceinline__ float silu_f(float x) { return x * __builtin_amdgcn_rcpf(1.f + __expf(-x)); }
; __device__ __forceinline__ v4u pack8(const f32x4 a, const f32x4 b) { v4u w; w.x = cvt_pk_bf16(a[0], a[1]); w.y = cvt_pk_bf16(a[2], a[3]); w.z = cvt_pk_bf16(b[0], b[1]); w.w = cvt_pk_bf16(b[2], b[3]); return w; }
;     __device__ __forceinline__ void operator()(const f32x4 (&acc)[2][2][4][2], const pg8::Unit& u, int wr, int wc, int fr, int fq) const {
;     ...
;         if (grp == 0) { WIN_LOOP( _Pragma("unroll") for (int i = 0; i < 4; ++i) { a[i] = silu_f(a[i]); b[i] = silu_f(b[i]); } *(v4u*)(QO + (size_t)row * DM + c) = pack8(a, b); ) }
;         else if (grp == 3) { WIN_LOOP( _Pragma("unroll") for (int i = 0; i < 4; ++i) { a[i] = silu_f(a[i]); b[i] = silu_f(b[i]); } *(v4u*)(GH + (size_t)row * 512 + c) = pack8(a, b); ) }
;         else if (grp == 1) {
;             f32x4 l0[2], l1[2];
; #pragma unroll
;             for (int bj = 0; bj < 2; ++bj) { l0[bj] = *(const f32x4*)(lb + cb + bj * 128); l1[bj] = *(const f32x4*)(lb + cb + bj * 128 + 4); }
;             WIN_LOOP( _Pragma("unroll") for (int i = 0; i < 4; ++i) { const float s0 = fminf(a[i], 0.f) - __logf(1.f + __expf(-fabsf(a[i]))), s1 = fminf(b[i], 0.f) - __logf(1.f + __expf(-fabsf(b[i]))); const float la = l0[bj][i], lbv = l1[bj][i];
;                     a[i] = la > 0.f ? __logf(la + (1.f - la) * __expf(s0)) : s0; b[i] = lbv > 0.f ? __logf(lbv + (1.f - lbv) * __expf(s1)) : s1; }
;                 *(f32x4*)(LF + (size_t)row * 512 + c) = a; *(f32x4*)(LF + (size_t)row * 512 + c + 4) = b; __builtin_amdgcn_sched_barrier(0); ) }
	v_cndmask_b32_e64 v195, 0, v216, s[40:41]
	v_sub_f32_e32 v151, v151, v195
	v_cndmask_b32_e64 v151, v194, v151, s[22:23]
	global_store_dwordx4 v[170:171], v[144:147], off
	global_store_dwordx4 v[170:171], v[148:151], off offset:16
	s_nop 1
	v_pk_mul_f32 v[148:149], v[108:109], v[168:169] op_sel_hi:[1,0]
	v_pk_mul_f32 v[150:151], v[110:111], v[168:169] op_sel_hi:[1,0]
	v_pk_mul_f32 v[146:147], v[106:107], v[168:169] op_sel_hi:[1,0]
	v_pk_mul_f32 v[144:145], v[104:105], v[168:169] op_sel_hi:[1,0]
	v_min_f32_e32 v168, 0, v148
	v_mul_f32_e64 v148, |v148|, s57
	v_exp_f32_e32 v148, v148
	s_nop 0
	v_add_f32_e32 v148, 1.0, v148
	v_log_f32_e32 v148, v148
	s_nop 0
	v_mul_f32_e32 v194, 0x3f317217, v148
	v_fma_f32 v194, v148, s52, -v194
	v_fmac_f32_e32 v194, 0x3377d1cf, v148
	v_fmac_f32_e32 v194, 0x3f317217, v148
	v_mov_b32_e32 v148, v194
	v_sub_f32_e32 v148, v168, v148
	v_min_f32_e32 v168, 0, v144
	v_mul_f32_e64 v144, |v144|, s57
	v_exp_f32_e32 v144, v144
	s_nop 0
	v_add_f32_e32 v144, 1.0, v144
	v_log_f32_e32 v144, v144
	s_nop 0
	v_mul_f32_e32 v194, 0x3f317217, v144
	v_fma_f32 v194, v144, s52, -v194
	v_fmac_f32_e32 v194, 0x3377d1cf, v144
	v_fmac_f32_e32 v194, 0x3f317217, v144
	v_mov_b32_e32 v144, v194
	v_sub_f32_e32 v168, v168, v144
	v_mul_f32_e32 v144, 0x3fb8aa3b, v148
	v_exp_f32_e32 v144, v144
	s_nop 0
	v_fma_f32 v144, v183, v144, v132
	v_cmp_gt_f32_e64 s[40:41], s97, v144
	s_nop 1
	v_cndmask_b32_e64 v194, 0, 32, s[40:41]
	v_ldexp_f32 v144, v144, v194
	v_log_f32_e32 v144, v144
	s_nop 0
	v_mul_f32_e32 v194, 0x3f317217, v144
	v_fma_f32 v194, v144, s52, -v194
	v_fmac_f32_e32 v194, 0x3377d1cf, v144
	v_fmac_f32_e32 v194, 0x3f317217, v144
	v_cmp_lt_f32_e64 s[42:43], |v144|, s53
	s_nop 1
	v_cndmask_b32_e64 v144, v144, v194, s[42:43]
	v_cndmask_b32_e64 v194, 0, v216, s[40:41]
	v_sub_f32_e32 v144, v144, v194
	v_cndmask_b32_e64 v144, v148, v144, s[20:21]
	v_mul_f32_e32 v148, 0x3fb8aa3b, v168
	v_exp_f32_e32 v148, v148
	s_nop 0
	v_fma_f32 v148, v182, v148, v128
	v_cmp_gt_f32_e64 s[40:41], s97, v148
	s_nop 1
	v_cndmask_b32_e64 v194, 0, 32, s[40:41]
	v_ldexp_f32 v148, v148, v194
	v_log_f32_e32 v148, v148
	s_nop 0
	v_mul_f32_e32 v194, 0x3f317217, v148
	v_fma_f32 v194, v148, s52, -v194
	v_fmac_f32_e32 v194, 0x3377d1cf, v148
	v_fmac_f32_e32 v194, 0x3f317217, v148
	v_cmp_lt_f32_e64 s[42:43], |v148|, s53
	s_nop 1
	v_cndmask_b32_e64 v148, v148, v194, s[42:43]
	v_cndmask_b32_e64 v194, 0, v216, s[40:41]
	v_sub_f32_e32 v148, v148, v194
	v_cndmask_b32_e64 v148, v168, v148, s[18:19]
	v_min_f32_e32 v168, 0, v149
	v_mul_f32_e64 v149, |v149|, s57
	v_exp_f32_e32 v149, v149
	s_nop 0
	v_add_f32_e32 v149, 1.0, v149
	v_log_f32_e32 v149, v149
	s_nop 0
	v_mul_f32_e32 v194, 0x3f317217, v149
	v_fma_f32 v194, v149, s52, -v194
	v_fmac_f32_e32 v194, 0x3377d1cf, v149
	v_fmac_f32_e32 v194, 0x3f317217, v149
	v_mov_b32_e32 v149, v194
	v_sub_f32_e32 v149, v168, v149
	v_min_f32_e32 v168, 0, v145
	v_mul_f32_e64 v145, |v145|, s57
	v_exp_f32_e32 v145, v145
	s_nop 0
	v_add_f32_e32 v145, 1.0, v145
	v_log_f32_e32 v145, v145
	s_nop 0
	v_mul_f32_e32 v194, 0x3f317217, v145
	v_fma_f32 v194, v145, s52, -v194
	v_fmac_f32_e32 v194, 0x3377d1cf, v145
	v_fmac_f32_e32 v194, 0x3f317217, v145
	v_mov_b32_e32 v145, v194
	v_sub_f32_e32 v168, v168, v145
	v_mul_f32_e32 v145, 0x3fb8aa3b, v149
	v_exp_f32_e32 v145, v145
	s_nop 0
	v_fma_f32 v145, v181, v145, v133
	v_cmp_gt_f32_e64 s[40:41], s97, v145
	s_nop 1
	v_cndmask_b32_e64 v194, 0, 32, s[40:41]
	v_ldexp_f32 v145, v145, v194
	v_log_f32_e32 v145, v145
	s_nop 0
	v_mul_f32_e32 v194, 0x3f317217, v145
	v_fma_f32 v194, v145, s52, -v194
	v_fmac_f32_e32 v194, 0x3377d1cf, v145
	v_fmac_f32_e32 v194, 0x3f317217, v145
	v_cmp_lt_f32_e64 s[42:43], |v145|, s53
	s_nop 1
	v_cndmask_b32_e64 v145, v145, v194, s[42:43]
	v_cndmask_b32_e64 v194, 0, v216, s[40:41]
	v_sub_f32_e32 v145, v145, v194
	v_cndmask_b32_e64 v145, v149, v145, s[16:17]
	v_mul_f32_e32 v149, 0x3fb8aa3b, v168
	v_exp_f32_e32 v149, v149
	s_nop 0
	v_fma_f32 v149, v180, v149, v129
	v_cmp_gt_f32_e64 s[40:41], s97, v149
	s_nop 1
	v_cndmask_b32_e64 v194, 0, 32, s[40:41]
	v_ldexp_f32 v149, v149, v194
	v_log_f32_e32 v149, v149
	s_nop 0
	v_mul_f32_e32 v194, 0x3f317217, v149
	v_fma_f32 v194, v149, s52, -v194
	v_fmac_f32_e32 v194, 0x3377d1cf, v149
	v_fmac_f32_e32 v194, 0x3f317217, v149
	v_cmp_lt_f32_e64 s[42:43], |v149|, s53
	s_nop 1
	v_cndmask_b32_e64 v149, v149, v194, s[42:43]
	v_cndmask_b32_e64 v194, 0, v216, s[40:41]
	v_sub_f32_e32 v149, v149, v194
	v_cndmask_b32_e64 v149, v168, v149, s[14:15]
	v_min_f32_e32 v168, 0, v150
	v_mul_f32_e64 v150, |v150|, s57
	v_exp_f32_e32 v150, v150
	s_nop 0
	v_add_f32_e32 v150, 1.0, v150
	v_log_f32_e32 v150, v150
	s_nop 0
	v_mul_f32_e32 v194, 0x3f317217, v150
	v_fma_f32 v194, v150, s52, -v194
	v_fmac_f32_e32 v194, 0x3377d1cf, v150
	v_fmac_f32_e32 v194, 0x3f317217, v150
	v_mov_b32_e32 v150, v194
	v_sub_f32_e32 v150, v168, v150
	v_min_f32_e32 v168, 0, v146
	v_mul_f32_e64 v146, |v146|, s57
	v_exp_f32_e32 v146, v146
	s_nop 0
	v_add_f32_e32 v146, 1.0, v146
	v_log_f32_e32 v146, v146
	s_nop 0
	v_mul_f32_e32 v194, 0x3f317217, v146
	v_fma_f32 v194, v146, s52, -v194
	v_fmac_f32_e32 v194, 0x3377d1cf, v146
	v_fmac_f32_e32 v194, 0x3f317217, v146
	v_mov_b32_e32 v146, v194
	v_sub_f32_e32 v168, v168, v146
	v_mul_f32_e32 v146, 0x3fb8aa3b, v150
	v_exp_f32_e32 v146, v146
	s_nop 0
	v_fma_f32 v146, v179, v146, v134
	v_cmp_gt_f32_e64 s[40:41], s97, v146
	s_nop 1
	v_cndmask_b32_e64 v194, 0, 32, s[40:41]
	v_ldexp_f32 v146, v146, v194
	v_log_f32_e32 v146, v146
	s_nop 0
	v_mul_f32_e32 v194, 0x3f317217, v146
	v_fma_f32 v194, v146, s52, -v194
	v_fmac_f32_e32 v194, 0x3377d1cf, v146
	v_fmac_f32_e32 v194, 0x3f317217, v146
; __device__ __forceinline__ float silu_f(float x) { return x * __builtin_amdgcn_rcpf(1.f + __expf(-x)); }
; __device__ __forceinline__ v4u pack8(const f32x4 a, const f32x4 b) { v4u w; w.x = cvt_pk_bf16(a[0], a[1]); w.y = cvt_pk_bf16(a[2], a[3]); w.z = cvt_pk_bf16(b[0], b[1]); w.w = cvt_pk_bf16(b[2], b[3]); return w; }
;     __device__ __forceinline__ void operator()(const f32x4 (&acc)[2][2][4][2], const pg8::Unit& u, int wr, int wc, int fr, int fq) const {
;     ...
;         if (grp == 0) { WIN_LOOP( _Pragma("unroll") for (int i = 0; i < 4; ++i) { a[i] = silu_f(a[i]); b[i] = silu_f(b[i]); } *(v4u*)(QO + (size_t)row * DM + c) = pack8(a, b); ) }
;         else if (grp == 3) { WIN_LOOP( _Pragma("unroll") for (int i = 0; i < 4; ++i) { a[i] = silu_f(a[i]); b[i] = silu_f(b[i]); } *(v4u*)(GH + (size_t)row * 512 + c) = pack8(a, b); ) }
;         else if (grp == 1) {
;             f32x4 l0[2], l1[2];
; #pragma unroll
;             for (int bj = 0; bj < 2; ++bj) { l0[bj] = *(const f32x4*)(lb + cb + bj * 128); l1[bj] = *(const f32x4*)(lb + cb + bj * 128 + 4); }
;             WIN_LOOP( _Pragma("unroll") for (int i = 0; i < 4; ++i) { const float s0 = fminf(a[i], 0.f) - __logf(1.f + __expf(-fabsf(a[i]))), s1 = fminf(b[i], 0.f) - __logf(1.f + __expf(-fabsf(b[i]))); const float la = l0[bj][i], lbv = l1[bj][i];
;                     a[i] = la > 0.f ? __logf(la + (1.f - la) * __expf(s0)) : s0; b[i] = lbv > 0.f ? __logf(lbv + (1.f - lbv) * __expf(s1)) : s1; }
;                 *(f32x4*)(LF + (size_t)row * 512 + c) = a; *(f32x4*)(LF + (size_t)row * 512 + c + 4) = b; __builtin_amdgcn_sched_barrier(0); ) }
	v_cmp_lt_f32_e64 s[42:43], |v146|, s53
	s_nop 1
	v_cndmask_b32_e64 v146, v146, v194, s[42:43]
	v_cndmask_b32_e64 v194, 0, v216, s[40:41]
	v_sub_f32_e32 v146, v146, v194
	v_cndmask_b32_e64 v146, v150, v146, s[12:13]
	v_mul_f32_e32 v150, 0x3fb8aa3b, v168
	v_exp_f32_e32 v150, v150
	s_nop 0
	v_fma_f32 v150, v178, v150, v130
	v_cmp_gt_f32_e64 s[40:41], s97, v150
	s_nop 1
	v_cndmask_b32_e64 v194, 0, 32, s[40:41]
	v_ldexp_f32 v150, v150, v194
	v_log_f32_e32 v150, v150
	s_nop 0
	v_mul_f32_e32 v194, 0x3f317217, v150
	v_fma_f32 v194, v150, s52, -v194
	v_fmac_f32_e32 v194, 0x3377d1cf, v150
	v_fmac_f32_e32 v194, 0x3f317217, v150
	v_cmp_lt_f32_e64 s[42:43], |v150|, s53
	s_nop 1
	v_cndmask_b32_e64 v150, v150, v194, s[42:43]
	v_cndmask_b32_e64 v194, 0, v216, s[40:41]
	v_sub_f32_e32 v150, v150, v194
	v_cndmask_b32_e64 v150, v168, v150, s[10:11]
	v_min_f32_e32 v168, 0, v151
	v_mul_f32_e64 v151, |v151|, s57
	v_exp_f32_e32 v151, v151
	s_nop 0
	v_add_f32_e32 v151, 1.0, v151
	v_log_f32_e32 v151, v151
	s_nop 0
	v_mul_f32_e32 v194, 0x3f317217, v151
	v_fma_f32 v194, v151, s52, -v194
	v_fmac_f32_e32 v194, 0x3377d1cf, v151
	v_fmac_f32_e32 v194, 0x3f317217, v151
	v_mov_b32_e32 v151, v194
	v_sub_f32_e32 v151, v168, v151
	v_min_f32_e32 v168, 0, v147
	v_mul_f32_e64 v147, |v147|, s57
	v_exp_f32_e32 v147, v147
	s_nop 0
	v_add_f32_e32 v147, 1.0, v147
	v_log_f32_e32 v147, v147
	s_nop 0
	v_mul_f32_e32 v194, 0x3f317217, v147
	v_fma_f32 v194, v147, s52, -v194
	v_fmac_f32_e32 v194, 0x3377d1cf, v147
	v_fmac_f32_e32 v194, 0x3f317217, v147
	v_mov_b32_e32 v147, v194
	v_sub_f32_e32 v168, v168, v147
	v_mul_f32_e32 v147, 0x3fb8aa3b, v151
	v_exp_f32_e32 v147, v147
	s_nop 0
	v_fma_f32 v147, v177, v147, v135
	v_cmp_gt_f32_e64 s[40:41], s97, v147
	s_nop 1
	v_cndmask_b32_e64 v194, 0, 32, s[40:41]
	v_ldexp_f32 v147, v147, v194
	v_log_f32_e32 v147, v147
	s_nop 0
	v_mul_f32_e32 v194, 0x3f317217, v147
	v_fma_f32 v194, v147, s52, -v194
	v_fmac_f32_e32 v194, 0x3377d1cf, v147
	v_fmac_f32_e32 v194, 0x3f317217, v147
	v_cmp_lt_f32_e64 s[42:43], |v147|, s53
	s_nop 1
	v_cndmask_b32_e64 v147, v147, v194, s[42:43]
	v_cndmask_b32_e64 v194, 0, v216, s[40:41]
	v_sub_f32_e32 v147, v147, v194
	v_cndmask_b32_e64 v147, v151, v147, s[8:9]
	v_mul_f32_e32 v151, 0x3fb8aa3b, v168
	v_exp_f32_e32 v151, v151
	s_nop 0
	v_fma_f32 v151, v167, v151, v131
	v_cmp_gt_f32_e64 s[40:41], s97, v151
	s_nop 1
	v_cndmask_b32_e64 v194, 0, 32, s[40:41]
	v_ldexp_f32 v151, v151, v194
	v_log_f32_e32 v151, v151
	s_nop 0
	v_mul_f32_e32 v194, 0x3f317217, v151
	v_fma_f32 v194, v151, s52, -v194
	v_fmac_f32_e32 v194, 0x3377d1cf, v151
	v_fmac_f32_e32 v194, 0x3f317217, v151
	v_cmp_lt_f32_e64 s[42:43], |v151|, s53
	s_nop 1
	v_cndmask_b32_e64 v151, v151, v194, s[42:43]
	v_cndmask_b32_e64 v194, 0, v216, s[40:41]
	v_sub_f32_e32 v151, v151, v194
	v_cndmask_b32_e32 v151, v168, v151, vcc
	global_store_dwordx4 v[170:171], v[144:147], off offset:512
	global_store_dwordx4 v[170:171], v[148:151], off offset:528
	s_nop 1
	v_or_b32_e32 v148, 48, v166
	v_ashrrev_i32_e32 v149, 31, v148
	v_lshlrev_b64 v[144:145], 6, v[148:149]
	v_lshl_add_u64 v[144:145], v[160:161], 0, v[144:145]
	s_nop 0
	s_waitcnt lgkmcnt(0)
	s_nop 3
	s_nop 0
	s_nop 1
	s_waitcnt lgkmcnt(0)
	s_nop 1
	s_waitcnt lgkmcnt(0)
	s_nop 1
	v_mov_b32_e32 v168, v253
	v_lshlrev_b64 v[144:145], 11, v[148:149]
	v_lshl_add_u64 v[170:171], s[50:51], 0, v[144:145]
	v_lshl_add_u64 v[170:171], v[170:171], 0, v[192:193]
	v_pk_mul_f32 v[148:149], v[36:37], v[168:169] op_sel_hi:[1,0]
	v_pk_mul_f32 v[144:145], v[32:33], v[168:169] op_sel_hi:[1,0]
	v_min_f32_e32 v194, 0, v148
	v_mul_f32_e64 v148, |v148|, s57
	v_exp_f32_e32 v148, v148
	v_pk_mul_f32 v[150:151], v[38:39], v[168:169] op_sel_hi:[1,0]
	v_pk_mul_f32 v[146:147], v[34:35], v[168:169] op_sel_hi:[1,0]
	v_add_f32_e32 v148, 1.0, v148
	v_log_f32_e32 v148, v148
	s_nop 0
	v_mul_f32_e32 v195, 0x3f317217, v148
	v_fma_f32 v195, v148, s52, -v195
	v_fmac_f32_e32 v195, 0x3377d1cf, v148
	v_fmac_f32_e32 v195, 0x3f317217, v148
	v_mov_b32_e32 v148, v195
	v_sub_f32_e32 v148, v194, v148
	v_min_f32_e32 v194, 0, v144
	v_mul_f32_e64 v144, |v144|, s57
	v_exp_f32_e32 v144, v144
	s_nop 0
	v_add_f32_e32 v144, 1.0, v144
	v_log_f32_e32 v144, v144
	s_nop 0
	v_mul_f32_e32 v195, 0x3f317217, v144
	v_fma_f32 v195, v144, s52, -v195
	v_fmac_f32_e32 v195, 0x3377d1cf, v144
	v_fmac_f32_e32 v195, 0x3f317217, v144
	v_mov_b32_e32 v144, v195
	v_sub_f32_e32 v194, v194, v144
	v_mul_f32_e32 v144, 0x3fb8aa3b, v148
	v_exp_f32_e32 v144, v144
	s_nop 0
	v_fma_f32 v144, v190, v144, v140
	v_cmp_gt_f32_e64 s[40:41], s97, v144
	s_nop 1
	v_cndmask_b32_e64 v195, 0, 32, s[40:41]
	v_ldexp_f32 v144, v144, v195
	v_log_f32_e32 v144, v144
	s_nop 0
	v_mul_f32_e32 v195, 0x3f317217, v144
	v_fma_f32 v195, v144, s52, -v195
	v_fmac_f32_e32 v195, 0x3377d1cf, v144
	v_fmac_f32_e32 v195, 0x3f317217, v144
	v_cmp_lt_f32_e64 s[42:43], |v144|, s53
	s_nop 1
	v_cndmask_b32_e64 v144, v144, v195, s[42:43]
	v_cndmask_b32_e64 v195, 0, v216, s[40:41]
	v_sub_f32_e32 v144, v144, v195
	v_cndmask_b32_e64 v144, v148, v144, s[38:39]
	v_mul_f32_e32 v148, 0x3fb8aa3b, v194
	v_exp_f32_e32 v148, v148
	s_nop 0
	v_fma_f32 v148, v191, v148, v136
	v_cmp_gt_f32_e64 s[40:41], s97, v148
	s_nop 1
	v_cndmask_b32_e64 v195, 0, 32, s[40:41]
	v_ldexp_f32 v148, v148, v195
	v_log_f32_e32 v148, v148
	s_nop 0
	v_mul_f32_e32 v195, 0x3f317217, v148
	v_fma_f32 v195, v148, s52, -v195
	v_fmac_f32_e32 v195, 0x3377d1cf, v148
	v_fmac_f32_e32 v195, 0x3f317217, v148
	v_cmp_lt_f32_e64 s[42:43], |v148|, s53
	s_nop 1
	v_cndmask_b32_e64 v148, v148, v195, s[42:43]
	v_cndmask_b32_e64 v195, 0, v216, s[40:41]
	v_sub_f32_e32 v148, v148, v195
	v_cndmask_b32_e64 v148, v194, v148, s[36:37]
; __device__ __forceinline__ float silu_f(float x) { return x * __builtin_amdgcn_rcpf(1.f + __expf(-x)); }
; __device__ __forceinline__ v4u pack8(const f32x4 a, const f32x4 b) { v4u w; w.x = cvt_pk_bf16(a[0], a[1]); w.y = cvt_pk_bf16(a[2], a[3]); w.z = cvt_pk_bf16(b[0], b[1]); w.w = cvt_pk_bf16(b[2], b[3]); return w; }
;     __device__ __forceinline__ void operator()(const f32x4 (&acc)[2][2][4][2], const pg8::Unit& u, int wr, int wc, int fr, int fq) const {
;     ...
;         if (grp == 0) { WIN_LOOP( _Pragma("unroll") for (int i = 0; i < 4; ++i) { a[i] = silu_f(a[i]); b[i] = silu_f(b[i]); } *(v4u*)(QO + (size_t)row * DM + c) = pack8(a, b); ) }
;         else if (grp == 3) { WIN_LOOP( _Pragma("unroll") for (int i = 0; i < 4; ++i) { a[i] = silu_f(a[i]); b[i] = silu_f(b[i]); } *(v4u*)(GH + (size_t)row * 512 + c) = pack8(a, b); ) }
;         else if (grp == 1) {
;             f32x4 l0[2], l1[2];
; #pragma unroll
;             for (int bj = 0; bj < 2; ++bj) { l0[bj] = *(const f32x4*)(lb + cb + bj * 128); l1[bj] = *(const f32x4*)(lb + cb + bj * 128 + 4); }
;             WIN_LOOP( _Pragma("unroll") for (int i = 0; i < 4; ++i) { const float s0 = fminf(a[i], 0.f) - __logf(1.f + __expf(-fabsf(a[i]))), s1 = fminf(b[i], 0.f) - __logf(1.f + __expf(-fabsf(b[i]))); const float la = l0[bj][i], lbv = l1[bj][i];
;                     a[i] = la > 0.f ? __logf(la + (1.f - la) * __expf(s0)) : s0; b[i] = lbv > 0.f ? __logf(lbv + (1.f - lbv) * __expf(s1)) : s1; }
;                 *(f32x4*)(LF + (size_t)row * 512 + c) = a; *(f32x4*)(LF + (size_t)row * 512 + c + 4) = b; __builtin_amdgcn_sched_barrier(0); ) }
	v_min_f32_e32 v194, 0, v149
	v_mul_f32_e64 v149, |v149|, s57
	v_exp_f32_e32 v149, v149
	s_nop 0
	v_add_f32_e32 v149, 1.0, v149
	v_log_f32_e32 v149, v149
	s_nop 0
	v_mul_f32_e32 v195, 0x3f317217, v149
	v_fma_f32 v195, v149, s52, -v195
	v_fmac_f32_e32 v195, 0x3377d1cf, v149
	v_fmac_f32_e32 v195, 0x3f317217, v149
	v_mov_b32_e32 v149, v195
	v_sub_f32_e32 v149, v194, v149
	v_min_f32_e32 v194, 0, v145
	v_mul_f32_e64 v145, |v145|, s57
	v_exp_f32_e32 v145, v145
	s_nop 0
	v_add_f32_e32 v145, 1.0, v145
	v_log_f32_e32 v145, v145
	s_nop 0
	v_mul_f32_e32 v195, 0x3f317217, v145
	v_fma_f32 v195, v145, s52, -v195
	v_fmac_f32_e32 v195, 0x3377d1cf, v145
	v_fmac_f32_e32 v195, 0x3f317217, v145
	v_mov_b32_e32 v145, v195
	v_sub_f32_e32 v194, v194, v145
	v_mul_f32_e32 v145, 0x3fb8aa3b, v149
	v_exp_f32_e32 v145, v145
	s_nop 0
	v_fma_f32 v145, v188, v145, v141
	v_cmp_gt_f32_e64 s[40:41], s97, v145
	s_nop 1
	v_cndmask_b32_e64 v195, 0, 32, s[40:41]
	v_ldexp_f32 v145, v145, v195
	v_log_f32_e32 v145, v145
	s_nop 0
	v_mul_f32_e32 v195, 0x3f317217, v145
	v_fma_f32 v195, v145, s52, -v195
	v_fmac_f32_e32 v195, 0x3377d1cf, v145
	v_fmac_f32_e32 v195, 0x3f317217, v145
	v_cmp_lt_f32_e64 s[42:43], |v145|, s53
	s_nop 1
	v_cndmask_b32_e64 v145, v145, v195, s[42:43]
	v_cndmask_b32_e64 v195, 0, v216, s[40:41]
	v_sub_f32_e32 v145, v145, v195
	v_cndmask_b32_e64 v145, v149, v145, s[34:35]
	v_mul_f32_e32 v149, 0x3fb8aa3b, v194
	v_exp_f32_e32 v149, v149
	s_nop 0
	v_fma_f32 v149, v189, v149, v137
	v_cmp_gt_f32_e64 s[40:41], s97, v149
	s_nop 1
	v_cndmask_b32_e64 v195, 0, 32, s[40:41]
	v_ldexp_f32 v149, v149, v195
	v_log_f32_e32 v149, v149
	s_nop 0
	v_mul_f32_e32 v195, 0x3f317217, v149
	v_fma_f32 v195, v149, s52, -v195
	v_fmac_f32_e32 v195, 0x3377d1cf, v149
	v_fmac_f32_e32 v195, 0x3f317217, v149
	v_cmp_lt_f32_e64 s[42:43], |v149|, s53
	s_nop 1
	v_cndmask_b32_e64 v149, v149, v195, s[42:43]
	v_cndmask_b32_e64 v195, 0, v216, s[40:41]
	v_sub_f32_e32 v149, v149, v195
	v_cndmask_b32_e64 v149, v194, v149, s[30:31]
	v_min_f32_e32 v194, 0, v150
	v_mul_f32_e64 v150, |v150|, s57
	v_exp_f32_e32 v150, v150
	s_nop 0
	v_add_f32_e32 v150, 1.0, v150
	v_log_f32_e32 v150, v150
	s_nop 0
	v_mul_f32_e32 v195, 0x3f317217, v150
	v_fma_f32 v195, v150, s52, -v195
	v_fmac_f32_e32 v195, 0x3377d1cf, v150
	v_fmac_f32_e32 v195, 0x3f317217, v150
	v_mov_b32_e32 v150, v195
	v_sub_f32_e32 v150, v194, v150
	v_min_f32_e32 v194, 0, v146
	v_mul_f32_e64 v146, |v146|, s57
	v_exp_f32_e32 v146, v146
	s_nop 0
	v_add_f32_e32 v146, 1.0, v146
	v_log_f32_e32 v146, v146
	s_nop 0
	v_mul_f32_e32 v195, 0x3f317217, v146
	v_fma_f32 v195, v146, s52, -v195
	v_fmac_f32_e32 v195, 0x3377d1cf, v146
	v_fmac_f32_e32 v195, 0x3f317217, v146
	v_mov_b32_e32 v146, v195
	v_sub_f32_e32 v194, v194, v146
	v_mul_f32_e32 v146, 0x3fb8aa3b, v150
	v_exp_f32_e32 v146, v146
	s_nop 0
	v_fma_f32 v146, v187, v146, v142
	v_cmp_gt_f32_e64 s[40:41], s97, v146
	s_nop 1
	v_cndmask_b32_e64 v195, 0, 32, s[40:41]
	v_ldexp_f32 v146, v146, v195
	v_log_f32_e32 v146, v146
	s_nop 0
	v_mul_f32_e32 v195, 0x3f317217, v146
	v_fma_f32 v195, v146, s52, -v195
	v_fmac_f32_e32 v195, 0x3377d1cf, v146
	v_fmac_f32_e32 v195, 0x3f317217, v146
	v_cmp_lt_f32_e64 s[42:43], |v146|, s53
	s_nop 1
	v_cndmask_b32_e64 v146, v146, v195, s[42:43]
	v_cndmask_b32_e64 v195, 0, v216, s[40:41]
	v_sub_f32_e32 v146, v146, v195
	v_cndmask_b32_e64 v146, v150, v146, s[28:29]
	v_mul_f32_e32 v150, 0x3fb8aa3b, v194
	v_exp_f32_e32 v150, v150
	s_nop 0
	v_fma_f32 v150, v186, v150, v138
	v_cmp_gt_f32_e64 s[40:41], s97, v150
	s_nop 1
	v_cndmask_b32_e64 v195, 0, 32, s[40:41]
	v_ldexp_f32 v150, v150, v195
	v_log_f32_e32 v150, v150
	s_nop 0
	v_mul_f32_e32 v195, 0x3f317217, v150
	v_fma_f32 v195, v150, s52, -v195
	v_fmac_f32_e32 v195, 0x3377d1cf, v150
	v_fmac_f32_e32 v195, 0x3f317217, v150
	v_cmp_lt_f32_e64 s[42:43], |v150|, s53
	s_nop 1
	v_cndmask_b32_e64 v150, v150, v195, s[42:43]
	v_cndmask_b32_e64 v195, 0, v216, s[40:41]
	v_sub_f32_e32 v150, v150, v195
	v_cndmask_b32_e64 v150, v194, v150, s[26:27]
	v_min_f32_e32 v194, 0, v151
	v_mul_f32_e64 v151, |v151|, s57
	v_exp_f32_e32 v151, v151
	s_nop 0
	v_add_f32_e32 v151, 1.0, v151
	v_log_f32_e32 v151, v151
	s_nop 0
	v_mul_f32_e32 v195, 0x3f317217, v151
	v_fma_f32 v195, v151, s52, -v195
	v_fmac_f32_e32 v195, 0x3377d1cf, v151
	v_fmac_f32_e32 v195, 0x3f317217, v151
	v_mov_b32_e32 v151, v195
	v_sub_f32_e32 v151, v194, v151
	v_min_f32_e32 v194, 0, v147
	v_mul_f32_e64 v147, |v147|, s57
	v_exp_f32_e32 v147, v147
	s_nop 0
	v_add_f32_e32 v147, 1.0, v147
	v_log_f32_e32 v147, v147
	s_nop 0
	v_mul_f32_e32 v195, 0x3f317217, v147
	v_fma_f32 v195, v147, s52, -v195
	v_fmac_f32_e32 v195, 0x3377d1cf, v147
	v_fmac_f32_e32 v195, 0x3f317217, v147
	v_mov_b32_e32 v147, v195
	v_sub_f32_e32 v194, v194, v147
	v_mul_f32_e32 v147, 0x3fb8aa3b, v151
	v_exp_f32_e32 v147, v147
	s_nop 0
	v_fma_f32 v147, v185, v147, v143
	v_cmp_gt_f32_e64 s[40:41], s97, v147
	s_nop 1
	v_cndmask_b32_e64 v195, 0, 32, s[40:41]
	v_ldexp_f32 v147, v147, v195
	v_log_f32_e32 v147, v147
	s_nop 0
	v_mul_f32_e32 v195, 0x3f317217, v147
	v_fma_f32 v195, v147, s52, -v195
	v_fmac_f32_e32 v195, 0x3377d1cf, v147
	v_fmac_f32_e32 v195, 0x3f317217, v147
	v_cmp_lt_f32_e64 s[42:43], |v147|, s53
	s_nop 1
	v_cndmask_b32_e64 v147, v147, v195, s[42:43]
	v_cndmask_b32_e64 v195, 0, v216, s[40:41]
	v_sub_f32_e32 v147, v147, v195
	v_cndmask_b32_e64 v147, v151, v147, s[24:25]
	v_mul_f32_e32 v151, 0x3fb8aa3b, v194
	v_exp_f32_e32 v151, v151
	s_nop 0
	v_fma_f32 v151, v184, v151, v139
	v_cmp_gt_f32_e64 s[40:41], s97, v151
	s_nop 1
	v_cndmask_b32_e64 v195, 0, 32, s[40:41]
	v_ldexp_f32 v151, v151, v195
	v_log_f32_e32 v151, v151
	s_nop 0
	v_mul_f32_e32 v195, 0x3f317217, v151
; __device__ __forceinline__ float silu_f(float x) { return x * __builtin_amdgcn_rcpf(1.f + __expf(-x)); }
; __device__ __forceinline__ v4u pack8(const f32x4 a, const f32x4 b) { v4u w; w.x = cvt_pk_bf16(a[0], a[1]); w.y = cvt_pk_bf16(a[2], a[3]); w.z = cvt_pk_bf16(b[0], b[1]); w.w = cvt_pk_bf16(b[2], b[3]); return w; }
;     __device__ __forceinline__ void operator()(const f32x4 (&acc)[2][2][4][2], const pg8::Unit& u, int wr, int wc, int fr, int fq) const {
;     ...
;         if (grp == 0) { WIN_LOOP( _Pragma("unroll") for (int i = 0; i < 4; ++i) { a[i] = silu_f(a[i]); b[i] = silu_f(b[i]); } *(v4u*)(QO + (size_t)row * DM + c) = pack8(a, b); ) }
;         else if (grp == 3) { WIN_LOOP( _Pragma("unroll") for (int i = 0; i < 4; ++i) { a[i] = silu_f(a[i]); b[i] = silu_f(b[i]); } *(v4u*)(GH + (size_t)row * 512 + c) = pack8(a, b); ) }
;         else if (grp == 1) {
;             f32x4 l0[2], l1[2];
; #pragma unroll
;             for (int bj = 0; bj < 2; ++bj) { l0[bj] = *(const f32x4*)(lb + cb + bj * 128); l1[bj] = *(const f32x4*)(lb + cb + bj * 128 + 4); }
;             WIN_LOOP( _Pragma("unroll") for (int i = 0; i < 4; ++i) { const float s0 = fminf(a[i], 0.f) - __logf(1.f + __expf(-fabsf(a[i]))), s1 = fminf(b[i], 0.f) - __logf(1.f + __expf(-fabsf(b[i]))); const float la = l0[bj][i], lbv = l1[bj][i];
;                     a[i] = la > 0.f ? __logf(la + (1.f - la) * __expf(s0)) : s0; b[i] = lbv > 0.f ? __logf(lbv + (1.f - lbv) * __expf(s1)) : s1; }
;                 *(f32x4*)(LF + (size_t)row * 512 + c) = a; *(f32x4*)(LF + (size_t)row * 512 + c + 4) = b; __builtin_amdgcn_sched_barrier(0); ) }
	v_fma_f32 v195, v151, s52, -v195
	v_fmac_f32_e32 v195, 0x3377d1cf, v151
	v_fmac_f32_e32 v195, 0x3f317217, v151
	v_cmp_lt_f32_e64 s[42:43], |v151|, s53
	s_nop 1
	v_cndmask_b32_e64 v151, v151, v195, s[42:43]
	v_cndmask_b32_e64 v195, 0, v216, s[40:41]
	v_sub_f32_e32 v151, v151, v195
	v_cndmask_b32_e64 v151, v194, v151, s[22:23]
	global_store_dwordx4 v[170:171], v[144:147], off
	global_store_dwordx4 v[170:171], v[148:151], off offset:16
	s_nop 1
	v_pk_mul_f32 v[148:149], v[100:101], v[168:169] op_sel_hi:[1,0]
	v_pk_mul_f32 v[150:151], v[102:103], v[168:169] op_sel_hi:[1,0]
	v_pk_mul_f32 v[146:147], v[98:99], v[168:169] op_sel_hi:[1,0]
	v_pk_mul_f32 v[144:145], v[96:97], v[168:169] op_sel_hi:[1,0]
	v_min_f32_e32 v168, 0, v148
	v_mul_f32_e64 v148, |v148|, s57
	v_exp_f32_e32 v148, v148
	s_nop 0
	v_add_f32_e32 v148, 1.0, v148
	v_log_f32_e32 v148, v148
	s_nop 0
	v_mul_f32_e32 v194, 0x3f317217, v148
	v_fma_f32 v194, v148, s52, -v194
	v_fmac_f32_e32 v194, 0x3377d1cf, v148
	v_fmac_f32_e32 v194, 0x3f317217, v148
	v_mov_b32_e32 v148, v194
	v_sub_f32_e32 v148, v168, v148
	v_min_f32_e32 v168, 0, v144
	v_mul_f32_e64 v144, |v144|, s57
	v_exp_f32_e32 v144, v144
	s_nop 0
	v_add_f32_e32 v144, 1.0, v144
	v_log_f32_e32 v144, v144
	s_nop 0
	v_mul_f32_e32 v194, 0x3f317217, v144
	v_fma_f32 v194, v144, s52, -v194
	v_fmac_f32_e32 v194, 0x3377d1cf, v144
	v_fmac_f32_e32 v194, 0x3f317217, v144
	v_mov_b32_e32 v144, v194
	v_sub_f32_e32 v168, v168, v144
	v_mul_f32_e32 v144, 0x3fb8aa3b, v148
	v_exp_f32_e32 v144, v144
	s_nop 0
	v_fma_f32 v144, v183, v144, v132
	v_cmp_gt_f32_e64 s[40:41], s97, v144
	s_nop 1
	v_cndmask_b32_e64 v194, 0, 32, s[40:41]
	v_ldexp_f32 v144, v144, v194
	v_log_f32_e32 v144, v144
	s_nop 0
	v_mul_f32_e32 v194, 0x3f317217, v144
	v_fma_f32 v194, v144, s52, -v194
	v_fmac_f32_e32 v194, 0x3377d1cf, v144
	v_fmac_f32_e32 v194, 0x3f317217, v144
	v_cmp_lt_f32_e64 s[42:43], |v144|, s53
	s_nop 1
	v_cndmask_b32_e64 v144, v144, v194, s[42:43]
	v_cndmask_b32_e64 v194, 0, v216, s[40:41]
	v_sub_f32_e32 v144, v144, v194
	v_cndmask_b32_e64 v144, v148, v144, s[20:21]
	v_mul_f32_e32 v148, 0x3fb8aa3b, v168
	v_exp_f32_e32 v148, v148
	s_nop 0
	v_fma_f32 v148, v182, v148, v128
	v_cmp_gt_f32_e64 s[40:41], s97, v148
	s_nop 1
	v_cndmask_b32_e64 v194, 0, 32, s[40:41]
	v_ldexp_f32 v148, v148, v194
	v_log_f32_e32 v148, v148
	s_nop 0
	v_mul_f32_e32 v194, 0x3f317217, v148
	v_fma_f32 v194, v148, s52, -v194
	v_fmac_f32_e32 v194, 0x3377d1cf, v148
	v_fmac_f32_e32 v194, 0x3f317217, v148
	v_cmp_lt_f32_e64 s[42:43], |v148|, s53
	s_nop 1
	v_cndmask_b32_e64 v148, v148, v194, s[42:43]
	v_cndmask_b32_e64 v194, 0, v216, s[40:41]
	v_sub_f32_e32 v148, v148, v194
	v_cndmask_b32_e64 v148, v168, v148, s[18:19]
	v_min_f32_e32 v168, 0, v149
	v_mul_f32_e64 v149, |v149|, s57
	v_exp_f32_e32 v149, v149
	s_nop 0
	v_add_f32_e32 v149, 1.0, v149
	v_log_f32_e32 v149, v149
	s_nop 0
	v_mul_f32_e32 v194, 0x3f317217, v149
	v_fma_f32 v194, v149, s52, -v194
	v_fmac_f32_e32 v194, 0x3377d1cf, v149
	v_fmac_f32_e32 v194, 0x3f317217, v149
	v_mov_b32_e32 v149, v194
	v_sub_f32_e32 v149, v168, v149
	v_min_f32_e32 v168, 0, v145
	v_mul_f32_e64 v145, |v145|, s57
	v_exp_f32_e32 v145, v145
	s_nop 0
	v_add_f32_e32 v145, 1.0, v145
	v_log_f32_e32 v145, v145
	s_nop 0
	v_mul_f32_e32 v194, 0x3f317217, v145
	v_fma_f32 v194, v145, s52, -v194
	v_fmac_f32_e32 v194, 0x3377d1cf, v145
	v_fmac_f32_e32 v194, 0x3f317217, v145
	v_mov_b32_e32 v145, v194
	v_sub_f32_e32 v168, v168, v145
	v_mul_f32_e32 v145, 0x3fb8aa3b, v149
	v_exp_f32_e32 v145, v145
	s_nop 0
	v_fma_f32 v145, v181, v145, v133
	v_cmp_gt_f32_e64 s[40:41], s97, v145
	s_nop 1
	v_cndmask_b32_e64 v194, 0, 32, s[40:41]
	v_ldexp_f32 v145, v145, v194
	v_log_f32_e32 v145, v145
	s_nop 0
	v_mul_f32_e32 v194, 0x3f317217, v145
	v_fma_f32 v194, v145, s52, -v194
	v_fmac_f32_e32 v194, 0x3377d1cf, v145
	v_fmac_f32_e32 v194, 0x3f317217, v145
	v_cmp_lt_f32_e64 s[42:43], |v145|, s53
	s_nop 1
	v_cndmask_b32_e64 v145, v145, v194, s[42:43]
	v_cndmask_b32_e64 v194, 0, v216, s[40:41]
	v_sub_f32_e32 v145, v145, v194
	v_cndmask_b32_e64 v145, v149, v145, s[16:17]
	v_mul_f32_e32 v149, 0x3fb8aa3b, v168
	v_exp_f32_e32 v149, v149
	s_nop 0
	v_fma_f32 v149, v180, v149, v129
	v_cmp_gt_f32_e64 s[40:41], s97, v149
	s_nop 1
	v_cndmask_b32_e64 v194, 0, 32, s[40:41]
	v_ldexp_f32 v149, v149, v194
	v_log_f32_e32 v149, v149
	s_nop 0
	v_mul_f32_e32 v194, 0x3f317217, v149
	v_fma_f32 v194, v149, s52, -v194
	v_fmac_f32_e32 v194, 0x3377d1cf, v149
	v_fmac_f32_e32 v194, 0x3f317217, v149
	v_cmp_lt_f32_e64 s[42:43], |v149|, s53
	s_nop 1
	v_cndmask_b32_e64 v149, v149, v194, s[42:43]
	v_cndmask_b32_e64 v194, 0, v216, s[40:41]
	v_sub_f32_e32 v149, v149, v194
	v_cndmask_b32_e64 v149, v168, v149, s[14:15]
	v_min_f32_e32 v168, 0, v150
	v_mul_f32_e64 v150, |v150|, s57
	v_exp_f32_e32 v150, v150
	s_nop 0
	v_add_f32_e32 v150, 1.0, v150
	v_log_f32_e32 v150, v150
	s_nop 0
	v_mul_f32_e32 v194, 0x3f317217, v150
	v_fma_f32 v194, v150, s52, -v194
	v_fmac_f32_e32 v194, 0x3377d1cf, v150
	v_fmac_f32_e32 v194, 0x3f317217, v150
	v_mov_b32_e32 v150, v194
	v_sub_f32_e32 v150, v168, v150
	v_min_f32_e32 v168, 0, v146
	v_mul_f32_e64 v146, |v146|, s57
	v_exp_f32_e32 v146, v146
	s_nop 0
	v_add_f32_e32 v146, 1.0, v146
	v_log_f32_e32 v146, v146
	s_nop 0
	v_mul_f32_e32 v194, 0x3f317217, v146
	v_fma_f32 v194, v146, s52, -v194
	v_fmac_f32_e32 v194, 0x3377d1cf, v146
	v_fmac_f32_e32 v194, 0x3f317217, v146
	v_mov_b32_e32 v146, v194
	v_sub_f32_e32 v168, v168, v146
	v_mul_f32_e32 v146, 0x3fb8aa3b, v150
	v_exp_f32_e32 v146, v146
	s_nop 0
	v_fma_f32 v146, v179, v146, v134
	v_cmp_gt_f32_e64 s[40:41], s97, v146
	s_nop 1
	v_cndmask_b32_e64 v194, 0, 32, s[40:41]
; __device__ __forceinline__ float silu_f(float x) { return x * __builtin_amdgcn_rcpf(1.f + __expf(-x)); }
; __device__ __forceinline__ v4u pack8(const f32x4 a, const f32x4 b) { v4u w; w.x = cvt_pk_bf16(a[0], a[1]); w.y = cvt_pk_bf16(a[2], a[3]); w.z = cvt_pk_bf16(b[0], b[1]); w.w = cvt_pk_bf16(b[2], b[3]); return w; }
;     __device__ __forceinline__ void operator()(const f32x4 (&acc)[2][2][4][2], const pg8::Unit& u, int wr, int wc, int fr, int fq) const {
;     ...
;         if (grp == 0) { WIN_LOOP( _Pragma("unroll") for (int i = 0; i < 4; ++i) { a[i] = silu_f(a[i]); b[i] = silu_f(b[i]); } *(v4u*)(QO + (size_t)row * DM + c) = pack8(a, b); ) }
;         else if (grp == 3) { WIN_LOOP( _Pragma("unroll") for (int i = 0; i < 4; ++i) { a[i] = silu_f(a[i]); b[i] = silu_f(b[i]); } *(v4u*)(GH + (size_t)row * 512 + c) = pack8(a, b); ) }
;         else if (grp == 1) {
;             f32x4 l0[2], l1[2];
; #pragma unroll
;             for (int bj = 0; bj < 2; ++bj) { l0[bj] = *(const f32x4*)(lb + cb + bj * 128); l1[bj] = *(const f32x4*)(lb + cb + bj * 128 + 4); }
;             WIN_LOOP( _Pragma("unroll") for (int i = 0; i < 4; ++i) { const float s0 = fminf(a[i], 0.f) - __logf(1.f + __expf(-fabsf(a[i]))), s1 = fminf(b[i], 0.f) - __logf(1.f + __expf(-fabsf(b[i]))); const float la = l0[bj][i], lbv = l1[bj][i];
;                     a[i] = la > 0.f ? __logf(la + (1.f - la) * __expf(s0)) : s0; b[i] = lbv > 0.f ? __logf(lbv + (1.f - lbv) * __expf(s1)) : s1; }
;                 *(f32x4*)(LF + (size_t)row * 512 + c) = a; *(f32x4*)(LF + (size_t)row * 512 + c + 4) = b; __builtin_amdgcn_sched_barrier(0); ) }
	v_ldexp_f32 v146, v146, v194
	v_log_f32_e32 v146, v146
	s_nop 0
	v_mul_f32_e32 v194, 0x3f317217, v146
	v_fma_f32 v194, v146, s52, -v194
	v_fmac_f32_e32 v194, 0x3377d1cf, v146
	v_fmac_f32_e32 v194, 0x3f317217, v146
	v_cmp_lt_f32_e64 s[42:43], |v146|, s53
	s_nop 1
	v_cndmask_b32_e64 v146, v146, v194, s[42:43]
	v_cndmask_b32_e64 v194, 0, v216, s[40:41]
	v_sub_f32_e32 v146, v146, v194
	v_cndmask_b32_e64 v146, v150, v146, s[12:13]
	v_mul_f32_e32 v150, 0x3fb8aa3b, v168
	v_exp_f32_e32 v150, v150
	s_nop 0
	v_fma_f32 v150, v178, v150, v130
	v_cmp_gt_f32_e64 s[40:41], s97, v150
	s_nop 1
	v_cndmask_b32_e64 v194, 0, 32, s[40:41]
	v_ldexp_f32 v150, v150, v194
	v_log_f32_e32 v150, v150
	s_nop 0
	v_mul_f32_e32 v194, 0x3f317217, v150
	v_fma_f32 v194, v150, s52, -v194
	v_fmac_f32_e32 v194, 0x3377d1cf, v150
	v_fmac_f32_e32 v194, 0x3f317217, v150
	v_cmp_lt_f32_e64 s[42:43], |v150|, s53
	s_nop 1
	v_cndmask_b32_e64 v150, v150, v194, s[42:43]
	v_cndmask_b32_e64 v194, 0, v216, s[40:41]
	v_sub_f32_e32 v150, v150, v194
	v_cndmask_b32_e64 v150, v168, v150, s[10:11]
	v_min_f32_e32 v168, 0, v151
	v_mul_f32_e64 v151, |v151|, s57
	v_exp_f32_e32 v151, v151
	s_nop 0
	v_add_f32_e32 v151, 1.0, v151
	v_log_f32_e32 v151, v151
	s_nop 0
	v_mul_f32_e32 v194, 0x3f317217, v151
	v_fma_f32 v194, v151, s52, -v194
	v_fmac_f32_e32 v194, 0x3377d1cf, v151
	v_fmac_f32_e32 v194, 0x3f317217, v151
	v_mov_b32_e32 v151, v194
	v_sub_f32_e32 v151, v168, v151
	v_min_f32_e32 v168, 0, v147
	v_mul_f32_e64 v147, |v147|, s57
	v_exp_f32_e32 v147, v147
	s_nop 0
	v_add_f32_e32 v147, 1.0, v147
	v_log_f32_e32 v147, v147
	s_nop 0
	v_mul_f32_e32 v194, 0x3f317217, v147
	v_fma_f32 v194, v147, s52, -v194
	v_fmac_f32_e32 v194, 0x3377d1cf, v147
	v_fmac_f32_e32 v194, 0x3f317217, v147
	v_mov_b32_e32 v147, v194
	v_sub_f32_e32 v168, v168, v147
	v_mul_f32_e32 v147, 0x3fb8aa3b, v151
	v_exp_f32_e32 v147, v147
	s_nop 0
	v_fma_f32 v147, v177, v147, v135
	v_cmp_gt_f32_e64 s[40:41], s97, v147
	s_nop 1
	v_cndmask_b32_e64 v194, 0, 32, s[40:41]
	v_ldexp_f32 v147, v147, v194
	v_log_f32_e32 v147, v147
	s_nop 0
	v_mul_f32_e32 v194, 0x3f317217, v147
	v_fma_f32 v194, v147, s52, -v194
	v_fmac_f32_e32 v194, 0x3377d1cf, v147
	v_fmac_f32_e32 v194, 0x3f317217, v147
	v_cmp_lt_f32_e64 s[42:43], |v147|, s53
	s_nop 1
	v_cndmask_b32_e64 v147, v147, v194, s[42:43]
	v_cndmask_b32_e64 v194, 0, v216, s[40:41]
	v_sub_f32_e32 v147, v147, v194
	v_cndmask_b32_e64 v147, v151, v147, s[8:9]
	v_mul_f32_e32 v151, 0x3fb8aa3b, v168
	v_exp_f32_e32 v151, v151
	s_nop 0
	v_fma_f32 v151, v167, v151, v131
	v_cmp_gt_f32_e64 s[40:41], s97, v151
	s_nop 1
	v_cndmask_b32_e64 v194, 0, 32, s[40:41]
	v_ldexp_f32 v151, v151, v194
	v_log_f32_e32 v151, v151
	s_nop 0
	v_mul_f32_e32 v194, 0x3f317217, v151
	v_fma_f32 v194, v151, s52, -v194
	v_fmac_f32_e32 v194, 0x3377d1cf, v151
	v_fmac_f32_e32 v194, 0x3f317217, v151
	v_cmp_lt_f32_e64 s[42:43], |v151|, s53
	s_nop 1
	v_cndmask_b32_e64 v151, v151, v194, s[42:43]
	v_cndmask_b32_e64 v194, 0, v216, s[40:41]
	v_sub_f32_e32 v151, v151, v194
	v_cndmask_b32_e32 v151, v168, v151, vcc
	global_store_dwordx4 v[170:171], v[144:147], off offset:512
	global_store_dwordx4 v[170:171], v[148:151], off offset:528
	s_nop 1
	v_add_u32_e32 v148, 0x80, v166
	v_ashrrev_i32_e32 v149, 31, v148
	v_lshlrev_b64 v[144:145], 6, v[148:149]
	v_lshl_add_u64 v[144:145], v[160:161], 0, v[144:145]
	s_nop 0
	s_waitcnt lgkmcnt(0)
	s_nop 3
	s_nop 0
	s_nop 1
	s_waitcnt lgkmcnt(0)
	s_nop 1
	s_waitcnt lgkmcnt(0)
	s_nop 1
	v_mov_b32_e32 v168, v254
	v_lshlrev_b64 v[144:145], 11, v[148:149]
	v_lshl_add_u64 v[170:171], s[50:51], 0, v[144:145]
	v_lshl_add_u64 v[170:171], v[170:171], 0, v[192:193]
	v_pk_mul_f32 v[148:149], v[28:29], v[168:169] op_sel_hi:[1,0]
	v_pk_mul_f32 v[144:145], v[24:25], v[168:169] op_sel_hi:[1,0]
	v_min_f32_e32 v194, 0, v148
	v_mul_f32_e64 v148, |v148|, s57
	v_exp_f32_e32 v148, v148
	v_pk_mul_f32 v[150:151], v[30:31], v[168:169] op_sel_hi:[1,0]
	v_pk_mul_f32 v[146:147], v[26:27], v[168:169] op_sel_hi:[1,0]
	v_add_f32_e32 v148, 1.0, v148
	v_log_f32_e32 v148, v148
	s_nop 0
	v_mul_f32_e32 v195, 0x3f317217, v148
	v_fma_f32 v195, v148, s52, -v195
	v_fmac_f32_e32 v195, 0x3377d1cf, v148
	v_fmac_f32_e32 v195, 0x3f317217, v148
	v_mov_b32_e32 v148, v195
	v_sub_f32_e32 v148, v194, v148
	v_min_f32_e32 v194, 0, v144
	v_mul_f32_e64 v144, |v144|, s57
	v_exp_f32_e32 v144, v144
	s_nop 0
	v_add_f32_e32 v144, 1.0, v144
	v_log_f32_e32 v144, v144
	s_nop 0
	v_mul_f32_e32 v195, 0x3f317217, v144
	v_fma_f32 v195, v144, s52, -v195
	v_fmac_f32_e32 v195, 0x3377d1cf, v144
	v_fmac_f32_e32 v195, 0x3f317217, v144
	v_mov_b32_e32 v144, v195
	v_sub_f32_e32 v194, v194, v144
	v_mul_f32_e32 v144, 0x3fb8aa3b, v148
	v_exp_f32_e32 v144, v144
	s_nop 0
	v_fma_f32 v144, v190, v144, v140
	v_cmp_gt_f32_e64 s[40:41], s97, v144
	s_nop 1
	v_cndmask_b32_e64 v195, 0, 32, s[40:41]
	v_ldexp_f32 v144, v144, v195
	v_log_f32_e32 v144, v144
	s_nop 0
	v_mul_f32_e32 v195, 0x3f317217, v144
	v_fma_f32 v195, v144, s52, -v195
	v_fmac_f32_e32 v195, 0x3377d1cf, v144
	v_fmac_f32_e32 v195, 0x3f317217, v144
	v_cmp_lt_f32_e64 s[42:43], |v144|, s53
	s_nop 1
	v_cndmask_b32_e64 v144, v144, v195, s[42:43]
	v_cndmask_b32_e64 v195, 0, v216, s[40:41]
	v_sub_f32_e32 v144, v144, v195
	v_cndmask_b32_e64 v144, v148, v144, s[38:39]
	v_mul_f32_e32 v148, 0x3fb8aa3b, v194
	v_exp_f32_e32 v148, v148
	s_nop 0
	v_fma_f32 v148, v191, v148, v136
	v_cmp_gt_f32_e64 s[40:41], s97, v148
	s_nop 1
	v_cndmask_b32_e64 v195, 0, 32, s[40:41]
	v_ldexp_f32 v148, v148, v195
	v_log_f32_e32 v148, v148
	s_nop 0
	v_mul_f32_e32 v195, 0x3f317217, v148
	v_fma_f32 v195, v148, s52, -v195
	v_fmac_f32_e32 v195, 0x3377d1cf, v148
	v_fmac_f32_e32 v195, 0x3f317217, v148
; __device__ __forceinline__ float silu_f(float x) { return x * __builtin_amdgcn_rcpf(1.f + __expf(-x)); }
; __device__ __forceinline__ v4u pack8(const f32x4 a, const f32x4 b) { v4u w; w.x = cvt_pk_bf16(a[0], a[1]); w.y = cvt_pk_bf16(a[2], a[3]); w.z = cvt_pk_bf16(b[0], b[1]); w.w = cvt_pk_bf16(b[2], b[3]); return w; }
;     __device__ __forceinline__ void operator()(const f32x4 (&acc)[2][2][4][2], const pg8::Unit& u, int wr, int wc, int fr, int fq) const {
;     ...
;         if (grp == 0) { WIN_LOOP( _Pragma("unroll") for (int i = 0; i < 4; ++i) { a[i] = silu_f(a[i]); b[i] = silu_f(b[i]); } *(v4u*)(QO + (size_t)row * DM + c) = pack8(a, b); ) }
;         else if (grp == 3) { WIN_LOOP( _Pragma("unroll") for (int i = 0; i < 4; ++i) { a[i] = silu_f(a[i]); b[i] = silu_f(b[i]); } *(v4u*)(GH + (size_t)row * 512 + c) = pack8(a, b); ) }
;         else if (grp == 1) {
;             f32x4 l0[2], l1[2];
; #pragma unroll
;             for (int bj = 0; bj < 2; ++bj) { l0[bj] = *(const f32x4*)(lb + cb + bj * 128); l1[bj] = *(const f32x4*)(lb + cb + bj * 128 + 4); }
;             WIN_LOOP( _Pragma("unroll") for (int i = 0; i < 4; ++i) { const float s0 = fminf(a[i], 0.f) - __logf(1.f + __expf(-fabsf(a[i]))), s1 = fminf(b[i], 0.f) - __logf(1.f + __expf(-fabsf(b[i]))); const float la = l0[bj][i], lbv = l1[bj][i];
;                     a[i] = la > 0.f ? __logf(la + (1.f - la) * __expf(s0)) : s0; b[i] = lbv > 0.f ? __logf(lbv + (1.f - lbv) * __expf(s1)) : s1; }
;                 *(f32x4*)(LF + (size_t)row * 512 + c) = a; *(f32x4*)(LF + (size_t)row * 512 + c + 4) = b; __builtin_amdgcn_sched_barrier(0); ) }
	v_cmp_lt_f32_e64 s[42:43], |v148|, s53
	s_nop 1
	v_cndmask_b32_e64 v148, v148, v195, s[42:43]
	v_cndmask_b32_e64 v195, 0, v216, s[40:41]
	v_sub_f32_e32 v148, v148, v195
	v_cndmask_b32_e64 v148, v194, v148, s[36:37]
	v_min_f32_e32 v194, 0, v149
	v_mul_f32_e64 v149, |v149|, s57
	v_exp_f32_e32 v149, v149
	s_nop 0
	v_add_f32_e32 v149, 1.0, v149
	v_log_f32_e32 v149, v149
	s_nop 0
	v_mul_f32_e32 v195, 0x3f317217, v149
	v_fma_f32 v195, v149, s52, -v195
	v_fmac_f32_e32 v195, 0x3377d1cf, v149
	v_fmac_f32_e32 v195, 0x3f317217, v149
	v_mov_b32_e32 v149, v195
	v_sub_f32_e32 v149, v194, v149
	v_min_f32_e32 v194, 0, v145
	v_mul_f32_e64 v145, |v145|, s57
	v_exp_f32_e32 v145, v145
	s_nop 0
	v_add_f32_e32 v145, 1.0, v145
	v_log_f32_e32 v145, v145
	s_nop 0
	v_mul_f32_e32 v195, 0x3f317217, v145
	v_fma_f32 v195, v145, s52, -v195
	v_fmac_f32_e32 v195, 0x3377d1cf, v145
	v_fmac_f32_e32 v195, 0x3f317217, v145
	v_mov_b32_e32 v145, v195
	v_sub_f32_e32 v194, v194, v145
	v_mul_f32_e32 v145, 0x3fb8aa3b, v149
	v_exp_f32_e32 v145, v145
	s_nop 0
	v_fma_f32 v145, v188, v145, v141
	v_cmp_gt_f32_e64 s[40:41], s97, v145
	s_nop 1
	v_cndmask_b32_e64 v195, 0, 32, s[40:41]
	v_ldexp_f32 v145, v145, v195
	v_log_f32_e32 v145, v145
	s_nop 0
	v_mul_f32_e32 v195, 0x3f317217, v145
	v_fma_f32 v195, v145, s52, -v195
	v_fmac_f32_e32 v195, 0x3377d1cf, v145
	v_fmac_f32_e32 v195, 0x3f317217, v145
	v_cmp_lt_f32_e64 s[42:43], |v145|, s53
	s_nop 1
	v_cndmask_b32_e64 v145, v145, v195, s[42:43]
	v_cndmask_b32_e64 v195, 0, v216, s[40:41]
	v_sub_f32_e32 v145, v145, v195
	v_cndmask_b32_e64 v145, v149, v145, s[34:35]
	v_mul_f32_e32 v149, 0x3fb8aa3b, v194
	v_exp_f32_e32 v149, v149
	s_nop 0
	v_fma_f32 v149, v189, v149, v137
	v_cmp_gt_f32_e64 s[40:41], s97, v149
	s_nop 1
	v_cndmask_b32_e64 v195, 0, 32, s[40:41]
	v_ldexp_f32 v149, v149, v195
	v_log_f32_e32 v149, v149
	s_nop 0
	v_mul_f32_e32 v195, 0x3f317217, v149
	v_fma_f32 v195, v149, s52, -v195
	v_fmac_f32_e32 v195, 0x3377d1cf, v149
	v_fmac_f32_e32 v195, 0x3f317217, v149
	v_cmp_lt_f32_e64 s[42:43], |v149|, s53
	s_nop 1
	v_cndmask_b32_e64 v149, v149, v195, s[42:43]
	v_cndmask_b32_e64 v195, 0, v216, s[40:41]
	v_sub_f32_e32 v149, v149, v195
	v_cndmask_b32_e64 v149, v194, v149, s[30:31]
	v_min_f32_e32 v194, 0, v150
	v_mul_f32_e64 v150, |v150|, s57
	v_exp_f32_e32 v150, v150
	s_nop 0
	v_add_f32_e32 v150, 1.0, v150
	v_log_f32_e32 v150, v150
	s_nop 0
	v_mul_f32_e32 v195, 0x3f317217, v150
	v_fma_f32 v195, v150, s52, -v195
	v_fmac_f32_e32 v195, 0x3377d1cf, v150
	v_fmac_f32_e32 v195, 0x3f317217, v150
	v_mov_b32_e32 v150, v195
	v_sub_f32_e32 v150, v194, v150
	v_min_f32_e32 v194, 0, v146
	v_mul_f32_e64 v146, |v146|, s57
	v_exp_f32_e32 v146, v146
	s_nop 0
	v_add_f32_e32 v146, 1.0, v146
	v_log_f32_e32 v146, v146
	s_nop 0
	v_mul_f32_e32 v195, 0x3f317217, v146
	v_fma_f32 v195, v146, s52, -v195
	v_fmac_f32_e32 v195, 0x3377d1cf, v146
	v_fmac_f32_e32 v195, 0x3f317217, v146
	v_mov_b32_e32 v146, v195
	v_sub_f32_e32 v194, v194, v146
	v_mul_f32_e32 v146, 0x3fb8aa3b, v150
	v_exp_f32_e32 v146, v146
	s_nop 0
	v_fma_f32 v146, v187, v146, v142
	v_cmp_gt_f32_e64 s[40:41], s97, v146
	s_nop 1
	v_cndmask_b32_e64 v195, 0, 32, s[40:41]
	v_ldexp_f32 v146, v146, v195
	v_log_f32_e32 v146, v146
	s_nop 0
	v_mul_f32_e32 v195, 0x3f317217, v146
	v_fma_f32 v195, v146, s52, -v195
	v_fmac_f32_e32 v195, 0x3377d1cf, v146
	v_fmac_f32_e32 v195, 0x3f317217, v146
	v_cmp_lt_f32_e64 s[42:43], |v146|, s53
	s_nop 1
	v_cndmask_b32_e64 v146, v146, v195, s[42:43]
	v_cndmask_b32_e64 v195, 0, v216, s[40:41]
	v_sub_f32_e32 v146, v146, v195
	v_cndmask_b32_e64 v146, v150, v146, s[28:29]
	v_mul_f32_e32 v150, 0x3fb8aa3b, v194
	v_exp_f32_e32 v150, v150
	s_nop 0
	v_fma_f32 v150, v186, v150, v138
	v_cmp_gt_f32_e64 s[40:41], s97, v150
	s_nop 1
	v_cndmask_b32_e64 v195, 0, 32, s[40:41]
	v_ldexp_f32 v150, v150, v195
	v_log_f32_e32 v150, v150
	s_nop 0
	v_mul_f32_e32 v195, 0x3f317217, v150
	v_fma_f32 v195, v150, s52, -v195
	v_fmac_f32_e32 v195, 0x3377d1cf, v150
	v_fmac_f32_e32 v195, 0x3f317217, v150
	v_cmp_lt_f32_e64 s[42:43], |v150|, s53
	s_nop 1
	v_cndmask_b32_e64 v150, v150, v195, s[42:43]
	v_cndmask_b32_e64 v195, 0, v216, s[40:41]
	v_sub_f32_e32 v150, v150, v195
	v_cndmask_b32_e64 v150, v194, v150, s[26:27]
	v_min_f32_e32 v194, 0, v151
	v_mul_f32_e64 v151, |v151|, s57
	v_exp_f32_e32 v151, v151
	s_nop 0
	v_add_f32_e32 v151, 1.0, v151
	v_log_f32_e32 v151, v151
	s_nop 0
	v_mul_f32_e32 v195, 0x3f317217, v151
	v_fma_f32 v195, v151, s52, -v195
	v_fmac_f32_e32 v195, 0x3377d1cf, v151
	v_fmac_f32_e32 v195, 0x3f317217, v151
	v_mov_b32_e32 v151, v195
	v_sub_f32_e32 v151, v194, v151
	v_min_f32_e32 v194, 0, v147
	v_mul_f32_e64 v147, |v147|, s57
	v_exp_f32_e32 v147, v147
	s_nop 0
	v_add_f32_e32 v147, 1.0, v147
	v_log_f32_e32 v147, v147
	s_nop 0
	v_mul_f32_e32 v195, 0x3f317217, v147
	v_fma_f32 v195, v147, s52, -v195
	v_fmac_f32_e32 v195, 0x3377d1cf, v147
	v_fmac_f32_e32 v195, 0x3f317217, v147
	v_mov_b32_e32 v147, v195
	v_sub_f32_e32 v194, v194, v147
	v_mul_f32_e32 v147, 0x3fb8aa3b, v151
	v_exp_f32_e32 v147, v147
	s_nop 0
	v_fma_f32 v147, v185, v147, v143
	v_cmp_gt_f32_e64 s[40:41], s97, v147
	s_nop 1
	v_cndmask_b32_e64 v195, 0, 32, s[40:41]
	v_ldexp_f32 v147, v147, v195
	v_log_f32_e32 v147, v147
	s_nop 0
	v_mul_f32_e32 v195, 0x3f317217, v147
	v_fma_f32 v195, v147, s52, -v195
	v_fmac_f32_e32 v195, 0x3377d1cf, v147
	v_fmac_f32_e32 v195, 0x3f317217, v147
	v_cmp_lt_f32_e64 s[42:43], |v147|, s53
	s_nop 1
	v_cndmask_b32_e64 v147, v147, v195, s[42:43]
	v_cndmask_b32_e64 v195, 0, v216, s[40:41]
	v_sub_f32_e32 v147, v147, v195
	v_cndmask_b32_e64 v147, v151, v147, s[24:25]
	v_mul_f32_e32 v151, 0x3fb8aa3b, v194
	v_exp_f32_e32 v151, v151
; __device__ __forceinline__ float silu_f(float x) { return x * __builtin_amdgcn_rcpf(1.f + __expf(-x)); }
; __device__ __forceinline__ v4u pack8(const f32x4 a, const f32x4 b) { v4u w; w.x = cvt_pk_bf16(a[0], a[1]); w.y = cvt_pk_bf16(a[2], a[3]); w.z = cvt_pk_bf16(b[0], b[1]); w.w = cvt_pk_bf16(b[2], b[3]); return w; }
;     __device__ __forceinline__ void operator()(const f32x4 (&acc)[2][2][4][2], const pg8::Unit& u, int wr, int wc, int fr, int fq) const {
;     ...
;         if (grp == 0) { WIN_LOOP( _Pragma("unroll") for (int i = 0; i < 4; ++i) { a[i] = silu_f(a[i]); b[i] = silu_f(b[i]); } *(v4u*)(QO + (size_t)row * DM + c) = pack8(a, b); ) }
;         else if (grp == 3) { WIN_LOOP( _Pragma("unroll") for (int i = 0; i < 4; ++i) { a[i] = silu_f(a[i]); b[i] = silu_f(b[i]); } *(v4u*)(GH + (size_t)row * 512 + c) = pack8(a, b); ) }
;         else if (grp == 1) {
;             f32x4 l0[2], l1[2];
; #pragma unroll
;             for (int bj = 0; bj < 2; ++bj) { l0[bj] = *(const f32x4*)(lb + cb + bj * 128); l1[bj] = *(const f32x4*)(lb + cb + bj * 128 + 4); }
;             WIN_LOOP( _Pragma("unroll") for (int i = 0; i < 4; ++i) { const float s0 = fminf(a[i], 0.f) - __logf(1.f + __expf(-fabsf(a[i]))), s1 = fminf(b[i], 0.f) - __logf(1.f + __expf(-fabsf(b[i]))); const float la = l0[bj][i], lbv = l1[bj][i];
;                     a[i] = la > 0.f ? __logf(la + (1.f - la) * __expf(s0)) : s0; b[i] = lbv > 0.f ? __logf(lbv + (1.f - lbv) * __expf(s1)) : s1; }
;                 *(f32x4*)(LF + (size_t)row * 512 + c) = a; *(f32x4*)(LF + (size_t)row * 512 + c + 4) = b; __builtin_amdgcn_sched_barrier(0); ) }
	s_nop 0
	v_fma_f32 v151, v184, v151, v139
	v_cmp_gt_f32_e64 s[40:41], s97, v151
	s_nop 1
	v_cndmask_b32_e64 v195, 0, 32, s[40:41]
	v_ldexp_f32 v151, v151, v195
	v_log_f32_e32 v151, v151
	s_nop 0
	v_mul_f32_e32 v195, 0x3f317217, v151
	v_fma_f32 v195, v151, s52, -v195
	v_fmac_f32_e32 v195, 0x3377d1cf, v151
	v_fmac_f32_e32 v195, 0x3f317217, v151
	v_cmp_lt_f32_e64 s[42:43], |v151|, s53
	s_nop 1
	v_cndmask_b32_e64 v151, v151, v195, s[42:43]
	v_cndmask_b32_e64 v195, 0, v216, s[40:41]
	v_sub_f32_e32 v151, v151, v195
	v_cndmask_b32_e64 v151, v194, v151, s[22:23]
	global_store_dwordx4 v[170:171], v[144:147], off
	global_store_dwordx4 v[170:171], v[148:151], off offset:16
	s_nop 1
	v_pk_mul_f32 v[148:149], v[92:93], v[168:169] op_sel_hi:[1,0]
	v_pk_mul_f32 v[150:151], v[94:95], v[168:169] op_sel_hi:[1,0]
	v_pk_mul_f32 v[146:147], v[90:91], v[168:169] op_sel_hi:[1,0]
	v_pk_mul_f32 v[144:145], v[88:89], v[168:169] op_sel_hi:[1,0]
	v_min_f32_e32 v168, 0, v148
	v_mul_f32_e64 v148, |v148|, s57
	v_exp_f32_e32 v148, v148
	s_nop 0
	v_add_f32_e32 v148, 1.0, v148
	v_log_f32_e32 v148, v148
	s_nop 0
	v_mul_f32_e32 v194, 0x3f317217, v148
	v_fma_f32 v194, v148, s52, -v194
	v_fmac_f32_e32 v194, 0x3377d1cf, v148
	v_fmac_f32_e32 v194, 0x3f317217, v148
	v_mov_b32_e32 v148, v194
	v_sub_f32_e32 v148, v168, v148
	v_min_f32_e32 v168, 0, v144
	v_mul_f32_e64 v144, |v144|, s57
	v_exp_f32_e32 v144, v144
	s_nop 0
	v_add_f32_e32 v144, 1.0, v144
	v_log_f32_e32 v144, v144
	s_nop 0
	v_mul_f32_e32 v194, 0x3f317217, v144
	v_fma_f32 v194, v144, s52, -v194
	v_fmac_f32_e32 v194, 0x3377d1cf, v144
	v_fmac_f32_e32 v194, 0x3f317217, v144
	v_mov_b32_e32 v144, v194
	v_sub_f32_e32 v168, v168, v144
	v_mul_f32_e32 v144, 0x3fb8aa3b, v148
	v_exp_f32_e32 v144, v144
	s_nop 0
	v_fma_f32 v144, v183, v144, v132
	v_cmp_gt_f32_e64 s[40:41], s97, v144
	s_nop 1
	v_cndmask_b32_e64 v194, 0, 32, s[40:41]
	v_ldexp_f32 v144, v144, v194
	v_log_f32_e32 v144, v144
	s_nop 0
	v_mul_f32_e32 v194, 0x3f317217, v144
	v_fma_f32 v194, v144, s52, -v194
	v_fmac_f32_e32 v194, 0x3377d1cf, v144
	v_fmac_f32_e32 v194, 0x3f317217, v144
	v_cmp_lt_f32_e64 s[42:43], |v144|, s53
	s_nop 1
	v_cndmask_b32_e64 v144, v144, v194, s[42:43]
	v_cndmask_b32_e64 v194, 0, v216, s[40:41]
	v_sub_f32_e32 v144, v144, v194
	v_cndmask_b32_e64 v144, v148, v144, s[20:21]
	v_mul_f32_e32 v148, 0x3fb8aa3b, v168
	v_exp_f32_e32 v148, v148
	s_nop 0
	v_fma_f32 v148, v182, v148, v128
	v_cmp_gt_f32_e64 s[40:41], s97, v148
	s_nop 1
	v_cndmask_b32_e64 v194, 0, 32, s[40:41]
	v_ldexp_f32 v148, v148, v194
	v_log_f32_e32 v148, v148
	s_nop 0
	v_mul_f32_e32 v194, 0x3f317217, v148
	v_fma_f32 v194, v148, s52, -v194
	v_fmac_f32_e32 v194, 0x3377d1cf, v148
	v_fmac_f32_e32 v194, 0x3f317217, v148
	v_cmp_lt_f32_e64 s[42:43], |v148|, s53
	s_nop 1
	v_cndmask_b32_e64 v148, v148, v194, s[42:43]
	v_cndmask_b32_e64 v194, 0, v216, s[40:41]
	v_sub_f32_e32 v148, v148, v194
	v_cndmask_b32_e64 v148, v168, v148, s[18:19]
	v_min_f32_e32 v168, 0, v149
	v_mul_f32_e64 v149, |v149|, s57
	v_exp_f32_e32 v149, v149
	s_nop 0
	v_add_f32_e32 v149, 1.0, v149
	v_log_f32_e32 v149, v149
	s_nop 0
	v_mul_f32_e32 v194, 0x3f317217, v149
	v_fma_f32 v194, v149, s52, -v194
	v_fmac_f32_e32 v194, 0x3377d1cf, v149
	v_fmac_f32_e32 v194, 0x3f317217, v149
	v_mov_b32_e32 v149, v194
	v_sub_f32_e32 v149, v168, v149
	v_min_f32_e32 v168, 0, v145
	v_mul_f32_e64 v145, |v145|, s57
	v_exp_f32_e32 v145, v145
	s_nop 0
	v_add_f32_e32 v145, 1.0, v145
	v_log_f32_e32 v145, v145
	s_nop 0
	v_mul_f32_e32 v194, 0x3f317217, v145
	v_fma_f32 v194, v145, s52, -v194
	v_fmac_f32_e32 v194, 0x3377d1cf, v145
	v_fmac_f32_e32 v194, 0x3f317217, v145
	v_mov_b32_e32 v145, v194
	v_sub_f32_e32 v168, v168, v145
	v_mul_f32_e32 v145, 0x3fb8aa3b, v149
	v_exp_f32_e32 v145, v145
	s_nop 0
	v_fma_f32 v145, v181, v145, v133
	v_cmp_gt_f32_e64 s[40:41], s97, v145
	s_nop 1
	v_cndmask_b32_e64 v194, 0, 32, s[40:41]
	v_ldexp_f32 v145, v145, v194
	v_log_f32_e32 v145, v145
	s_nop 0
	v_mul_f32_e32 v194, 0x3f317217, v145
	v_fma_f32 v194, v145, s52, -v194
	v_fmac_f32_e32 v194, 0x3377d1cf, v145
	v_fmac_f32_e32 v194, 0x3f317217, v145
	v_cmp_lt_f32_e64 s[42:43], |v145|, s53
	s_nop 1
	v_cndmask_b32_e64 v145, v145, v194, s[42:43]
	v_cndmask_b32_e64 v194, 0, v216, s[40:41]
	v_sub_f32_e32 v145, v145, v194
	v_cndmask_b32_e64 v145, v149, v145, s[16:17]
	v_mul_f32_e32 v149, 0x3fb8aa3b, v168
	v_exp_f32_e32 v149, v149
	s_nop 0
	v_fma_f32 v149, v180, v149, v129
	v_cmp_gt_f32_e64 s[40:41], s97, v149
	s_nop 1
	v_cndmask_b32_e64 v194, 0, 32, s[40:41]
	v_ldexp_f32 v149, v149, v194
	v_log_f32_e32 v149, v149
	s_nop 0
	v_mul_f32_e32 v194, 0x3f317217, v149
	v_fma_f32 v194, v149, s52, -v194
	v_fmac_f32_e32 v194, 0x3377d1cf, v149
	v_fmac_f32_e32 v194, 0x3f317217, v149
	v_cmp_lt_f32_e64 s[42:43], |v149|, s53
	s_nop 1
	v_cndmask_b32_e64 v149, v149, v194, s[42:43]
	v_cndmask_b32_e64 v194, 0, v216, s[40:41]
	v_sub_f32_e32 v149, v149, v194
	v_cndmask_b32_e64 v149, v168, v149, s[14:15]
	v_min_f32_e32 v168, 0, v150
	v_mul_f32_e64 v150, |v150|, s57
	v_exp_f32_e32 v150, v150
	s_nop 0
	v_add_f32_e32 v150, 1.0, v150
	v_log_f32_e32 v150, v150
	s_nop 0
	v_mul_f32_e32 v194, 0x3f317217, v150
	v_fma_f32 v194, v150, s52, -v194
	v_fmac_f32_e32 v194, 0x3377d1cf, v150
	v_fmac_f32_e32 v194, 0x3f317217, v150
	v_mov_b32_e32 v150, v194
	v_sub_f32_e32 v150, v168, v150
	v_min_f32_e32 v168, 0, v146
	v_mul_f32_e64 v146, |v146|, s57
	v_exp_f32_e32 v146, v146
	s_nop 0
	v_add_f32_e32 v146, 1.0, v146
	v_log_f32_e32 v146, v146
	s_nop 0
	v_mul_f32_e32 v194, 0x3f317217, v146
	v_fma_f32 v194, v146, s52, -v194
	v_fmac_f32_e32 v194, 0x3377d1cf, v146
	v_fmac_f32_e32 v194, 0x3f317217, v146
	v_mov_b32_e32 v146, v194
; __device__ __forceinline__ float silu_f(float x) { return x * __builtin_amdgcn_rcpf(1.f + __expf(-x)); }
; __device__ __forceinline__ v4u pack8(const f32x4 a, const f32x4 b) { v4u w; w.x = cvt_pk_bf16(a[0], a[1]); w.y = cvt_pk_bf16(a[2], a[3]); w.z = cvt_pk_bf16(b[0], b[1]); w.w = cvt_pk_bf16(b[2], b[3]); return w; }
;     __device__ __forceinline__ void operator()(const f32x4 (&acc)[2][2][4][2], const pg8::Unit& u, int wr, int wc, int fr, int fq) const {
;     ...
;         if (grp == 0) { WIN_LOOP( _Pragma("unroll") for (int i = 0; i < 4; ++i) { a[i] = silu_f(a[i]); b[i] = silu_f(b[i]); } *(v4u*)(QO + (size_t)row * DM + c) = pack8(a, b); ) }
;         else if (grp == 3) { WIN_LOOP( _Pragma("unroll") for (int i = 0; i < 4; ++i) { a[i] = silu_f(a[i]); b[i] = silu_f(b[i]); } *(v4u*)(GH + (size_t)row * 512 + c) = pack8(a, b); ) }
;         else if (grp == 1) {
;             f32x4 l0[2], l1[2];
; #pragma unroll
;             for (int bj = 0; bj < 2; ++bj) { l0[bj] = *(const f32x4*)(lb + cb + bj * 128); l1[bj] = *(const f32x4*)(lb + cb + bj * 128 + 4); }
;             WIN_LOOP( _Pragma("unroll") for (int i = 0; i < 4; ++i) { const float s0 = fminf(a[i], 0.f) - __logf(1.f + __expf(-fabsf(a[i]))), s1 = fminf(b[i], 0.f) - __logf(1.f + __expf(-fabsf(b[i]))); const float la = l0[bj][i], lbv = l1[bj][i];
;                     a[i] = la > 0.f ? __logf(la + (1.f - la) * __expf(s0)) : s0; b[i] = lbv > 0.f ? __logf(lbv + (1.f - lbv) * __expf(s1)) : s1; }
;                 *(f32x4*)(LF + (size_t)row * 512 + c) = a; *(f32x4*)(LF + (size_t)row * 512 + c + 4) = b; __builtin_amdgcn_sched_barrier(0); ) }
	v_sub_f32_e32 v168, v168, v146
	v_mul_f32_e32 v146, 0x3fb8aa3b, v150
	v_exp_f32_e32 v146, v146
	s_nop 0
	v_fma_f32 v146, v179, v146, v134
	v_cmp_gt_f32_e64 s[40:41], s97, v146
	s_nop 1
	v_cndmask_b32_e64 v194, 0, 32, s[40:41]
	v_ldexp_f32 v146, v146, v194
	v_log_f32_e32 v146, v146
	s_nop 0
	v_mul_f32_e32 v194, 0x3f317217, v146
	v_fma_f32 v194, v146, s52, -v194
	v_fmac_f32_e32 v194, 0x3377d1cf, v146
	v_fmac_f32_e32 v194, 0x3f317217, v146
	v_cmp_lt_f32_e64 s[42:43], |v146|, s53
	s_nop 1
	v_cndmask_b32_e64 v146, v146, v194, s[42:43]
	v_cndmask_b32_e64 v194, 0, v216, s[40:41]
	v_sub_f32_e32 v146, v146, v194
	v_cndmask_b32_e64 v146, v150, v146, s[12:13]
	v_mul_f32_e32 v150, 0x3fb8aa3b, v168
	v_exp_f32_e32 v150, v150
	s_nop 0
	v_fma_f32 v150, v178, v150, v130
	v_cmp_gt_f32_e64 s[40:41], s97, v150
	s_nop 1
	v_cndmask_b32_e64 v194, 0, 32, s[40:41]
	v_ldexp_f32 v150, v150, v194
	v_log_f32_e32 v150, v150
	s_nop 0
	v_mul_f32_e32 v194, 0x3f317217, v150
	v_fma_f32 v194, v150, s52, -v194
	v_fmac_f32_e32 v194, 0x3377d1cf, v150
	v_fmac_f32_e32 v194, 0x3f317217, v150
	v_cmp_lt_f32_e64 s[42:43], |v150|, s53
	s_nop 1
	v_cndmask_b32_e64 v150, v150, v194, s[42:43]
	v_cndmask_b32_e64 v194, 0, v216, s[40:41]
	v_sub_f32_e32 v150, v150, v194
	v_cndmask_b32_e64 v150, v168, v150, s[10:11]
	v_min_f32_e32 v168, 0, v151
	v_mul_f32_e64 v151, |v151|, s57
	v_exp_f32_e32 v151, v151
	s_nop 0
	v_add_f32_e32 v151, 1.0, v151
	v_log_f32_e32 v151, v151
	s_nop 0
	v_mul_f32_e32 v194, 0x3f317217, v151
	v_fma_f32 v194, v151, s52, -v194
	v_fmac_f32_e32 v194, 0x3377d1cf, v151
	v_fmac_f32_e32 v194, 0x3f317217, v151
	v_mov_b32_e32 v151, v194
	v_sub_f32_e32 v151, v168, v151
	v_min_f32_e32 v168, 0, v147
	v_mul_f32_e64 v147, |v147|, s57
	v_exp_f32_e32 v147, v147
	s_nop 0
	v_add_f32_e32 v147, 1.0, v147
	v_log_f32_e32 v147, v147
	s_nop 0
	v_mul_f32_e32 v194, 0x3f317217, v147
	v_fma_f32 v194, v147, s52, -v194
	v_fmac_f32_e32 v194, 0x3377d1cf, v147
	v_fmac_f32_e32 v194, 0x3f317217, v147
	v_mov_b32_e32 v147, v194
	v_sub_f32_e32 v168, v168, v147
	v_mul_f32_e32 v147, 0x3fb8aa3b, v151
	v_exp_f32_e32 v147, v147
	s_nop 0
	v_fma_f32 v147, v177, v147, v135
	v_cmp_gt_f32_e64 s[40:41], s97, v147
	s_nop 1
	v_cndmask_b32_e64 v194, 0, 32, s[40:41]
	v_ldexp_f32 v147, v147, v194
	v_log_f32_e32 v147, v147
	s_nop 0
	v_mul_f32_e32 v194, 0x3f317217, v147
	v_fma_f32 v194, v147, s52, -v194
	v_fmac_f32_e32 v194, 0x3377d1cf, v147
	v_fmac_f32_e32 v194, 0x3f317217, v147
	v_cmp_lt_f32_e64 s[42:43], |v147|, s53
	s_nop 1
	v_cndmask_b32_e64 v147, v147, v194, s[42:43]
	v_cndmask_b32_e64 v194, 0, v216, s[40:41]
	v_sub_f32_e32 v147, v147, v194
	v_cndmask_b32_e64 v147, v151, v147, s[8:9]
	v_mul_f32_e32 v151, 0x3fb8aa3b, v168
	v_exp_f32_e32 v151, v151
	s_nop 0
	v_fma_f32 v151, v167, v151, v131
	v_cmp_gt_f32_e64 s[40:41], s97, v151
	s_nop 1
	v_cndmask_b32_e64 v194, 0, 32, s[40:41]
	v_ldexp_f32 v151, v151, v194
	v_log_f32_e32 v151, v151
	s_nop 0
	v_mul_f32_e32 v194, 0x3f317217, v151
	v_fma_f32 v194, v151, s52, -v194
	v_fmac_f32_e32 v194, 0x3377d1cf, v151
	v_fmac_f32_e32 v194, 0x3f317217, v151
	v_cmp_lt_f32_e64 s[42:43], |v151|, s53
	s_nop 1
	v_cndmask_b32_e64 v151, v151, v194, s[42:43]
	v_cndmask_b32_e64 v194, 0, v216, s[40:41]
	v_sub_f32_e32 v151, v151, v194
	v_cndmask_b32_e32 v151, v168, v151, vcc
	global_store_dwordx4 v[170:171], v[144:147], off offset:512
	global_store_dwordx4 v[170:171], v[148:151], off offset:528
	s_nop 1
	v_add_u32_e32 v148, 0x90, v166
	v_ashrrev_i32_e32 v149, 31, v148
	v_lshlrev_b64 v[144:145], 6, v[148:149]
	v_lshl_add_u64 v[144:145], v[160:161], 0, v[144:145]
	s_nop 0
	s_waitcnt lgkmcnt(0)
	s_nop 3
	s_nop 0
	s_nop 1
	s_waitcnt lgkmcnt(0)
	s_nop 1
	s_waitcnt lgkmcnt(0)
	s_nop 1
	v_mov_b32_e32 v168, v240
	v_lshlrev_b64 v[144:145], 11, v[148:149]
	v_lshl_add_u64 v[170:171], s[50:51], 0, v[144:145]
	v_lshl_add_u64 v[170:171], v[170:171], 0, v[192:193]
	v_pk_mul_f32 v[148:149], v[20:21], v[168:169] op_sel_hi:[1,0]
	v_pk_mul_f32 v[144:145], v[16:17], v[168:169] op_sel_hi:[1,0]
	v_min_f32_e32 v194, 0, v148
	v_mul_f32_e64 v148, |v148|, s57
	v_exp_f32_e32 v148, v148
	v_pk_mul_f32 v[150:151], v[22:23], v[168:169] op_sel_hi:[1,0]
	v_pk_mul_f32 v[146:147], v[18:19], v[168:169] op_sel_hi:[1,0]
	v_add_f32_e32 v148, 1.0, v148
	v_log_f32_e32 v148, v148
	s_nop 0
	v_mul_f32_e32 v195, 0x3f317217, v148
	v_fma_f32 v195, v148, s52, -v195
	v_fmac_f32_e32 v195, 0x3377d1cf, v148
	v_fmac_f32_e32 v195, 0x3f317217, v148
	v_mov_b32_e32 v148, v195
	v_sub_f32_e32 v148, v194, v148
	v_min_f32_e32 v194, 0, v144
	v_mul_f32_e64 v144, |v144|, s57
	v_exp_f32_e32 v144, v144
	s_nop 0
	v_add_f32_e32 v144, 1.0, v144
	v_log_f32_e32 v144, v144
	s_nop 0
	v_mul_f32_e32 v195, 0x3f317217, v144
	v_fma_f32 v195, v144, s52, -v195
	v_fmac_f32_e32 v195, 0x3377d1cf, v144
	v_fmac_f32_e32 v195, 0x3f317217, v144
	v_mov_b32_e32 v144, v195
	v_sub_f32_e32 v194, v194, v144
	v_mul_f32_e32 v144, 0x3fb8aa3b, v148
	v_exp_f32_e32 v144, v144
	s_nop 0
	v_fma_f32 v144, v190, v144, v140
	v_cmp_gt_f32_e64 s[40:41], s97, v144
	s_nop 1
	v_cndmask_b32_e64 v195, 0, 32, s[40:41]
	v_ldexp_f32 v144, v144, v195
	v_log_f32_e32 v144, v144
	s_nop 0
	v_mul_f32_e32 v195, 0x3f317217, v144
	v_fma_f32 v195, v144, s52, -v195
	v_fmac_f32_e32 v195, 0x3377d1cf, v144
	v_fmac_f32_e32 v195, 0x3f317217, v144
	v_cmp_lt_f32_e64 s[42:43], |v144|, s53
	s_nop 1
	v_cndmask_b32_e64 v144, v144, v195, s[42:43]
	v_cndmask_b32_e64 v195, 0, v216, s[40:41]
	v_sub_f32_e32 v144, v144, v195
	v_cndmask_b32_e64 v144, v148, v144, s[38:39]
	v_mul_f32_e32 v148, 0x3fb8aa3b, v194
	v_exp_f32_e32 v148, v148
	s_nop 0
	v_fma_f32 v148, v191, v148, v136
	v_cmp_gt_f32_e64 s[40:41], s97, v148
	s_nop 1
; __device__ __forceinline__ float silu_f(float x) { return x * __builtin_amdgcn_rcpf(1.f + __expf(-x)); }
; __device__ __forceinline__ v4u pack8(const f32x4 a, const f32x4 b) { v4u w; w.x = cvt_pk_bf16(a[0], a[1]); w.y = cvt_pk_bf16(a[2], a[3]); w.z = cvt_pk_bf16(b[0], b[1]); w.w = cvt_pk_bf16(b[2], b[3]); return w; }
;     __device__ __forceinline__ void operator()(const f32x4 (&acc)[2][2][4][2], const pg8::Unit& u, int wr, int wc, int fr, int fq) const {
;     ...
;         if (grp == 0) { WIN_LOOP( _Pragma("unroll") for (int i = 0; i < 4; ++i) { a[i] = silu_f(a[i]); b[i] = silu_f(b[i]); } *(v4u*)(QO + (size_t)row * DM + c) = pack8(a, b); ) }
;         else if (grp == 3) { WIN_LOOP( _Pragma("unroll") for (int i = 0; i < 4; ++i) { a[i] = silu_f(a[i]); b[i] = silu_f(b[i]); } *(v4u*)(GH + (size_t)row * 512 + c) = pack8(a, b); ) }
;         else if (grp == 1) {
;             f32x4 l0[2], l1[2];
; #pragma unroll
;             for (int bj = 0; bj < 2; ++bj) { l0[bj] = *(const f32x4*)(lb + cb + bj * 128); l1[bj] = *(const f32x4*)(lb + cb + bj * 128 + 4); }
;             WIN_LOOP( _Pragma("unroll") for (int i = 0; i < 4; ++i) { const float s0 = fminf(a[i], 0.f) - __logf(1.f + __expf(-fabsf(a[i]))), s1 = fminf(b[i], 0.f) - __logf(1.f + __expf(-fabsf(b[i]))); const float la = l0[bj][i], lbv = l1[bj][i];
;                     a[i] = la > 0.f ? __logf(la + (1.f - la) * __expf(s0)) : s0; b[i] = lbv > 0.f ? __logf(lbv + (1.f - lbv) * __expf(s1)) : s1; }
;                 *(f32x4*)(LF + (size_t)row * 512 + c) = a; *(f32x4*)(LF + (size_t)row * 512 + c + 4) = b; __builtin_amdgcn_sched_barrier(0); ) }
	v_cndmask_b32_e64 v195, 0, 32, s[40:41]
	v_ldexp_f32 v148, v148, v195
	v_log_f32_e32 v148, v148
	s_nop 0
	v_mul_f32_e32 v195, 0x3f317217, v148
	v_fma_f32 v195, v148, s52, -v195
	v_fmac_f32_e32 v195, 0x3377d1cf, v148
	v_fmac_f32_e32 v195, 0x3f317217, v148
	v_cmp_lt_f32_e64 s[42:43], |v148|, s53
	s_nop 1
	v_cndmask_b32_e64 v148, v148, v195, s[42:43]
	v_cndmask_b32_e64 v195, 0, v216, s[40:41]
	v_sub_f32_e32 v148, v148, v195
	v_cndmask_b32_e64 v148, v194, v148, s[36:37]
	v_min_f32_e32 v194, 0, v149
	v_mul_f32_e64 v149, |v149|, s57
	v_exp_f32_e32 v149, v149
	s_nop 0
	v_add_f32_e32 v149, 1.0, v149
	v_log_f32_e32 v149, v149
	s_nop 0
	v_mul_f32_e32 v195, 0x3f317217, v149
	v_fma_f32 v195, v149, s52, -v195
	v_fmac_f32_e32 v195, 0x3377d1cf, v149
	v_fmac_f32_e32 v195, 0x3f317217, v149
	v_mov_b32_e32 v149, v195
	v_sub_f32_e32 v149, v194, v149
	v_min_f32_e32 v194, 0, v145
	v_mul_f32_e64 v145, |v145|, s57
	v_exp_f32_e32 v145, v145
	s_nop 0
	v_add_f32_e32 v145, 1.0, v145
	v_log_f32_e32 v145, v145
	s_nop 0
	v_mul_f32_e32 v195, 0x3f317217, v145
	v_fma_f32 v195, v145, s52, -v195
	v_fmac_f32_e32 v195, 0x3377d1cf, v145
	v_fmac_f32_e32 v195, 0x3f317217, v145
	v_mov_b32_e32 v145, v195
	v_sub_f32_e32 v194, v194, v145
	v_mul_f32_e32 v145, 0x3fb8aa3b, v149
	v_exp_f32_e32 v145, v145
	s_nop 0
	v_fma_f32 v145, v188, v145, v141
	v_cmp_gt_f32_e64 s[40:41], s97, v145
	s_nop 1
	v_cndmask_b32_e64 v195, 0, 32, s[40:41]
	v_ldexp_f32 v145, v145, v195
	v_log_f32_e32 v145, v145
	s_nop 0
	v_mul_f32_e32 v195, 0x3f317217, v145
	v_fma_f32 v195, v145, s52, -v195
	v_fmac_f32_e32 v195, 0x3377d1cf, v145
	v_fmac_f32_e32 v195, 0x3f317217, v145
	v_cmp_lt_f32_e64 s[42:43], |v145|, s53
	s_nop 1
	v_cndmask_b32_e64 v145, v145, v195, s[42:43]
	v_cndmask_b32_e64 v195, 0, v216, s[40:41]
	v_sub_f32_e32 v145, v145, v195
	v_cndmask_b32_e64 v145, v149, v145, s[34:35]
	v_mul_f32_e32 v149, 0x3fb8aa3b, v194
	v_exp_f32_e32 v149, v149
	s_nop 0
	v_fma_f32 v149, v189, v149, v137
	v_cmp_gt_f32_e64 s[40:41], s97, v149
	s_nop 1
	v_cndmask_b32_e64 v195, 0, 32, s[40:41]
	v_ldexp_f32 v149, v149, v195
	v_log_f32_e32 v149, v149
	s_nop 0
	v_mul_f32_e32 v195, 0x3f317217, v149
	v_fma_f32 v195, v149, s52, -v195
	v_fmac_f32_e32 v195, 0x3377d1cf, v149
	v_fmac_f32_e32 v195, 0x3f317217, v149
	v_cmp_lt_f32_e64 s[42:43], |v149|, s53
	s_nop 1
	v_cndmask_b32_e64 v149, v149, v195, s[42:43]
	v_cndmask_b32_e64 v195, 0, v216, s[40:41]
	v_sub_f32_e32 v149, v149, v195
	v_cndmask_b32_e64 v149, v194, v149, s[30:31]
	v_min_f32_e32 v194, 0, v150
	v_mul_f32_e64 v150, |v150|, s57
	v_exp_f32_e32 v150, v150
	s_nop 0
	v_add_f32_e32 v150, 1.0, v150
	v_log_f32_e32 v150, v150
	s_nop 0
	v_mul_f32_e32 v195, 0x3f317217, v150
	v_fma_f32 v195, v150, s52, -v195
	v_fmac_f32_e32 v195, 0x3377d1cf, v150
	v_fmac_f32_e32 v195, 0x3f317217, v150
	v_mov_b32_e32 v150, v195
	v_sub_f32_e32 v150, v194, v150
	v_min_f32_e32 v194, 0, v146
	v_mul_f32_e64 v146, |v146|, s57
	v_exp_f32_e32 v146, v146
	s_nop 0
	v_add_f32_e32 v146, 1.0, v146
	v_log_f32_e32 v146, v146
	s_nop 0
	v_mul_f32_e32 v195, 0x3f317217, v146
	v_fma_f32 v195, v146, s52, -v195
	v_fmac_f32_e32 v195, 0x3377d1cf, v146
	v_fmac_f32_e32 v195, 0x3f317217, v146
	v_mov_b32_e32 v146, v195
	v_sub_f32_e32 v194, v194, v146
	v_mul_f32_e32 v146, 0x3fb8aa3b, v150
	v_exp_f32_e32 v146, v146
	s_nop 0
	v_fma_f32 v146, v187, v146, v142
	v_cmp_gt_f32_e64 s[40:41], s97, v146
	s_nop 1
	v_cndmask_b32_e64 v195, 0, 32, s[40:41]
	v_ldexp_f32 v146, v146, v195
	v_log_f32_e32 v146, v146
	s_nop 0
	v_mul_f32_e32 v195, 0x3f317217, v146
	v_fma_f32 v195, v146, s52, -v195
	v_fmac_f32_e32 v195, 0x3377d1cf, v146
	v_fmac_f32_e32 v195, 0x3f317217, v146
	v_cmp_lt_f32_e64 s[42:43], |v146|, s53
	s_nop 1
	v_cndmask_b32_e64 v146, v146, v195, s[42:43]
	v_cndmask_b32_e64 v195, 0, v216, s[40:41]
	v_sub_f32_e32 v146, v146, v195
	v_cndmask_b32_e64 v146, v150, v146, s[28:29]
	v_mul_f32_e32 v150, 0x3fb8aa3b, v194
	v_exp_f32_e32 v150, v150
	s_nop 0
	v_fma_f32 v150, v186, v150, v138
	v_cmp_gt_f32_e64 s[40:41], s97, v150
	s_nop 1
	v_cndmask_b32_e64 v195, 0, 32, s[40:41]
	v_ldexp_f32 v150, v150, v195
	v_log_f32_e32 v150, v150
	s_nop 0
	v_mul_f32_e32 v195, 0x3f317217, v150
	v_fma_f32 v195, v150, s52, -v195
	v_fmac_f32_e32 v195, 0x3377d1cf, v150
	v_fmac_f32_e32 v195, 0x3f317217, v150
	v_cmp_lt_f32_e64 s[42:43], |v150|, s53
	s_nop 1
	v_cndmask_b32_e64 v150, v150, v195, s[42:43]
	v_cndmask_b32_e64 v195, 0, v216, s[40:41]
	v_sub_f32_e32 v150, v150, v195
	v_cndmask_b32_e64 v150, v194, v150, s[26:27]
	v_min_f32_e32 v194, 0, v151
	v_mul_f32_e64 v151, |v151|, s57
	v_exp_f32_e32 v151, v151
	s_nop 0
	v_add_f32_e32 v151, 1.0, v151
	v_log_f32_e32 v151, v151
	s_nop 0
	v_mul_f32_e32 v195, 0x3f317217, v151
	v_fma_f32 v195, v151, s52, -v195
	v_fmac_f32_e32 v195, 0x3377d1cf, v151
	v_fmac_f32_e32 v195, 0x3f317217, v151
	v_mov_b32_e32 v151, v195
	v_sub_f32_e32 v151, v194, v151
	v_min_f32_e32 v194, 0, v147
	v_mul_f32_e64 v147, |v147|, s57
	v_exp_f32_e32 v147, v147
	s_nop 0
	v_add_f32_e32 v147, 1.0, v147
	v_log_f32_e32 v147, v147
	s_nop 0
	v_mul_f32_e32 v195, 0x3f317217, v147
	v_fma_f32 v195, v147, s52, -v195
	v_fmac_f32_e32 v195, 0x3377d1cf, v147
	v_fmac_f32_e32 v195, 0x3f317217, v147
	v_mov_b32_e32 v147, v195
	v_sub_f32_e32 v194, v194, v147
	v_mul_f32_e32 v147, 0x3fb8aa3b, v151
	v_exp_f32_e32 v147, v147
	s_nop 0
	v_fma_f32 v147, v185, v147, v143
	v_cmp_gt_f32_e64 s[40:41], s97, v147
	s_nop 1
	v_cndmask_b32_e64 v195, 0, 32, s[40:41]
	v_ldexp_f32 v147, v147, v195
	v_log_f32_e32 v147, v147
	s_nop 0
	v_mul_f32_e32 v195, 0x3f317217, v147
	v_fma_f32 v195, v147, s52, -v195
	v_fmac_f32_e32 v195, 0x3377d1cf, v147
	v_fmac_f32_e32 v195, 0x3f317217, v147
	v_cmp_lt_f32_e64 s[42:43], |v147|, s53
; __device__ __forceinline__ float silu_f(float x) { return x * __builtin_amdgcn_rcpf(1.f + __expf(-x)); }
; __device__ __forceinline__ v4u pack8(const f32x4 a, const f32x4 b) { v4u w; w.x = cvt_pk_bf16(a[0], a[1]); w.y = cvt_pk_bf16(a[2], a[3]); w.z = cvt_pk_bf16(b[0], b[1]); w.w = cvt_pk_bf16(b[2], b[3]); return w; }
;     __device__ __forceinline__ void operator()(const f32x4 (&acc)[2][2][4][2], const pg8::Unit& u, int wr, int wc, int fr, int fq) const {
;     ...
;         if (grp == 0) { WIN_LOOP( _Pragma("unroll") for (int i = 0; i < 4; ++i) { a[i] = silu_f(a[i]); b[i] = silu_f(b[i]); } *(v4u*)(QO + (size_t)row * DM + c) = pack8(a, b); ) }
;         else if (grp == 3) { WIN_LOOP( _Pragma("unroll") for (int i = 0; i < 4; ++i) { a[i] = silu_f(a[i]); b[i] = silu_f(b[i]); } *(v4u*)(GH + (size_t)row * 512 + c) = pack8(a, b); ) }
;         else if (grp == 1) {
;             f32x4 l0[2], l1[2];
; #pragma unroll
;             for (int bj = 0; bj < 2; ++bj) { l0[bj] = *(const f32x4*)(lb + cb + bj * 128); l1[bj] = *(const f32x4*)(lb + cb + bj * 128 + 4); }
;             WIN_LOOP( _Pragma("unroll") for (int i = 0; i < 4; ++i) { const float s0 = fminf(a[i], 0.f) - __logf(1.f + __expf(-fabsf(a[i]))), s1 = fminf(b[i], 0.f) - __logf(1.f + __expf(-fabsf(b[i]))); const float la = l0[bj][i], lbv = l1[bj][i];
;                     a[i] = la > 0.f ? __logf(la + (1.f - la) * __expf(s0)) : s0; b[i] = lbv > 0.f ? __logf(lbv + (1.f - lbv) * __expf(s1)) : s1; }
;                 *(f32x4*)(LF + (size_t)row * 512 + c) = a; *(f32x4*)(LF + (size_t)row * 512 + c + 4) = b; __builtin_amdgcn_sched_barrier(0); ) }
	s_nop 1
	v_cndmask_b32_e64 v147, v147, v195, s[42:43]
	v_cndmask_b32_e64 v195, 0, v216, s[40:41]
	v_sub_f32_e32 v147, v147, v195
	v_cndmask_b32_e64 v147, v151, v147, s[24:25]
	v_mul_f32_e32 v151, 0x3fb8aa3b, v194
	v_exp_f32_e32 v151, v151
	s_nop 0
	v_fma_f32 v151, v184, v151, v139
	v_cmp_gt_f32_e64 s[40:41], s97, v151
	s_nop 1
	v_cndmask_b32_e64 v195, 0, 32, s[40:41]
	v_ldexp_f32 v151, v151, v195
	v_log_f32_e32 v151, v151
	s_nop 0
	v_mul_f32_e32 v195, 0x3f317217, v151
	v_fma_f32 v195, v151, s52, -v195
	v_fmac_f32_e32 v195, 0x3377d1cf, v151
	v_fmac_f32_e32 v195, 0x3f317217, v151
	v_cmp_lt_f32_e64 s[42:43], |v151|, s53
	s_nop 1
	v_cndmask_b32_e64 v151, v151, v195, s[42:43]
	v_cndmask_b32_e64 v195, 0, v216, s[40:41]
	v_sub_f32_e32 v151, v151, v195
	v_cndmask_b32_e64 v151, v194, v151, s[22:23]
	global_store_dwordx4 v[170:171], v[144:147], off
	global_store_dwordx4 v[170:171], v[148:151], off offset:16
	s_nop 1
	v_pk_mul_f32 v[148:149], v[84:85], v[168:169] op_sel_hi:[1,0]
	v_pk_mul_f32 v[150:151], v[86:87], v[168:169] op_sel_hi:[1,0]
	v_pk_mul_f32 v[146:147], v[82:83], v[168:169] op_sel_hi:[1,0]
	v_pk_mul_f32 v[144:145], v[80:81], v[168:169] op_sel_hi:[1,0]
	v_min_f32_e32 v168, 0, v148
	v_mul_f32_e64 v148, |v148|, s57
	v_exp_f32_e32 v148, v148
	s_nop 0
	v_add_f32_e32 v148, 1.0, v148
	v_log_f32_e32 v148, v148
	s_nop 0
	v_mul_f32_e32 v194, 0x3f317217, v148
	v_fma_f32 v194, v148, s52, -v194
	v_fmac_f32_e32 v194, 0x3377d1cf, v148
	v_fmac_f32_e32 v194, 0x3f317217, v148
	v_mov_b32_e32 v148, v194
	v_sub_f32_e32 v148, v168, v148
	v_min_f32_e32 v168, 0, v144
	v_mul_f32_e64 v144, |v144|, s57
	v_exp_f32_e32 v144, v144
	s_nop 0
	v_add_f32_e32 v144, 1.0, v144
	v_log_f32_e32 v144, v144
	s_nop 0
	v_mul_f32_e32 v194, 0x3f317217, v144
	v_fma_f32 v194, v144, s52, -v194
	v_fmac_f32_e32 v194, 0x3377d1cf, v144
	v_fmac_f32_e32 v194, 0x3f317217, v144
	v_mov_b32_e32 v144, v194
	v_sub_f32_e32 v168, v168, v144
	v_mul_f32_e32 v144, 0x3fb8aa3b, v148
	v_exp_f32_e32 v144, v144
	s_nop 0
	v_fma_f32 v144, v183, v144, v132
	v_cmp_gt_f32_e64 s[40:41], s97, v144
	s_nop 1
	v_cndmask_b32_e64 v194, 0, 32, s[40:41]
	v_ldexp_f32 v144, v144, v194
	v_log_f32_e32 v144, v144
	s_nop 0
	v_mul_f32_e32 v194, 0x3f317217, v144
	v_fma_f32 v194, v144, s52, -v194
	v_fmac_f32_e32 v194, 0x3377d1cf, v144
	v_fmac_f32_e32 v194, 0x3f317217, v144
	v_cmp_lt_f32_e64 s[42:43], |v144|, s53
	s_nop 1
	v_cndmask_b32_e64 v144, v144, v194, s[42:43]
	v_cndmask_b32_e64 v194, 0, v216, s[40:41]
	v_sub_f32_e32 v144, v144, v194
	v_cndmask_b32_e64 v144, v148, v144, s[20:21]
	v_mul_f32_e32 v148, 0x3fb8aa3b, v168
	v_exp_f32_e32 v148, v148
	s_nop 0
	v_fma_f32 v148, v182, v148, v128
	v_cmp_gt_f32_e64 s[40:41], s97, v148
	s_nop 1
	v_cndmask_b32_e64 v194, 0, 32, s[40:41]
	v_ldexp_f32 v148, v148, v194
	v_log_f32_e32 v148, v148
	s_nop 0
	v_mul_f32_e32 v194, 0x3f317217, v148
	v_fma_f32 v194, v148, s52, -v194
	v_fmac_f32_e32 v194, 0x3377d1cf, v148
	v_fmac_f32_e32 v194, 0x3f317217, v148
	v_cmp_lt_f32_e64 s[42:43], |v148|, s53
	s_nop 1
	v_cndmask_b32_e64 v148, v148, v194, s[42:43]
	v_cndmask_b32_e64 v194, 0, v216, s[40:41]
	v_sub_f32_e32 v148, v148, v194
	v_cndmask_b32_e64 v148, v168, v148, s[18:19]
	v_min_f32_e32 v168, 0, v149
	v_mul_f32_e64 v149, |v149|, s57
	v_exp_f32_e32 v149, v149
	s_nop 0
	v_add_f32_e32 v149, 1.0, v149
	v_log_f32_e32 v149, v149
	s_nop 0
	v_mul_f32_e32 v194, 0x3f317217, v149
	v_fma_f32 v194, v149, s52, -v194
	v_fmac_f32_e32 v194, 0x3377d1cf, v149
	v_fmac_f32_e32 v194, 0x3f317217, v149
	v_mov_b32_e32 v149, v194
	v_sub_f32_e32 v149, v168, v149
	v_min_f32_e32 v168, 0, v145
	v_mul_f32_e64 v145, |v145|, s57
	v_exp_f32_e32 v145, v145
	s_nop 0
	v_add_f32_e32 v145, 1.0, v145
	v_log_f32_e32 v145, v145
	s_nop 0
	v_mul_f32_e32 v194, 0x3f317217, v145
	v_fma_f32 v194, v145, s52, -v194
	v_fmac_f32_e32 v194, 0x3377d1cf, v145
	v_fmac_f32_e32 v194, 0x3f317217, v145
	v_mov_b32_e32 v145, v194
	v_sub_f32_e32 v168, v168, v145
	v_mul_f32_e32 v145, 0x3fb8aa3b, v149
	v_exp_f32_e32 v145, v145
	s_nop 0
	v_fma_f32 v145, v181, v145, v133
	v_cmp_gt_f32_e64 s[40:41], s97, v145
	s_nop 1
	v_cndmask_b32_e64 v194, 0, 32, s[40:41]
	v_ldexp_f32 v145, v145, v194
	v_log_f32_e32 v145, v145
	s_nop 0
	v_mul_f32_e32 v194, 0x3f317217, v145
	v_fma_f32 v194, v145, s52, -v194
	v_fmac_f32_e32 v194, 0x3377d1cf, v145
	v_fmac_f32_e32 v194, 0x3f317217, v145
	v_cmp_lt_f32_e64 s[42:43], |v145|, s53
	s_nop 1
	v_cndmask_b32_e64 v145, v145, v194, s[42:43]
	v_cndmask_b32_e64 v194, 0, v216, s[40:41]
	v_sub_f32_e32 v145, v145, v194
	v_cndmask_b32_e64 v145, v149, v145, s[16:17]
	v_mul_f32_e32 v149, 0x3fb8aa3b, v168
	v_exp_f32_e32 v149, v149
	s_nop 0
	v_fma_f32 v149, v180, v149, v129
	v_cmp_gt_f32_e64 s[40:41], s97, v149
	s_nop 1
	v_cndmask_b32_e64 v194, 0, 32, s[40:41]
	v_ldexp_f32 v149, v149, v194
	v_log_f32_e32 v149, v149
	s_nop 0
	v_mul_f32_e32 v194, 0x3f317217, v149
	v_fma_f32 v194, v149, s52, -v194
	v_fmac_f32_e32 v194, 0x3377d1cf, v149
	v_fmac_f32_e32 v194, 0x3f317217, v149
	v_cmp_lt_f32_e64 s[42:43], |v149|, s53
	s_nop 1
	v_cndmask_b32_e64 v149, v149, v194, s[42:43]
	v_cndmask_b32_e64 v194, 0, v216, s[40:41]
	v_sub_f32_e32 v149, v149, v194
	v_cndmask_b32_e64 v149, v168, v149, s[14:15]
	v_min_f32_e32 v168, 0, v150
	v_mul_f32_e64 v150, |v150|, s57
	v_exp_f32_e32 v150, v150
	s_nop 0
	v_add_f32_e32 v150, 1.0, v150
	v_log_f32_e32 v150, v150
	s_nop 0
	v_mul_f32_e32 v194, 0x3f317217, v150
	v_fma_f32 v194, v150, s52, -v194
	v_fmac_f32_e32 v194, 0x3377d1cf, v150
	v_fmac_f32_e32 v194, 0x3f317217, v150
	v_mov_b32_e32 v150, v194
	v_sub_f32_e32 v150, v168, v150
	v_min_f32_e32 v168, 0, v146
	v_mul_f32_e64 v146, |v146|, s57
	v_exp_f32_e32 v146, v146
	s_nop 0
; __device__ __forceinline__ float silu_f(float x) { return x * __builtin_amdgcn_rcpf(1.f + __expf(-x)); }
; __device__ __forceinline__ v4u pack8(const f32x4 a, const f32x4 b) { v4u w; w.x = cvt_pk_bf16(a[0], a[1]); w.y = cvt_pk_bf16(a[2], a[3]); w.z = cvt_pk_bf16(b[0], b[1]); w.w = cvt_pk_bf16(b[2], b[3]); return w; }
;     __device__ __forceinline__ void operator()(const f32x4 (&acc)[2][2][4][2], const pg8::Unit& u, int wr, int wc, int fr, int fq) const {
;     ...
;         if (grp == 0) { WIN_LOOP( _Pragma("unroll") for (int i = 0; i < 4; ++i) { a[i] = silu_f(a[i]); b[i] = silu_f(b[i]); } *(v4u*)(QO + (size_t)row * DM + c) = pack8(a, b); ) }
;         else if (grp == 3) { WIN_LOOP( _Pragma("unroll") for (int i = 0; i < 4; ++i) { a[i] = silu_f(a[i]); b[i] = silu_f(b[i]); } *(v4u*)(GH + (size_t)row * 512 + c) = pack8(a, b); ) }
;         else if (grp == 1) {
;             f32x4 l0[2], l1[2];
; #pragma unroll
;             for (int bj = 0; bj < 2; ++bj) { l0[bj] = *(const f32x4*)(lb + cb + bj * 128); l1[bj] = *(const f32x4*)(lb + cb + bj * 128 + 4); }
;             WIN_LOOP( _Pragma("unroll") for (int i = 0; i < 4; ++i) { const float s0 = fminf(a[i], 0.f) - __logf(1.f + __expf(-fabsf(a[i]))), s1 = fminf(b[i], 0.f) - __logf(1.f + __expf(-fabsf(b[i]))); const float la = l0[bj][i], lbv = l1[bj][i];
;                     a[i] = la > 0.f ? __logf(la + (1.f - la) * __expf(s0)) : s0; b[i] = lbv > 0.f ? __logf(lbv + (1.f - lbv) * __expf(s1)) : s1; }
;                 *(f32x4*)(LF + (size_t)row * 512 + c) = a; *(f32x4*)(LF + (size_t)row * 512 + c + 4) = b; __builtin_amdgcn_sched_barrier(0); ) }
	v_add_f32_e32 v146, 1.0, v146
	v_log_f32_e32 v146, v146
	s_nop 0
	v_mul_f32_e32 v194, 0x3f317217, v146
	v_fma_f32 v194, v146, s52, -v194
	v_fmac_f32_e32 v194, 0x3377d1cf, v146
	v_fmac_f32_e32 v194, 0x3f317217, v146
	v_mov_b32_e32 v146, v194
	v_sub_f32_e32 v168, v168, v146
	v_mul_f32_e32 v146, 0x3fb8aa3b, v150
	v_exp_f32_e32 v146, v146
	s_nop 0
	v_fma_f32 v146, v179, v146, v134
	v_cmp_gt_f32_e64 s[40:41], s97, v146
	s_nop 1
	v_cndmask_b32_e64 v194, 0, 32, s[40:41]
	v_ldexp_f32 v146, v146, v194
	v_log_f32_e32 v146, v146
	s_nop 0
	v_mul_f32_e32 v194, 0x3f317217, v146
	v_fma_f32 v194, v146, s52, -v194
	v_fmac_f32_e32 v194, 0x3377d1cf, v146
	v_fmac_f32_e32 v194, 0x3f317217, v146
	v_cmp_lt_f32_e64 s[42:43], |v146|, s53
	s_nop 1
	v_cndmask_b32_e64 v146, v146, v194, s[42:43]
	v_cndmask_b32_e64 v194, 0, v216, s[40:41]
	v_sub_f32_e32 v146, v146, v194
	v_cndmask_b32_e64 v146, v150, v146, s[12:13]
	v_mul_f32_e32 v150, 0x3fb8aa3b, v168
	v_exp_f32_e32 v150, v150
	s_nop 0
	v_fma_f32 v150, v178, v150, v130
	v_cmp_gt_f32_e64 s[40:41], s97, v150
	s_nop 1
	v_cndmask_b32_e64 v194, 0, 32, s[40:41]
	v_ldexp_f32 v150, v150, v194
	v_log_f32_e32 v150, v150
	s_nop 0
	v_mul_f32_e32 v194, 0x3f317217, v150
	v_fma_f32 v194, v150, s52, -v194
	v_fmac_f32_e32 v194, 0x3377d1cf, v150
	v_fmac_f32_e32 v194, 0x3f317217, v150
	v_cmp_lt_f32_e64 s[42:43], |v150|, s53
	s_nop 1
	v_cndmask_b32_e64 v150, v150, v194, s[42:43]
	v_cndmask_b32_e64 v194, 0, v216, s[40:41]
	v_sub_f32_e32 v150, v150, v194
	v_cndmask_b32_e64 v150, v168, v150, s[10:11]
	v_min_f32_e32 v168, 0, v151
	v_mul_f32_e64 v151, |v151|, s57
	v_exp_f32_e32 v151, v151
	s_nop 0
	v_add_f32_e32 v151, 1.0, v151
	v_log_f32_e32 v151, v151
	s_nop 0
	v_mul_f32_e32 v194, 0x3f317217, v151
	v_fma_f32 v194, v151, s52, -v194
	v_fmac_f32_e32 v194, 0x3377d1cf, v151
	v_fmac_f32_e32 v194, 0x3f317217, v151
	v_mov_b32_e32 v151, v194
	v_sub_f32_e32 v151, v168, v151
	v_min_f32_e32 v168, 0, v147
	v_mul_f32_e64 v147, |v147|, s57
	v_exp_f32_e32 v147, v147
	s_nop 0
	v_add_f32_e32 v147, 1.0, v147
	v_log_f32_e32 v147, v147
	s_nop 0
	v_mul_f32_e32 v194, 0x3f317217, v147
	v_fma_f32 v194, v147, s52, -v194
	v_fmac_f32_e32 v194, 0x3377d1cf, v147
	v_fmac_f32_e32 v194, 0x3f317217, v147
	v_mov_b32_e32 v147, v194
	v_sub_f32_e32 v168, v168, v147
	v_mul_f32_e32 v147, 0x3fb8aa3b, v151
	v_exp_f32_e32 v147, v147
	s_nop 0
	v_fma_f32 v147, v177, v147, v135
	v_cmp_gt_f32_e64 s[40:41], s97, v147
	s_nop 1
	v_cndmask_b32_e64 v194, 0, 32, s[40:41]
	v_ldexp_f32 v147, v147, v194
	v_log_f32_e32 v147, v147
	s_nop 0
	v_mul_f32_e32 v194, 0x3f317217, v147
	v_fma_f32 v194, v147, s52, -v194
	v_fmac_f32_e32 v194, 0x3377d1cf, v147
	v_fmac_f32_e32 v194, 0x3f317217, v147
	v_cmp_lt_f32_e64 s[42:43], |v147|, s53
	s_nop 1
	v_cndmask_b32_e64 v147, v147, v194, s[42:43]
	v_cndmask_b32_e64 v194, 0, v216, s[40:41]
	v_sub_f32_e32 v147, v147, v194
	v_cndmask_b32_e64 v147, v151, v147, s[8:9]
	v_mul_f32_e32 v151, 0x3fb8aa3b, v168
	v_exp_f32_e32 v151, v151
	s_nop 0
	v_fma_f32 v151, v167, v151, v131
	v_cmp_gt_f32_e64 s[40:41], s97, v151
	s_nop 1
	v_cndmask_b32_e64 v194, 0, 32, s[40:41]
	v_ldexp_f32 v151, v151, v194
	v_log_f32_e32 v151, v151
	s_nop 0
	v_mul_f32_e32 v194, 0x3f317217, v151
	v_fma_f32 v194, v151, s52, -v194
	v_fmac_f32_e32 v194, 0x3377d1cf, v151
	v_fmac_f32_e32 v194, 0x3f317217, v151
	v_cmp_lt_f32_e64 s[42:43], |v151|, s53
	s_nop 1
	v_cndmask_b32_e64 v151, v151, v194, s[42:43]
	v_cndmask_b32_e64 v194, 0, v216, s[40:41]
	v_sub_f32_e32 v151, v151, v194
	v_cndmask_b32_e32 v151, v168, v151, vcc
	global_store_dwordx4 v[170:171], v[144:147], off offset:512
	global_store_dwordx4 v[170:171], v[148:151], off offset:528
	s_nop 1
	v_add_u32_e32 v148, 0xa0, v166
	v_ashrrev_i32_e32 v149, 31, v148
	v_lshlrev_b64 v[144:145], 6, v[148:149]
	v_lshl_add_u64 v[144:145], v[160:161], 0, v[144:145]
	s_nop 0
	s_waitcnt lgkmcnt(0)
	s_nop 3
	s_nop 0
	s_nop 1
	s_waitcnt lgkmcnt(0)
	s_nop 1
	s_waitcnt lgkmcnt(0)
	s_nop 1
	v_mov_b32_e32 v168, v241
	v_lshlrev_b64 v[144:145], 11, v[148:149]
	v_lshl_add_u64 v[170:171], s[50:51], 0, v[144:145]
	v_lshl_add_u64 v[170:171], v[170:171], 0, v[192:193]
	v_pk_mul_f32 v[148:149], v[12:13], v[168:169] op_sel_hi:[1,0]
	v_pk_mul_f32 v[144:145], v[8:9], v[168:169] op_sel_hi:[1,0]
	v_min_f32_e32 v194, 0, v148
	v_mul_f32_e64 v148, |v148|, s57
	v_exp_f32_e32 v148, v148
	v_pk_mul_f32 v[150:151], v[14:15], v[168:169] op_sel_hi:[1,0]
	v_pk_mul_f32 v[146:147], v[10:11], v[168:169] op_sel_hi:[1,0]
	v_add_f32_e32 v148, 1.0, v148
	v_log_f32_e32 v148, v148
	s_nop 0
	v_mul_f32_e32 v195, 0x3f317217, v148
	v_fma_f32 v195, v148, s52, -v195
	v_fmac_f32_e32 v195, 0x3377d1cf, v148
	v_fmac_f32_e32 v195, 0x3f317217, v148
	v_mov_b32_e32 v148, v195
	v_sub_f32_e32 v148, v194, v148
	v_min_f32_e32 v194, 0, v144
	v_mul_f32_e64 v144, |v144|, s57
	v_exp_f32_e32 v144, v144
	s_nop 0
	v_add_f32_e32 v144, 1.0, v144
	v_log_f32_e32 v144, v144
	s_nop 0
	v_mul_f32_e32 v195, 0x3f317217, v144
	v_fma_f32 v195, v144, s52, -v195
	v_fmac_f32_e32 v195, 0x3377d1cf, v144
	v_fmac_f32_e32 v195, 0x3f317217, v144
	v_mov_b32_e32 v144, v195
	v_sub_f32_e32 v194, v194, v144
	v_mul_f32_e32 v144, 0x3fb8aa3b, v148
	v_exp_f32_e32 v144, v144
	s_nop 0
	v_fma_f32 v144, v190, v144, v140
	v_cmp_gt_f32_e64 s[40:41], s97, v144
	s_nop 1
	v_cndmask_b32_e64 v195, 0, 32, s[40:41]
	v_ldexp_f32 v144, v144, v195
	v_log_f32_e32 v144, v144
	s_nop 0
	v_mul_f32_e32 v195, 0x3f317217, v144
	v_fma_f32 v195, v144, s52, -v195
	v_fmac_f32_e32 v195, 0x3377d1cf, v144
	v_fmac_f32_e32 v195, 0x3f317217, v144
	v_cmp_lt_f32_e64 s[42:43], |v144|, s53
	s_nop 1
	v_cndmask_b32_e64 v144, v144, v195, s[42:43]
	v_cndmask_b32_e64 v195, 0, v216, s[40:41]
; __device__ __forceinline__ float silu_f(float x) { return x * __builtin_amdgcn_rcpf(1.f + __expf(-x)); }
; __device__ __forceinline__ v4u pack8(const f32x4 a, const f32x4 b) { v4u w; w.x = cvt_pk_bf16(a[0], a[1]); w.y = cvt_pk_bf16(a[2], a[3]); w.z = cvt_pk_bf16(b[0], b[1]); w.w = cvt_pk_bf16(b[2], b[3]); return w; }
;     __device__ __forceinline__ void operator()(const f32x4 (&acc)[2][2][4][2], const pg8::Unit& u, int wr, int wc, int fr, int fq) const {
;     ...
;         if (grp == 0) { WIN_LOOP( _Pragma("unroll") for (int i = 0; i < 4; ++i) { a[i] = silu_f(a[i]); b[i] = silu_f(b[i]); } *(v4u*)(QO + (size_t)row * DM + c) = pack8(a, b); ) }
;         else if (grp == 3) { WIN_LOOP( _Pragma("unroll") for (int i = 0; i < 4; ++i) { a[i] = silu_f(a[i]); b[i] = silu_f(b[i]); } *(v4u*)(GH + (size_t)row * 512 + c) = pack8(a, b); ) }
;         else if (grp == 1) {
;             f32x4 l0[2], l1[2];
; #pragma unroll
;             for (int bj = 0; bj < 2; ++bj) { l0[bj] = *(const f32x4*)(lb + cb + bj * 128); l1[bj] = *(const f32x4*)(lb + cb + bj * 128 + 4); }
;             WIN_LOOP( _Pragma("unroll") for (int i = 0; i < 4; ++i) { const float s0 = fminf(a[i], 0.f) - __logf(1.f + __expf(-fabsf(a[i]))), s1 = fminf(b[i], 0.f) - __logf(1.f + __expf(-fabsf(b[i]))); const float la = l0[bj][i], lbv = l1[bj][i];
;                     a[i] = la > 0.f ? __logf(la + (1.f - la) * __expf(s0)) : s0; b[i] = lbv > 0.f ? __logf(lbv + (1.f - lbv) * __expf(s1)) : s1; }
;                 *(f32x4*)(LF + (size_t)row * 512 + c) = a; *(f32x4*)(LF + (size_t)row * 512 + c + 4) = b; __builtin_amdgcn_sched_barrier(0); ) }
	v_sub_f32_e32 v144, v144, v195
	v_cndmask_b32_e64 v144, v148, v144, s[38:39]
	v_mul_f32_e32 v148, 0x3fb8aa3b, v194
	v_exp_f32_e32 v148, v148
	s_nop 0
	v_fma_f32 v148, v191, v148, v136
	v_cmp_gt_f32_e64 s[40:41], s97, v148
	s_nop 1
	v_cndmask_b32_e64 v195, 0, 32, s[40:41]
	v_ldexp_f32 v148, v148, v195
	v_log_f32_e32 v148, v148
	s_nop 0
	v_mul_f32_e32 v195, 0x3f317217, v148
	v_fma_f32 v195, v148, s52, -v195
	v_fmac_f32_e32 v195, 0x3377d1cf, v148
	v_fmac_f32_e32 v195, 0x3f317217, v148
	v_cmp_lt_f32_e64 s[42:43], |v148|, s53
	s_nop 1
	v_cndmask_b32_e64 v148, v148, v195, s[42:43]
	v_cndmask_b32_e64 v195, 0, v216, s[40:41]
	v_sub_f32_e32 v148, v148, v195
	v_cndmask_b32_e64 v148, v194, v148, s[36:37]
	v_min_f32_e32 v194, 0, v149
	v_mul_f32_e64 v149, |v149|, s57
	v_exp_f32_e32 v149, v149
	s_nop 0
	v_add_f32_e32 v149, 1.0, v149
	v_log_f32_e32 v149, v149
	s_nop 0
	v_mul_f32_e32 v195, 0x3f317217, v149
	v_fma_f32 v195, v149, s52, -v195
	v_fmac_f32_e32 v195, 0x3377d1cf, v149
	v_fmac_f32_e32 v195, 0x3f317217, v149
	v_mov_b32_e32 v149, v195
	v_sub_f32_e32 v149, v194, v149
	v_min_f32_e32 v194, 0, v145
	v_mul_f32_e64 v145, |v145|, s57
	v_exp_f32_e32 v145, v145
	s_nop 0
	v_add_f32_e32 v145, 1.0, v145
	v_log_f32_e32 v145, v145
	s_nop 0
	v_mul_f32_e32 v195, 0x3f317217, v145
	v_fma_f32 v195, v145, s52, -v195
	v_fmac_f32_e32 v195, 0x3377d1cf, v145
	v_fmac_f32_e32 v195, 0x3f317217, v145
	v_mov_b32_e32 v145, v195
	v_sub_f32_e32 v194, v194, v145
	v_mul_f32_e32 v145, 0x3fb8aa3b, v149
	v_exp_f32_e32 v145, v145
	s_nop 0
	v_fma_f32 v145, v188, v145, v141
	v_cmp_gt_f32_e64 s[40:41], s97, v145
	s_nop 1
	v_cndmask_b32_e64 v195, 0, 32, s[40:41]
	v_ldexp_f32 v145, v145, v195
	v_log_f32_e32 v145, v145
	s_nop 0
	v_mul_f32_e32 v195, 0x3f317217, v145
	v_fma_f32 v195, v145, s52, -v195
	v_fmac_f32_e32 v195, 0x3377d1cf, v145
	v_fmac_f32_e32 v195, 0x3f317217, v145
	v_cmp_lt_f32_e64 s[42:43], |v145|, s53
	s_nop 1
	v_cndmask_b32_e64 v145, v145, v195, s[42:43]
	v_cndmask_b32_e64 v195, 0, v216, s[40:41]
	v_sub_f32_e32 v145, v145, v195
	v_cndmask_b32_e64 v145, v149, v145, s[34:35]
	v_mul_f32_e32 v149, 0x3fb8aa3b, v194
	v_exp_f32_e32 v149, v149
	s_nop 0
	v_fma_f32 v149, v189, v149, v137
	v_cmp_gt_f32_e64 s[40:41], s97, v149
	s_nop 1
	v_cndmask_b32_e64 v195, 0, 32, s[40:41]
	v_ldexp_f32 v149, v149, v195
	v_log_f32_e32 v149, v149
	s_nop 0
	v_mul_f32_e32 v195, 0x3f317217, v149
	v_fma_f32 v195, v149, s52, -v195
	v_fmac_f32_e32 v195, 0x3377d1cf, v149
	v_fmac_f32_e32 v195, 0x3f317217, v149
	v_cmp_lt_f32_e64 s[42:43], |v149|, s53
	s_nop 1
	v_cndmask_b32_e64 v149, v149, v195, s[42:43]
	v_cndmask_b32_e64 v195, 0, v216, s[40:41]
	v_sub_f32_e32 v149, v149, v195
	v_cndmask_b32_e64 v149, v194, v149, s[30:31]
	v_min_f32_e32 v194, 0, v150
	v_mul_f32_e64 v150, |v150|, s57
	v_exp_f32_e32 v150, v150
	s_nop 0
	v_add_f32_e32 v150, 1.0, v150
	v_log_f32_e32 v150, v150
	s_nop 0
	v_mul_f32_e32 v195, 0x3f317217, v150
	v_fma_f32 v195, v150, s52, -v195
	v_fmac_f32_e32 v195, 0x3377d1cf, v150
	v_fmac_f32_e32 v195, 0x3f317217, v150
	v_mov_b32_e32 v150, v195
	v_sub_f32_e32 v150, v194, v150
	v_min_f32_e32 v194, 0, v146
	v_mul_f32_e64 v146, |v146|, s57
	v_exp_f32_e32 v146, v146
	s_nop 0
	v_add_f32_e32 v146, 1.0, v146
	v_log_f32_e32 v146, v146
	s_nop 0
	v_mul_f32_e32 v195, 0x3f317217, v146
	v_fma_f32 v195, v146, s52, -v195
	v_fmac_f32_e32 v195, 0x3377d1cf, v146
	v_fmac_f32_e32 v195, 0x3f317217, v146
	v_mov_b32_e32 v146, v195
	v_sub_f32_e32 v194, v194, v146
	v_mul_f32_e32 v146, 0x3fb8aa3b, v150
	v_exp_f32_e32 v146, v146
	s_nop 0
	v_fma_f32 v146, v187, v146, v142
	v_cmp_gt_f32_e64 s[40:41], s97, v146
	s_nop 1
	v_cndmask_b32_e64 v195, 0, 32, s[40:41]
	v_ldexp_f32 v146, v146, v195
	v_log_f32_e32 v146, v146
	s_nop 0
	v_mul_f32_e32 v195, 0x3f317217, v146
	v_fma_f32 v195, v146, s52, -v195
	v_fmac_f32_e32 v195, 0x3377d1cf, v146
	v_fmac_f32_e32 v195, 0x3f317217, v146
	v_cmp_lt_f32_e64 s[42:43], |v146|, s53
	s_nop 1
	v_cndmask_b32_e64 v146, v146, v195, s[42:43]
	v_cndmask_b32_e64 v195, 0, v216, s[40:41]
	v_sub_f32_e32 v146, v146, v195
	v_cndmask_b32_e64 v146, v150, v146, s[28:29]
	v_mul_f32_e32 v150, 0x3fb8aa3b, v194
	v_exp_f32_e32 v150, v150
	s_nop 0
	v_fma_f32 v150, v186, v150, v138
	v_cmp_gt_f32_e64 s[40:41], s97, v150
	s_nop 1
	v_cndmask_b32_e64 v195, 0, 32, s[40:41]
	v_ldexp_f32 v150, v150, v195
	v_log_f32_e32 v150, v150
	s_nop 0
	v_mul_f32_e32 v195, 0x3f317217, v150
	v_fma_f32 v195, v150, s52, -v195
	v_fmac_f32_e32 v195, 0x3377d1cf, v150
	v_fmac_f32_e32 v195, 0x3f317217, v150
	v_cmp_lt_f32_e64 s[42:43], |v150|, s53
	s_nop 1
	v_cndmask_b32_e64 v150, v150, v195, s[42:43]
	v_cndmask_b32_e64 v195, 0, v216, s[40:41]
	v_sub_f32_e32 v150, v150, v195
	v_cndmask_b32_e64 v150, v194, v150, s[26:27]
	v_min_f32_e32 v194, 0, v151
	v_mul_f32_e64 v151, |v151|, s57
	v_exp_f32_e32 v151, v151
	s_nop 0
	v_add_f32_e32 v151, 1.0, v151
	v_log_f32_e32 v151, v151
	s_nop 0
	v_mul_f32_e32 v195, 0x3f317217, v151
	v_fma_f32 v195, v151, s52, -v195
	v_fmac_f32_e32 v195, 0x3377d1cf, v151
	v_fmac_f32_e32 v195, 0x3f317217, v151
	v_mov_b32_e32 v151, v195
	v_sub_f32_e32 v151, v194, v151
	v_min_f32_e32 v194, 0, v147
	v_mul_f32_e64 v147, |v147|, s57
	v_exp_f32_e32 v147, v147
	s_nop 0
	v_add_f32_e32 v147, 1.0, v147
	v_log_f32_e32 v147, v147
	s_nop 0
	v_mul_f32_e32 v195, 0x3f317217, v147
	v_fma_f32 v195, v147, s52, -v195
	v_fmac_f32_e32 v195, 0x3377d1cf, v147
	v_fmac_f32_e32 v195, 0x3f317217, v147
	v_mov_b32_e32 v147, v195
	v_sub_f32_e32 v194, v194, v147
	v_mul_f32_e32 v147, 0x3fb8aa3b, v151
	v_exp_f32_e32 v147, v147
	s_nop 0
	v_fma_f32 v147, v185, v147, v143
	v_cmp_gt_f32_e64 s[40:41], s97, v147
	s_nop 1
	v_cndmask_b32_e64 v195, 0, 32, s[40:41]
; __device__ __forceinline__ float silu_f(float x) { return x * __builtin_amdgcn_rcpf(1.f + __expf(-x)); }
; __device__ __forceinline__ v4u pack8(const f32x4 a, const f32x4 b) { v4u w; w.x = cvt_pk_bf16(a[0], a[1]); w.y = cvt_pk_bf16(a[2], a[3]); w.z = cvt_pk_bf16(b[0], b[1]); w.w = cvt_pk_bf16(b[2], b[3]); return w; }
;     __device__ __forceinline__ void operator()(const f32x4 (&acc)[2][2][4][2], const pg8::Unit& u, int wr, int wc, int fr, int fq) const {
;     ...
;         if (grp == 0) { WIN_LOOP( _Pragma("unroll") for (int i = 0; i < 4; ++i) { a[i] = silu_f(a[i]); b[i] = silu_f(b[i]); } *(v4u*)(QO + (size_t)row * DM + c) = pack8(a, b); ) }
;         else if (grp == 3) { WIN_LOOP( _Pragma("unroll") for (int i = 0; i < 4; ++i) { a[i] = silu_f(a[i]); b[i] = silu_f(b[i]); } *(v4u*)(GH + (size_t)row * 512 + c) = pack8(a, b); ) }
;         else if (grp == 1) {
;             f32x4 l0[2], l1[2];
; #pragma unroll
;             for (int bj = 0; bj < 2; ++bj) { l0[bj] = *(const f32x4*)(lb + cb + bj * 128); l1[bj] = *(const f32x4*)(lb + cb + bj * 128 + 4); }
;             WIN_LOOP( _Pragma("unroll") for (int i = 0; i < 4; ++i) { const float s0 = fminf(a[i], 0.f) - __logf(1.f + __expf(-fabsf(a[i]))), s1 = fminf(b[i], 0.f) - __logf(1.f + __expf(-fabsf(b[i]))); const float la = l0[bj][i], lbv = l1[bj][i];
;                     a[i] = la > 0.f ? __logf(la + (1.f - la) * __expf(s0)) : s0; b[i] = lbv > 0.f ? __logf(lbv + (1.f - lbv) * __expf(s1)) : s1; }
;                 *(f32x4*)(LF + (size_t)row * 512 + c) = a; *(f32x4*)(LF + (size_t)row * 512 + c + 4) = b; __builtin_amdgcn_sched_barrier(0); ) }
	v_ldexp_f32 v147, v147, v195
	v_log_f32_e32 v147, v147
	s_nop 0
	v_mul_f32_e32 v195, 0x3f317217, v147
	v_fma_f32 v195, v147, s52, -v195
	v_fmac_f32_e32 v195, 0x3377d1cf, v147
	v_fmac_f32_e32 v195, 0x3f317217, v147
	v_cmp_lt_f32_e64 s[42:43], |v147|, s53
	s_nop 1
	v_cndmask_b32_e64 v147, v147, v195, s[42:43]
	v_cndmask_b32_e64 v195, 0, v216, s[40:41]
	v_sub_f32_e32 v147, v147, v195
	v_cndmask_b32_e64 v147, v151, v147, s[24:25]
	v_mul_f32_e32 v151, 0x3fb8aa3b, v194
	v_exp_f32_e32 v151, v151
	s_nop 0
	v_fma_f32 v151, v184, v151, v139
	v_cmp_gt_f32_e64 s[40:41], s97, v151
	s_nop 1
	v_cndmask_b32_e64 v195, 0, 32, s[40:41]
	v_ldexp_f32 v151, v151, v195
	v_log_f32_e32 v151, v151
	s_nop 0
	v_mul_f32_e32 v195, 0x3f317217, v151
	v_fma_f32 v195, v151, s52, -v195
	v_fmac_f32_e32 v195, 0x3377d1cf, v151
	v_fmac_f32_e32 v195, 0x3f317217, v151
	v_cmp_lt_f32_e64 s[42:43], |v151|, s53
	s_nop 1
	v_cndmask_b32_e64 v151, v151, v195, s[42:43]
	v_cndmask_b32_e64 v195, 0, v216, s[40:41]
	v_sub_f32_e32 v151, v151, v195
	v_cndmask_b32_e64 v151, v194, v151, s[22:23]
	global_store_dwordx4 v[170:171], v[144:147], off
	global_store_dwordx4 v[170:171], v[148:151], off offset:16
	s_nop 1
	v_pk_mul_f32 v[148:149], v[76:77], v[168:169] op_sel_hi:[1,0]
	v_pk_mul_f32 v[150:151], v[78:79], v[168:169] op_sel_hi:[1,0]
	v_pk_mul_f32 v[146:147], v[74:75], v[168:169] op_sel_hi:[1,0]
	v_pk_mul_f32 v[144:145], v[72:73], v[168:169] op_sel_hi:[1,0]
	v_min_f32_e32 v168, 0, v148
	v_mul_f32_e64 v148, |v148|, s57
	v_exp_f32_e32 v148, v148
	s_nop 0
	v_add_f32_e32 v148, 1.0, v148
	v_log_f32_e32 v148, v148
	s_nop 0
	v_mul_f32_e32 v194, 0x3f317217, v148
	v_fma_f32 v194, v148, s52, -v194
	v_fmac_f32_e32 v194, 0x3377d1cf, v148
	v_fmac_f32_e32 v194, 0x3f317217, v148
	v_mov_b32_e32 v148, v194
	v_sub_f32_e32 v148, v168, v148
	v_min_f32_e32 v168, 0, v144
	v_mul_f32_e64 v144, |v144|, s57
	v_exp_f32_e32 v144, v144
	s_nop 0
	v_add_f32_e32 v144, 1.0, v144
	v_log_f32_e32 v144, v144
	s_nop 0
	v_mul_f32_e32 v194, 0x3f317217, v144
	v_fma_f32 v194, v144, s52, -v194
	v_fmac_f32_e32 v194, 0x3377d1cf, v144
	v_fmac_f32_e32 v194, 0x3f317217, v144
	v_mov_b32_e32 v144, v194
	v_sub_f32_e32 v168, v168, v144
	v_mul_f32_e32 v144, 0x3fb8aa3b, v148
	v_exp_f32_e32 v144, v144
	s_nop 0
	v_fma_f32 v144, v183, v144, v132
	v_cmp_gt_f32_e64 s[40:41], s97, v144
	s_nop 1
	v_cndmask_b32_e64 v194, 0, 32, s[40:41]
	v_ldexp_f32 v144, v144, v194
	v_log_f32_e32 v144, v144
	s_nop 0
	v_mul_f32_e32 v194, 0x3f317217, v144
	v_fma_f32 v194, v144, s52, -v194
	v_fmac_f32_e32 v194, 0x3377d1cf, v144
	v_fmac_f32_e32 v194, 0x3f317217, v144
	v_cmp_lt_f32_e64 s[42:43], |v144|, s53
	s_nop 1
	v_cndmask_b32_e64 v144, v144, v194, s[42:43]
	v_cndmask_b32_e64 v194, 0, v216, s[40:41]
	v_sub_f32_e32 v144, v144, v194
	v_cndmask_b32_e64 v144, v148, v144, s[20:21]
	v_mul_f32_e32 v148, 0x3fb8aa3b, v168
	v_exp_f32_e32 v148, v148
	s_nop 0
	v_fma_f32 v148, v182, v148, v128
	v_cmp_gt_f32_e64 s[40:41], s97, v148
	s_nop 1
	v_cndmask_b32_e64 v194, 0, 32, s[40:41]
	v_ldexp_f32 v148, v148, v194
	v_log_f32_e32 v148, v148
	s_nop 0
	v_mul_f32_e32 v194, 0x3f317217, v148
	v_fma_f32 v194, v148, s52, -v194
	v_fmac_f32_e32 v194, 0x3377d1cf, v148
	v_fmac_f32_e32 v194, 0x3f317217, v148
	v_cmp_lt_f32_e64 s[42:43], |v148|, s53
	s_nop 1
	v_cndmask_b32_e64 v148, v148, v194, s[42:43]
	v_cndmask_b32_e64 v194, 0, v216, s[40:41]
	v_sub_f32_e32 v148, v148, v194
	v_cndmask_b32_e64 v148, v168, v148, s[18:19]
	v_min_f32_e32 v168, 0, v149
	v_mul_f32_e64 v149, |v149|, s57
	v_exp_f32_e32 v149, v149
	s_nop 0
	v_add_f32_e32 v149, 1.0, v149
	v_log_f32_e32 v149, v149
	s_nop 0
	v_mul_f32_e32 v194, 0x3f317217, v149
	v_fma_f32 v194, v149, s52, -v194
	v_fmac_f32_e32 v194, 0x3377d1cf, v149
	v_fmac_f32_e32 v194, 0x3f317217, v149
	v_mov_b32_e32 v149, v194
	v_sub_f32_e32 v149, v168, v149
	v_min_f32_e32 v168, 0, v145
	v_mul_f32_e64 v145, |v145|, s57
	v_exp_f32_e32 v145, v145
	s_nop 0
	v_add_f32_e32 v145, 1.0, v145
	v_log_f32_e32 v145, v145
	s_nop 0
	v_mul_f32_e32 v194, 0x3f317217, v145
	v_fma_f32 v194, v145, s52, -v194
	v_fmac_f32_e32 v194, 0x3377d1cf, v145
	v_fmac_f32_e32 v194, 0x3f317217, v145
	v_mov_b32_e32 v145, v194
	v_sub_f32_e32 v168, v168, v145
	v_mul_f32_e32 v145, 0x3fb8aa3b, v149
	v_exp_f32_e32 v145, v145
	s_nop 0
	v_fma_f32 v145, v181, v145, v133
	v_cmp_gt_f32_e64 s[40:41], s97, v145
	s_nop 1
	v_cndmask_b32_e64 v194, 0, 32, s[40:41]
	v_ldexp_f32 v145, v145, v194
	v_log_f32_e32 v145, v145
	s_nop 0
	v_mul_f32_e32 v194, 0x3f317217, v145
	v_fma_f32 v194, v145, s52, -v194
	v_fmac_f32_e32 v194, 0x3377d1cf, v145
	v_fmac_f32_e32 v194, 0x3f317217, v145
	v_cmp_lt_f32_e64 s[42:43], |v145|, s53
	s_nop 1
	v_cndmask_b32_e64 v145, v145, v194, s[42:43]
	v_cndmask_b32_e64 v194, 0, v216, s[40:41]
	v_sub_f32_e32 v145, v145, v194
	v_cndmask_b32_e64 v145, v149, v145, s[16:17]
	v_mul_f32_e32 v149, 0x3fb8aa3b, v168
	v_exp_f32_e32 v149, v149
	s_nop 0
	v_fma_f32 v149, v180, v149, v129
	v_cmp_gt_f32_e64 s[40:41], s97, v149
	s_nop 1
	v_cndmask_b32_e64 v194, 0, 32, s[40:41]
	v_ldexp_f32 v149, v149, v194
	v_log_f32_e32 v149, v149
	s_nop 0
	v_mul_f32_e32 v194, 0x3f317217, v149
	v_fma_f32 v194, v149, s52, -v194
	v_fmac_f32_e32 v194, 0x3377d1cf, v149
	v_fmac_f32_e32 v194, 0x3f317217, v149
	v_cmp_lt_f32_e64 s[42:43], |v149|, s53
	s_nop 1
	v_cndmask_b32_e64 v149, v149, v194, s[42:43]
	v_cndmask_b32_e64 v194, 0, v216, s[40:41]
	v_sub_f32_e32 v149, v149, v194
	v_cndmask_b32_e64 v149, v168, v149, s[14:15]
	v_min_f32_e32 v168, 0, v150
	v_mul_f32_e64 v150, |v150|, s57
	v_exp_f32_e32 v150, v150
	s_nop 0
	v_add_f32_e32 v150, 1.0, v150
	v_log_f32_e32 v150, v150
	s_nop 0
	v_mul_f32_e32 v194, 0x3f317217, v150
	v_fma_f32 v194, v150, s52, -v194
; __device__ __forceinline__ float silu_f(float x) { return x * __builtin_amdgcn_rcpf(1.f + __expf(-x)); }
; __device__ __forceinline__ v4u pack8(const f32x4 a, const f32x4 b) { v4u w; w.x = cvt_pk_bf16(a[0], a[1]); w.y = cvt_pk_bf16(a[2], a[3]); w.z = cvt_pk_bf16(b[0], b[1]); w.w = cvt_pk_bf16(b[2], b[3]); return w; }
;     __device__ __forceinline__ void operator()(const f32x4 (&acc)[2][2][4][2], const pg8::Unit& u, int wr, int wc, int fr, int fq) const {
;     ...
;         if (grp == 0) { WIN_LOOP( _Pragma("unroll") for (int i = 0; i < 4; ++i) { a[i] = silu_f(a[i]); b[i] = silu_f(b[i]); } *(v4u*)(QO + (size_t)row * DM + c) = pack8(a, b); ) }
;         else if (grp == 3) { WIN_LOOP( _Pragma("unroll") for (int i = 0; i < 4; ++i) { a[i] = silu_f(a[i]); b[i] = silu_f(b[i]); } *(v4u*)(GH + (size_t)row * 512 + c) = pack8(a, b); ) }
;         else if (grp == 1) {
;             f32x4 l0[2], l1[2];
; #pragma unroll
;             for (int bj = 0; bj < 2; ++bj) { l0[bj] = *(const f32x4*)(lb + cb + bj * 128); l1[bj] = *(const f32x4*)(lb + cb + bj * 128 + 4); }
;             WIN_LOOP( _Pragma("unroll") for (int i = 0; i < 4; ++i) { const float s0 = fminf(a[i], 0.f) - __logf(1.f + __expf(-fabsf(a[i]))), s1 = fminf(b[i], 0.f) - __logf(1.f + __expf(-fabsf(b[i]))); const float la = l0[bj][i], lbv = l1[bj][i];
;                     a[i] = la > 0.f ? __logf(la + (1.f - la) * __expf(s0)) : s0; b[i] = lbv > 0.f ? __logf(lbv + (1.f - lbv) * __expf(s1)) : s1; }
;                 *(f32x4*)(LF + (size_t)row * 512 + c) = a; *(f32x4*)(LF + (size_t)row * 512 + c + 4) = b; __builtin_amdgcn_sched_barrier(0); ) }
	v_fmac_f32_e32 v194, 0x3377d1cf, v150
	v_fmac_f32_e32 v194, 0x3f317217, v150
	v_mov_b32_e32 v150, v194
	v_sub_f32_e32 v150, v168, v150
	v_min_f32_e32 v168, 0, v146
	v_mul_f32_e64 v146, |v146|, s57
	v_exp_f32_e32 v146, v146
	s_nop 0
	v_add_f32_e32 v146, 1.0, v146
	v_log_f32_e32 v146, v146
	s_nop 0
	v_mul_f32_e32 v194, 0x3f317217, v146
	v_fma_f32 v194, v146, s52, -v194
	v_fmac_f32_e32 v194, 0x3377d1cf, v146
	v_fmac_f32_e32 v194, 0x3f317217, v146
	v_mov_b32_e32 v146, v194
	v_sub_f32_e32 v168, v168, v146
	v_mul_f32_e32 v146, 0x3fb8aa3b, v150
	v_exp_f32_e32 v146, v146
	s_nop 0
	v_fma_f32 v146, v179, v146, v134
	v_cmp_gt_f32_e64 s[40:41], s97, v146
	s_nop 1
	v_cndmask_b32_e64 v194, 0, 32, s[40:41]
	v_ldexp_f32 v146, v146, v194
	v_log_f32_e32 v146, v146
	s_nop 0
	v_mul_f32_e32 v194, 0x3f317217, v146
	v_fma_f32 v194, v146, s52, -v194
	v_fmac_f32_e32 v194, 0x3377d1cf, v146
	v_fmac_f32_e32 v194, 0x3f317217, v146
	v_cmp_lt_f32_e64 s[42:43], |v146|, s53
	s_nop 1
	v_cndmask_b32_e64 v146, v146, v194, s[42:43]
	v_cndmask_b32_e64 v194, 0, v216, s[40:41]
	v_sub_f32_e32 v146, v146, v194
	v_cndmask_b32_e64 v146, v150, v146, s[12:13]
	v_mul_f32_e32 v150, 0x3fb8aa3b, v168
	v_exp_f32_e32 v150, v150
	s_nop 0
	v_fma_f32 v150, v178, v150, v130
	v_cmp_gt_f32_e64 s[40:41], s97, v150
	s_nop 1
	v_cndmask_b32_e64 v194, 0, 32, s[40:41]
	v_ldexp_f32 v150, v150, v194
	v_log_f32_e32 v150, v150
	s_nop 0
	v_mul_f32_e32 v194, 0x3f317217, v150
	v_fma_f32 v194, v150, s52, -v194
	v_fmac_f32_e32 v194, 0x3377d1cf, v150
	v_fmac_f32_e32 v194, 0x3f317217, v150
	v_cmp_lt_f32_e64 s[42:43], |v150|, s53
	s_nop 1
	v_cndmask_b32_e64 v150, v150, v194, s[42:43]
	v_cndmask_b32_e64 v194, 0, v216, s[40:41]
	v_sub_f32_e32 v150, v150, v194
	v_cndmask_b32_e64 v150, v168, v150, s[10:11]
	v_min_f32_e32 v168, 0, v151
	v_mul_f32_e64 v151, |v151|, s57
	v_exp_f32_e32 v151, v151
	s_nop 0
	v_add_f32_e32 v151, 1.0, v151
	v_log_f32_e32 v151, v151
	s_nop 0
	v_mul_f32_e32 v194, 0x3f317217, v151
	v_fma_f32 v194, v151, s52, -v194
	v_fmac_f32_e32 v194, 0x3377d1cf, v151
	v_fmac_f32_e32 v194, 0x3f317217, v151
	v_mov_b32_e32 v151, v194
	v_sub_f32_e32 v151, v168, v151
	v_min_f32_e32 v168, 0, v147
	v_mul_f32_e64 v147, |v147|, s57
	v_exp_f32_e32 v147, v147
	s_nop 0
	v_add_f32_e32 v147, 1.0, v147
	v_log_f32_e32 v147, v147
	s_nop 0
	v_mul_f32_e32 v194, 0x3f317217, v147
	v_fma_f32 v194, v147, s52, -v194
	v_fmac_f32_e32 v194, 0x3377d1cf, v147
	v_fmac_f32_e32 v194, 0x3f317217, v147
	v_mov_b32_e32 v147, v194
	v_sub_f32_e32 v168, v168, v147
	v_mul_f32_e32 v147, 0x3fb8aa3b, v151
	v_exp_f32_e32 v147, v147
	s_nop 0
	v_fma_f32 v147, v177, v147, v135
	v_cmp_gt_f32_e64 s[40:41], s97, v147
	s_nop 1
	v_cndmask_b32_e64 v194, 0, 32, s[40:41]
	v_ldexp_f32 v147, v147, v194
	v_log_f32_e32 v147, v147
	s_nop 0
	v_mul_f32_e32 v194, 0x3f317217, v147
	v_fma_f32 v194, v147, s52, -v194
	v_fmac_f32_e32 v194, 0x3377d1cf, v147
	v_fmac_f32_e32 v194, 0x3f317217, v147
	v_cmp_lt_f32_e64 s[42:43], |v147|, s53
	s_nop 1
	v_cndmask_b32_e64 v147, v147, v194, s[42:43]
	v_cndmask_b32_e64 v194, 0, v216, s[40:41]
	v_sub_f32_e32 v147, v147, v194
	v_cndmask_b32_e64 v147, v151, v147, s[8:9]
	v_mul_f32_e32 v151, 0x3fb8aa3b, v168
	v_exp_f32_e32 v151, v151
	s_nop 0
	v_fma_f32 v151, v167, v151, v131
	v_cmp_gt_f32_e64 s[40:41], s97, v151
	s_nop 1
	v_cndmask_b32_e64 v194, 0, 32, s[40:41]
	v_ldexp_f32 v151, v151, v194
	v_log_f32_e32 v151, v151
	s_nop 0
	v_mul_f32_e32 v194, 0x3f317217, v151
	v_fma_f32 v194, v151, s52, -v194
	v_fmac_f32_e32 v194, 0x3377d1cf, v151
	v_fmac_f32_e32 v194, 0x3f317217, v151
	v_cmp_lt_f32_e64 s[42:43], |v151|, s53
	s_nop 1
	v_cndmask_b32_e64 v151, v151, v194, s[42:43]
	v_cndmask_b32_e64 v194, 0, v216, s[40:41]
	v_sub_f32_e32 v151, v151, v194
	v_cndmask_b32_e32 v151, v168, v151, vcc
	global_store_dwordx4 v[170:171], v[144:147], off offset:512
	global_store_dwordx4 v[170:171], v[148:151], off offset:528
	s_nop 1
	v_add_u32_e32 v148, 0xb0, v166
	v_ashrrev_i32_e32 v149, 31, v148
	v_lshlrev_b64 v[144:145], 6, v[148:149]
	v_lshl_add_u64 v[144:145], v[160:161], 0, v[144:145]
	s_nop 0
	s_waitcnt lgkmcnt(0)
	s_nop 3
	v_lshlrev_b64 v[146:147], 11, v[148:149]
	s_nop 1
	v_lshl_add_u64 v[146:147], s[50:51], 0, v[146:147]
	v_lshl_add_u64 v[146:147], v[146:147], 0, v[192:193]
	s_waitcnt lgkmcnt(0)
	s_nop 1
	s_waitcnt lgkmcnt(0)
; __device__ __forceinline__ float silu_f(float x) { return x * __builtin_amdgcn_rcpf(1.f + __expf(-x)); }
; __device__ __forceinline__ v4u pack8(const f32x4 a, const f32x4 b) { v4u w; w.x = cvt_pk_bf16(a[0], a[1]); w.y = cvt_pk_bf16(a[2], a[3]); w.z = cvt_pk_bf16(b[0], b[1]); w.w = cvt_pk_bf16(b[2], b[3]); return w; }
;     __device__ __forceinline__ void operator()(const f32x4 (&acc)[2][2][4][2], const pg8::Unit& u, int wr, int wc, int fr, int fq) const {
;     ...
;         if (grp == 0) { WIN_LOOP( _Pragma("unroll") for (int i = 0; i < 4; ++i) { a[i] = silu_f(a[i]); b[i] = silu_f(b[i]); } *(v4u*)(QO + (size_t)row * DM + c) = pack8(a, b); ) }
;         else if (grp == 3) { WIN_LOOP( _Pragma("unroll") for (int i = 0; i < 4; ++i) { a[i] = silu_f(a[i]); b[i] = silu_f(b[i]); } *(v4u*)(GH + (size_t)row * 512 + c) = pack8(a, b); ) }
;         else if (grp == 1) {
;             f32x4 l0[2], l1[2];
; #pragma unroll
;             for (int bj = 0; bj < 2; ++bj) { l0[bj] = *(const f32x4*)(lb + cb + bj * 128); l1[bj] = *(const f32x4*)(lb + cb + bj * 128 + 4); }
;             WIN_LOOP( _Pragma("unroll") for (int i = 0; i < 4; ++i) { const float s0 = fminf(a[i], 0.f) - __logf(1.f + __expf(-fabsf(a[i]))), s1 = fminf(b[i], 0.f) - __logf(1.f + __expf(-fabsf(b[i]))); const float la = l0[bj][i], lbv = l1[bj][i];
;                     a[i] = la > 0.f ? __logf(la + (1.f - la) * __expf(s0)) : s0; b[i] = lbv > 0.f ? __logf(lbv + (1.f - lbv) * __expf(s1)) : s1; }
;                 *(f32x4*)(LF + (size_t)row * 512 + c) = a; *(f32x4*)(LF + (size_t)row * 512 + c + 4) = b; __builtin_amdgcn_sched_barrier(0); ) }
	s_nop 1
	v_mov_b32_e32 v144, v245
	s_nop 0
	v_pk_mul_f32 v[170:171], v[4:5], v[144:145] op_sel_hi:[1,0]
	v_pk_mul_f32 v[150:151], v[6:7], v[144:145] op_sel_hi:[1,0]
	v_pk_mul_f32 v[148:149], v[2:3], v[144:145] op_sel_hi:[1,0]
	v_pk_mul_f32 v[168:169], v[0:1], v[144:145] op_sel_hi:[1,0]
	v_min_f32_e32 v145, 0, v170
	v_mul_f32_e64 v170, |v170|, s57
	v_exp_f32_e32 v170, v170
	s_nop 0
	v_add_f32_e32 v170, 1.0, v170
	v_log_f32_e32 v170, v170
	s_nop 0
	v_mul_f32_e32 v194, 0x3f317217, v170
	v_fma_f32 v194, v170, s52, -v194
	v_fmac_f32_e32 v194, 0x3377d1cf, v170
	v_fmac_f32_e32 v194, 0x3f317217, v170
	v_mov_b32_e32 v170, v194
	v_sub_f32_e32 v145, v145, v170
	v_min_f32_e32 v170, 0, v168
	v_mul_f32_e64 v168, |v168|, s57
	v_exp_f32_e32 v168, v168
	s_nop 0
	v_add_f32_e32 v168, 1.0, v168
	v_log_f32_e32 v168, v168
	s_nop 0
	v_mul_f32_e32 v194, 0x3f317217, v168
	v_fma_f32 v194, v168, s52, -v194
	v_fmac_f32_e32 v194, 0x3377d1cf, v168
	v_fmac_f32_e32 v194, 0x3f317217, v168
	v_mov_b32_e32 v168, v194
	v_sub_f32_e32 v168, v170, v168
	v_mul_f32_e32 v170, 0x3fb8aa3b, v145
	v_exp_f32_e32 v170, v170
	s_nop 0
	v_fma_f32 v140, v190, v170, v140
	v_cmp_gt_f32_e64 s[40:41], s97, v140
	s_nop 1
	v_cndmask_b32_e64 v170, 0, 32, s[40:41]
	v_ldexp_f32 v140, v140, v170
	v_log_f32_e32 v140, v140
	s_nop 0
	v_mul_f32_e32 v170, 0x3f317217, v140
	v_fma_f32 v170, v140, s52, -v170
	v_fmac_f32_e32 v170, 0x3377d1cf, v140
	v_fmac_f32_e32 v170, 0x3f317217, v140
	v_cmp_lt_f32_e64 s[42:43], |v140|, s53
	s_nop 1
	v_cndmask_b32_e64 v140, v140, v170, s[42:43]
	v_cndmask_b32_e64 v170, 0, v216, s[40:41]
	v_sub_f32_e32 v140, v140, v170
	v_cndmask_b32_e64 v140, v145, v140, s[38:39]
	v_mul_f32_e32 v145, 0x3fb8aa3b, v168
	v_exp_f32_e32 v145, v145
	v_readlane_b32 s42, v255, 57
	v_readlane_b32 s43, v255, 58
	v_fma_f32 v136, v191, v145, v136
	v_cmp_gt_f32_e64 s[38:39], s97, v136
	s_nop 1
	v_cndmask_b32_e64 v145, 0, 32, s[38:39]
	v_ldexp_f32 v136, v136, v145
	v_log_f32_e32 v136, v136
	s_nop 0
	v_mul_f32_e32 v145, 0x3f317217, v136
	v_fma_f32 v145, v136, s52, -v145
	v_fmac_f32_e32 v145, 0x3377d1cf, v136
	v_fmac_f32_e32 v145, 0x3f317217, v136
	v_cmp_lt_f32_e64 s[40:41], |v136|, s53
	s_nop 1
	v_cndmask_b32_e64 v136, v136, v145, s[40:41]
	v_cndmask_b32_e64 v145, 0, v216, s[38:39]
	v_sub_f32_e32 v136, v136, v145
	v_cndmask_b32_e64 v136, v168, v136, s[36:37]
	v_mul_f32_e64 v168, |v171|, s57
	v_exp_f32_e32 v168, v168
	v_min_f32_e32 v145, 0, v171
	s_mov_b32 s40, s2
	v_add_f32_e32 v168, 1.0, v168
	v_log_f32_e32 v168, v168
	s_nop 0
	v_mul_f32_e32 v170, 0x3f317217, v168
	v_fma_f32 v170, v168, s52, -v170
	v_fmac_f32_e32 v170, 0x3377d1cf, v168
	v_fmac_f32_e32 v170, 0x3f317217, v168
	v_mov_b32_e32 v168, v170
	v_sub_f32_e32 v145, v145, v168
	v_min_f32_e32 v168, 0, v169
	v_mul_f32_e64 v169, |v169|, s57
	v_exp_f32_e32 v169, v169
	s_nop 0
	v_add_f32_e32 v169, 1.0, v169
	v_log_f32_e32 v169, v169
	s_nop 0
	v_mul_f32_e32 v170, 0x3f317217, v169
	v_fma_f32 v170, v169, s52, -v170
	v_fmac_f32_e32 v170, 0x3377d1cf, v169
	v_fmac_f32_e32 v170, 0x3f317217, v169
	v_mov_b32_e32 v169, v170
	v_sub_f32_e32 v168, v168, v169
	v_mul_f32_e32 v169, 0x3fb8aa3b, v145
	v_exp_f32_e32 v169, v169
	s_nop 0
	v_fma_f32 v141, v188, v169, v141
	v_cmp_gt_f32_e64 s[36:37], s97, v141
	s_nop 1
	v_cndmask_b32_e64 v169, 0, 32, s[36:37]
	v_ldexp_f32 v141, v141, v169
	v_log_f32_e32 v141, v141
	s_nop 0
	v_mul_f32_e32 v169, 0x3f317217, v141
	v_fma_f32 v169, v141, s52, -v169
	v_fmac_f32_e32 v169, 0x3377d1cf, v141
	v_fmac_f32_e32 v169, 0x3f317217, v141
	v_cmp_lt_f32_e64 s[38:39], |v141|, s53
	s_nop 1
	v_cndmask_b32_e64 v141, v141, v169, s[38:39]
	v_cndmask_b32_e64 v169, 0, v216, s[36:37]
	v_sub_f32_e32 v141, v141, v169
	v_cndmask_b32_e64 v141, v145, v141, s[34:35]
	v_mul_f32_e32 v145, 0x3fb8aa3b, v168
	v_exp_f32_e32 v145, v145
	v_readlane_b32 s38, v255, 53
	v_readlane_b32 s39, v255, 54
	v_fma_f32 v137, v189, v145, v137
	v_cmp_gt_f32_e64 s[34:35], s97, v137
	s_nop 1
	v_cndmask_b32_e64 v145, 0, 32, s[34:35]
	v_ldexp_f32 v137, v137, v145
	v_log_f32_e32 v137, v137
	s_nop 0
	v_mul_f32_e32 v145, 0x3f317217, v137
	v_fma_f32 v145, v137, s52, -v145
	v_fmac_f32_e32 v145, 0x3377d1cf, v137
	v_fmac_f32_e32 v145, 0x3f317217, v137
	v_cmp_lt_f32_e64 s[36:37], |v137|, s53
	s_nop 1
	v_cndmask_b32_e64 v137, v137, v145, s[36:37]
	v_cndmask_b32_e64 v145, 0, v216, s[34:35]
	v_sub_f32_e32 v137, v137, v145
	v_min_f32_e32 v145, 0, v150
	v_mul_f32_e64 v150, |v150|, s57
	v_exp_f32_e32 v150, v150
	v_cndmask_b32_e64 v137, v168, v137, s[30:31]
	v_readlane_b32 s36, v255, 51
	v_readlane_b32 s37, v255, 52
	v_add_f32_e32 v150, 1.0, v150
	v_log_f32_e32 v150, v150
	s_nop 0
	v_mul_f32_e32 v168, 0x3f317217, v150
	v_fma_f32 v168, v150, s52, -v168
	v_fmac_f32_e32 v168, 0x3377d1cf, v150
	v_fmac_f32_e32 v168, 0x3f317217, v150
	v_mov_b32_e32 v150, v168
	v_sub_f32_e32 v145, v145, v150
	v_min_f32_e32 v150, 0, v148
	v_mul_f32_e64 v148, |v148|, s57
	v_exp_f32_e32 v148, v148
	s_nop 0
	v_add_f32_e32 v148, 1.0, v148
	v_log_f32_e32 v148, v148
	s_nop 0
	v_mul_f32_e32 v168, 0x3f317217, v148
	v_fma_f32 v168, v148, s52, -v168
	v_fmac_f32_e32 v168, 0x3377d1cf, v148
	v_fmac_f32_e32 v168, 0x3f317217, v148
	v_mov_b32_e32 v148, v168
	v_sub_f32_e32 v148, v150, v148
	v_mul_f32_e32 v150, 0x3fb8aa3b, v145
	v_exp_f32_e32 v150, v150
	s_nop 0
	v_fma_f32 v142, v187, v150, v142
	v_cmp_gt_f32_e64 s[30:31], s97, v142
	s_nop 1
	v_cndmask_b32_e64 v150, 0, 32, s[30:31]
	v_ldexp_f32 v142, v142, v150
	v_log_f32_e32 v142, v142
	s_nop 0
	v_mul_f32_e32 v150, 0x3f317217, v142
	v_fma_f32 v150, v142, s52, -v150
	v_fmac_f32_e32 v150, 0x3377d1cf, v142
	v_fmac_f32_e32 v150, 0x3f317217, v142
	v_cmp_lt_f32_e64 s[34:35], |v142|, s53
	s_nop 1
; __device__ __forceinline__ float silu_f(float x) { return x * __builtin_amdgcn_rcpf(1.f + __expf(-x)); }
; __device__ __forceinline__ v4u pack8(const f32x4 a, const f32x4 b) { v4u w; w.x = cvt_pk_bf16(a[0], a[1]); w.y = cvt_pk_bf16(a[2], a[3]); w.z = cvt_pk_bf16(b[0], b[1]); w.w = cvt_pk_bf16(b[2], b[3]); return w; }
;     __device__ __forceinline__ void operator()(const f32x4 (&acc)[2][2][4][2], const pg8::Unit& u, int wr, int wc, int fr, int fq) const {
;     ...
;         if (grp == 0) { WIN_LOOP( _Pragma("unroll") for (int i = 0; i < 4; ++i) { a[i] = silu_f(a[i]); b[i] = silu_f(b[i]); } *(v4u*)(QO + (size_t)row * DM + c) = pack8(a, b); ) }
;         else if (grp == 3) { WIN_LOOP( _Pragma("unroll") for (int i = 0; i < 4; ++i) { a[i] = silu_f(a[i]); b[i] = silu_f(b[i]); } *(v4u*)(GH + (size_t)row * 512 + c) = pack8(a, b); ) }
;         else if (grp == 1) {
;             f32x4 l0[2], l1[2];
; #pragma unroll
;             for (int bj = 0; bj < 2; ++bj) { l0[bj] = *(const f32x4*)(lb + cb + bj * 128); l1[bj] = *(const f32x4*)(lb + cb + bj * 128 + 4); }
;             WIN_LOOP( _Pragma("unroll") for (int i = 0; i < 4; ++i) { const float s0 = fminf(a[i], 0.f) - __logf(1.f + __expf(-fabsf(a[i]))), s1 = fminf(b[i], 0.f) - __logf(1.f + __expf(-fabsf(b[i]))); const float la = l0[bj][i], lbv = l1[bj][i];
;                     a[i] = la > 0.f ? __logf(la + (1.f - la) * __expf(s0)) : s0; b[i] = lbv > 0.f ? __logf(lbv + (1.f - lbv) * __expf(s1)) : s1; }
;                 *(f32x4*)(LF + (size_t)row * 512 + c) = a; *(f32x4*)(LF + (size_t)row * 512 + c + 4) = b; __builtin_amdgcn_sched_barrier(0); ) }
	v_cndmask_b32_e64 v142, v142, v150, s[34:35]
	v_cndmask_b32_e64 v150, 0, v216, s[30:31]
	v_sub_f32_e32 v142, v142, v150
	v_cndmask_b32_e64 v142, v145, v142, s[28:29]
	v_mul_f32_e32 v145, 0x3fb8aa3b, v148
	v_exp_f32_e32 v145, v145
	v_readlane_b32 s34, v255, 49
	v_readlane_b32 s35, v255, 50
	v_fma_f32 v138, v186, v145, v138
	v_cmp_gt_f32_e64 s[28:29], s97, v138
	s_nop 1
	v_cndmask_b32_e64 v145, 0, 32, s[28:29]
	v_ldexp_f32 v138, v138, v145
	v_log_f32_e32 v138, v138
	s_nop 0
	v_mul_f32_e32 v145, 0x3f317217, v138
	v_fma_f32 v145, v138, s52, -v145
	v_fmac_f32_e32 v145, 0x3377d1cf, v138
	v_fmac_f32_e32 v145, 0x3f317217, v138
	v_cmp_lt_f32_e64 s[30:31], |v138|, s53
	s_nop 1
	v_cndmask_b32_e64 v138, v138, v145, s[30:31]
	v_cndmask_b32_e64 v145, 0, v216, s[28:29]
	v_sub_f32_e32 v138, v138, v145
	v_cndmask_b32_e64 v138, v148, v138, s[26:27]
	v_mul_f32_e64 v148, |v151|, s57
	v_exp_f32_e32 v148, v148
	v_min_f32_e32 v145, 0, v151
	v_readlane_b32 s30, v255, 47
	v_readlane_b32 s31, v255, 48
	v_add_f32_e32 v148, 1.0, v148
	v_log_f32_e32 v148, v148
	s_nop 0
	v_mul_f32_e32 v150, 0x3f317217, v148
	v_fma_f32 v150, v148, s52, -v150
	v_fmac_f32_e32 v150, 0x3377d1cf, v148
	v_fmac_f32_e32 v150, 0x3f317217, v148
	v_mov_b32_e32 v148, v150
	v_sub_f32_e32 v145, v145, v148
	v_min_f32_e32 v148, 0, v149
	v_mul_f32_e64 v149, |v149|, s57
	v_exp_f32_e32 v149, v149
	s_nop 0
	v_add_f32_e32 v149, 1.0, v149
	v_log_f32_e32 v149, v149
	s_nop 0
	v_mul_f32_e32 v150, 0x3f317217, v149
	v_fma_f32 v150, v149, s52, -v150
	v_fmac_f32_e32 v150, 0x3377d1cf, v149
	v_fmac_f32_e32 v150, 0x3f317217, v149
	v_mov_b32_e32 v149, v150
	v_sub_f32_e32 v148, v148, v149
	v_mul_f32_e32 v149, 0x3fb8aa3b, v145
	v_exp_f32_e32 v149, v149
	s_nop 0
	v_fmac_f32_e32 v143, v185, v149
	v_cmp_gt_f32_e64 s[26:27], s97, v143
	s_nop 1
	v_cndmask_b32_e64 v149, 0, 32, s[26:27]
	v_ldexp_f32 v143, v143, v149
	v_log_f32_e32 v143, v143
	s_nop 0
	v_mul_f32_e32 v149, 0x3f317217, v143
	v_fma_f32 v149, v143, s52, -v149
	v_fmac_f32_e32 v149, 0x3377d1cf, v143
	v_fmac_f32_e32 v149, 0x3f317217, v143
	v_cmp_lt_f32_e64 s[28:29], |v143|, s53
	s_nop 1
	v_cndmask_b32_e64 v143, v143, v149, s[28:29]
	v_cndmask_b32_e64 v149, 0, v216, s[26:27]
	v_sub_f32_e32 v143, v143, v149
	v_cndmask_b32_e64 v143, v145, v143, s[24:25]
	v_mul_f32_e32 v145, 0x3fb8aa3b, v148
	v_exp_f32_e32 v145, v145
	s_mov_b32 s29, s91
	s_mov_b32 s28, s95
	v_fmac_f32_e32 v139, v184, v145
	v_cmp_gt_f32_e64 s[24:25], s97, v139
	s_nop 1
	v_cndmask_b32_e64 v145, 0, 32, s[24:25]
	v_ldexp_f32 v139, v139, v145
	v_log_f32_e32 v139, v139
	s_nop 0
	v_mul_f32_e32 v145, 0x3f317217, v139
	v_fma_f32 v145, v139, s52, -v145
	v_fmac_f32_e32 v145, 0x3377d1cf, v139
	v_fmac_f32_e32 v145, 0x3f317217, v139
	v_cmp_lt_f32_e64 s[26:27], |v139|, s53
	s_nop 1
	v_cndmask_b32_e64 v139, v139, v145, s[26:27]
	v_cndmask_b32_e64 v145, 0, v216, s[24:25]
	v_readlane_b32 s27, v255, 56
	v_readlane_b32 s26, v255, 31
	v_sub_f32_e32 v139, v139, v145
	v_cndmask_b32_e64 v139, v148, v139, s[22:23]
	global_store_dwordx4 v[146:147], v[140:143], off
	global_store_dwordx4 v[146:147], v[136:139], off offset:16
	s_nop 0
	v_pk_mul_f32 v[142:143], v[68:69], v[144:145] op_sel_hi:[1,0]
	v_pk_mul_f32 v[138:139], v[70:71], v[144:145] op_sel_hi:[1,0]
	v_pk_mul_f32 v[136:137], v[66:67], v[144:145] op_sel_hi:[1,0]
	v_pk_mul_f32 v[140:141], v[64:65], v[144:145] op_sel_hi:[1,0]
	v_min_f32_e32 v144, 0, v142
	v_mul_f32_e64 v142, |v142|, s57
	v_exp_f32_e32 v142, v142
	s_nop 0
	v_add_f32_e32 v142, 1.0, v142
	v_log_f32_e32 v142, v142
	s_nop 0
	v_mul_f32_e32 v145, 0x3f317217, v142
	v_fma_f32 v145, v142, s52, -v145
	v_fmac_f32_e32 v145, 0x3377d1cf, v142
	v_fmac_f32_e32 v145, 0x3f317217, v142
	v_mov_b32_e32 v142, v145
	v_sub_f32_e32 v142, v144, v142
	v_min_f32_e32 v144, 0, v140
	v_mul_f32_e64 v140, |v140|, s57
	v_exp_f32_e32 v140, v140
	s_nop 0
	v_add_f32_e32 v140, 1.0, v140
	v_log_f32_e32 v140, v140
	s_nop 0
	v_mul_f32_e32 v145, 0x3f317217, v140
	v_fma_f32 v145, v140, s52, -v145
	v_fmac_f32_e32 v145, 0x3377d1cf, v140
	v_fmac_f32_e32 v145, 0x3f317217, v140
	v_mov_b32_e32 v140, v145
	v_sub_f32_e32 v140, v144, v140
	v_mul_f32_e32 v144, 0x3fb8aa3b, v142
	v_exp_f32_e32 v144, v144
	s_nop 0
	v_fma_f32 v132, v183, v144, v132
	v_cmp_gt_f32_e64 s[22:23], s97, v132
	s_nop 1
	v_cndmask_b32_e64 v144, 0, 32, s[22:23]
	v_ldexp_f32 v132, v132, v144
	v_log_f32_e32 v132, v132
	s_nop 0
	v_mul_f32_e32 v144, 0x3f317217, v132
	v_fma_f32 v144, v132, s52, -v144
	v_fmac_f32_e32 v144, 0x3377d1cf, v132
	v_fmac_f32_e32 v144, 0x3f317217, v132
	v_cmp_lt_f32_e64 s[24:25], |v132|, s53
	s_nop 1
	v_cndmask_b32_e64 v132, v132, v144, s[24:25]
	v_cndmask_b32_e64 v144, 0, v216, s[22:23]
	v_sub_f32_e32 v132, v132, v144
	v_cndmask_b32_e64 v132, v142, v132, s[20:21]
	v_mul_f32_e32 v142, 0x3fb8aa3b, v140
	v_exp_f32_e32 v142, v142
	s_nop 0
	v_fma_f32 v128, v182, v142, v128
	v_cmp_gt_f32_e64 s[20:21], s97, v128
	s_nop 1
	v_cndmask_b32_e64 v142, 0, 32, s[20:21]
	v_ldexp_f32 v128, v128, v142
	v_log_f32_e32 v128, v128
	s_nop 0
	v_mul_f32_e32 v142, 0x3f317217, v128
	v_fma_f32 v142, v128, s52, -v142
	v_fmac_f32_e32 v142, 0x3377d1cf, v128
	v_fmac_f32_e32 v142, 0x3f317217, v128
	v_cmp_lt_f32_e64 s[22:23], |v128|, s53
	s_nop 1
	v_cndmask_b32_e64 v128, v128, v142, s[22:23]
	v_cndmask_b32_e64 v142, 0, v216, s[20:21]
	v_sub_f32_e32 v128, v128, v142
	v_mul_f32_e64 v142, |v143|, s57
	v_exp_f32_e32 v142, v142
	v_cndmask_b32_e64 v128, v140, v128, s[18:19]
	v_min_f32_e32 v140, 0, v143
	v_readlane_b32 s23, v255, 55
	v_add_f32_e32 v142, 1.0, v142
	v_log_f32_e32 v142, v142
	s_nop 0
	v_mul_f32_e32 v143, 0x3f317217, v142
	v_fma_f32 v143, v142, s52, -v143
	v_fmac_f32_e32 v143, 0x3377d1cf, v142
; __device__ __forceinline__ float silu_f(float x) { return x * __builtin_amdgcn_rcpf(1.f + __expf(-x)); }
; __device__ __forceinline__ v4u pack8(const f32x4 a, const f32x4 b) { v4u w; w.x = cvt_pk_bf16(a[0], a[1]); w.y = cvt_pk_bf16(a[2], a[3]); w.z = cvt_pk_bf16(b[0], b[1]); w.w = cvt_pk_bf16(b[2], b[3]); return w; }
;     __device__ __forceinline__ void operator()(const f32x4 (&acc)[2][2][4][2], const pg8::Unit& u, int wr, int wc, int fr, int fq) const {
;     ...
;         if (grp == 0) { WIN_LOOP( _Pragma("unroll") for (int i = 0; i < 4; ++i) { a[i] = silu_f(a[i]); b[i] = silu_f(b[i]); } *(v4u*)(QO + (size_t)row * DM + c) = pack8(a, b); ) }
;         else if (grp == 3) { WIN_LOOP( _Pragma("unroll") for (int i = 0; i < 4; ++i) { a[i] = silu_f(a[i]); b[i] = silu_f(b[i]); } *(v4u*)(GH + (size_t)row * 512 + c) = pack8(a, b); ) }
;         else if (grp == 1) {
;             f32x4 l0[2], l1[2];
; #pragma unroll
;             for (int bj = 0; bj < 2; ++bj) { l0[bj] = *(const f32x4*)(lb + cb + bj * 128); l1[bj] = *(const f32x4*)(lb + cb + bj * 128 + 4); }
;             WIN_LOOP( _Pragma("unroll") for (int i = 0; i < 4; ++i) { const float s0 = fminf(a[i], 0.f) - __logf(1.f + __expf(-fabsf(a[i]))), s1 = fminf(b[i], 0.f) - __logf(1.f + __expf(-fabsf(b[i]))); const float la = l0[bj][i], lbv = l1[bj][i];
;                     a[i] = la > 0.f ? __logf(la + (1.f - la) * __expf(s0)) : s0; b[i] = lbv > 0.f ? __logf(lbv + (1.f - lbv) * __expf(s1)) : s1; }
;                 *(f32x4*)(LF + (size_t)row * 512 + c) = a; *(f32x4*)(LF + (size_t)row * 512 + c + 4) = b; __builtin_amdgcn_sched_barrier(0); ) }
	v_fmac_f32_e32 v143, 0x3f317217, v142
	v_mov_b32_e32 v142, v143
	v_sub_f32_e32 v140, v140, v142
	v_min_f32_e32 v142, 0, v141
	v_mul_f32_e64 v141, |v141|, s57
	v_exp_f32_e32 v141, v141
	s_nop 0
	v_add_f32_e32 v141, 1.0, v141
	v_log_f32_e32 v141, v141
	s_nop 0
	v_mul_f32_e32 v143, 0x3f317217, v141
	v_fma_f32 v143, v141, s52, -v143
	v_fmac_f32_e32 v143, 0x3377d1cf, v141
	v_fmac_f32_e32 v143, 0x3f317217, v141
	v_mov_b32_e32 v141, v143
	v_sub_f32_e32 v141, v142, v141
	v_mul_f32_e32 v142, 0x3fb8aa3b, v140
	v_exp_f32_e32 v142, v142
	s_nop 0
	v_fma_f32 v133, v181, v142, v133
	v_cmp_gt_f32_e64 s[18:19], s97, v133
	s_nop 1
	v_cndmask_b32_e64 v142, 0, 32, s[18:19]
	v_ldexp_f32 v133, v133, v142
	v_log_f32_e32 v133, v133
	s_nop 0
	v_mul_f32_e32 v142, 0x3f317217, v133
	v_fma_f32 v142, v133, s52, -v142
	v_fmac_f32_e32 v142, 0x3377d1cf, v133
	v_fmac_f32_e32 v142, 0x3f317217, v133
	v_cmp_lt_f32_e64 s[20:21], |v133|, s53
	s_nop 1
	v_cndmask_b32_e64 v133, v133, v142, s[20:21]
	v_cndmask_b32_e64 v142, 0, v216, s[18:19]
	v_sub_f32_e32 v133, v133, v142
	v_cndmask_b32_e64 v133, v140, v133, s[16:17]
	v_mul_f32_e32 v140, 0x3fb8aa3b, v141
	v_exp_f32_e32 v140, v140
	s_nop 0
	v_fma_f32 v129, v180, v140, v129
	v_cmp_gt_f32_e64 s[16:17], s97, v129
	s_nop 1
	v_cndmask_b32_e64 v140, 0, 32, s[16:17]
	v_ldexp_f32 v129, v129, v140
	v_log_f32_e32 v129, v129
	s_nop 0
	v_mul_f32_e32 v140, 0x3f317217, v129
	v_fma_f32 v140, v129, s52, -v140
	v_fmac_f32_e32 v140, 0x3377d1cf, v129
	v_fmac_f32_e32 v140, 0x3f317217, v129
	v_cmp_lt_f32_e64 s[18:19], |v129|, s53
	s_nop 1
	v_cndmask_b32_e64 v129, v129, v140, s[18:19]
	v_cndmask_b32_e64 v140, 0, v216, s[16:17]
	v_sub_f32_e32 v129, v129, v140
	v_min_f32_e32 v140, 0, v138
	v_mul_f32_e64 v138, |v138|, s57
	v_exp_f32_e32 v138, v138
	v_cndmask_b32_e64 v129, v141, v129, s[14:15]
	v_add_f32_e32 v138, 1.0, v138
	v_log_f32_e32 v138, v138
	s_nop 0
	v_mul_f32_e32 v141, 0x3f317217, v138
	v_fma_f32 v141, v138, s52, -v141
	v_fmac_f32_e32 v141, 0x3377d1cf, v138
	v_fmac_f32_e32 v141, 0x3f317217, v138
	v_mov_b32_e32 v138, v141
	v_sub_f32_e32 v138, v140, v138
	v_min_f32_e32 v140, 0, v136
	v_mul_f32_e64 v136, |v136|, s57
	v_exp_f32_e32 v136, v136
	s_nop 0
	v_add_f32_e32 v136, 1.0, v136
	v_log_f32_e32 v136, v136
	s_nop 0
	v_mul_f32_e32 v141, 0x3f317217, v136
	v_fma_f32 v141, v136, s52, -v141
	v_fmac_f32_e32 v141, 0x3377d1cf, v136
	v_fmac_f32_e32 v141, 0x3f317217, v136
	v_mov_b32_e32 v136, v141
	v_sub_f32_e32 v136, v140, v136
	v_mul_f32_e32 v140, 0x3fb8aa3b, v138
	v_exp_f32_e32 v140, v140
	s_nop 0
	v_fma_f32 v134, v179, v140, v134
	v_cmp_gt_f32_e64 s[14:15], s97, v134
	s_nop 1
	v_cndmask_b32_e64 v140, 0, 32, s[14:15]
	v_ldexp_f32 v134, v134, v140
	v_log_f32_e32 v134, v134
	s_nop 0
	v_mul_f32_e32 v140, 0x3f317217, v134
	v_fma_f32 v140, v134, s52, -v140
	v_fmac_f32_e32 v140, 0x3377d1cf, v134
	v_fmac_f32_e32 v140, 0x3f317217, v134
	v_cmp_lt_f32_e64 s[16:17], |v134|, s53
	s_nop 1
	v_cndmask_b32_e64 v134, v134, v140, s[16:17]
	v_cndmask_b32_e64 v140, 0, v216, s[14:15]
	v_sub_f32_e32 v134, v134, v140
	v_cndmask_b32_e64 v134, v138, v134, s[12:13]
	v_mul_f32_e32 v138, 0x3fb8aa3b, v136
	v_exp_f32_e32 v138, v138
	s_nop 0
	v_fma_f32 v130, v178, v138, v130
	v_cmp_gt_f32_e64 s[12:13], s97, v130
	s_nop 1
	v_cndmask_b32_e64 v138, 0, 32, s[12:13]
	v_ldexp_f32 v130, v130, v138
	v_log_f32_e32 v130, v130
	s_nop 0
	v_mul_f32_e32 v138, 0x3f317217, v130
	v_fma_f32 v138, v130, s52, -v138
	v_fmac_f32_e32 v138, 0x3377d1cf, v130
	v_fmac_f32_e32 v138, 0x3f317217, v130
	v_cmp_lt_f32_e64 s[14:15], |v130|, s53
	s_nop 1
	v_cndmask_b32_e64 v130, v130, v138, s[14:15]
	v_cndmask_b32_e64 v138, 0, v216, s[12:13]
	v_sub_f32_e32 v130, v130, v138
	v_mul_f32_e64 v138, |v139|, s57
	v_exp_f32_e32 v138, v138
	v_cndmask_b32_e64 v130, v136, v130, s[10:11]
	v_min_f32_e32 v136, 0, v139
	v_add_f32_e32 v138, 1.0, v138
	v_log_f32_e32 v138, v138
	s_nop 0
	v_mul_f32_e32 v139, 0x3f317217, v138
	v_fma_f32 v139, v138, s52, -v139
	v_fmac_f32_e32 v139, 0x3377d1cf, v138
	v_fmac_f32_e32 v139, 0x3f317217, v138
	v_mov_b32_e32 v138, v139
	v_sub_f32_e32 v136, v136, v138
	v_min_f32_e32 v138, 0, v137
	v_mul_f32_e64 v137, |v137|, s57
	v_exp_f32_e32 v137, v137
	s_nop 0
	v_add_f32_e32 v137, 1.0, v137
	v_log_f32_e32 v137, v137
	s_nop 0
	v_mul_f32_e32 v139, 0x3f317217, v137
	v_fma_f32 v139, v137, s52, -v139
	v_fmac_f32_e32 v139, 0x3377d1cf, v137
	v_fmac_f32_e32 v139, 0x3f317217, v137
	v_mov_b32_e32 v137, v139
	v_sub_f32_e32 v137, v138, v137
	v_mul_f32_e32 v138, 0x3fb8aa3b, v136
	v_exp_f32_e32 v138, v138
	s_nop 0
	v_fmac_f32_e32 v135, v177, v138
	v_cmp_gt_f32_e64 s[10:11], s97, v135
	s_nop 1
	v_cndmask_b32_e64 v138, 0, 32, s[10:11]
	v_ldexp_f32 v135, v135, v138
	v_log_f32_e32 v135, v135
	s_nop 0
	v_mul_f32_e32 v138, 0x3f317217, v135
	v_fma_f32 v138, v135, s52, -v138
	v_fmac_f32_e32 v138, 0x3377d1cf, v135
	v_fmac_f32_e32 v138, 0x3f317217, v135
	v_cmp_lt_f32_e64 s[12:13], |v135|, s53
	s_nop 1
	v_cndmask_b32_e64 v135, v135, v138, s[12:13]
	v_cndmask_b32_e64 v138, 0, v216, s[10:11]
	v_sub_f32_e32 v135, v135, v138
	v_cndmask_b32_e64 v135, v136, v135, s[8:9]
	v_mul_f32_e32 v136, 0x3fb8aa3b, v137
	v_exp_f32_e32 v136, v136
	s_nop 0
	v_fmac_f32_e32 v131, v167, v136
	v_cmp_gt_f32_e64 s[8:9], s97, v131
	s_nop 1
	v_cndmask_b32_e64 v136, 0, 32, s[8:9]
	v_ldexp_f32 v131, v131, v136
	v_log_f32_e32 v131, v131
	s_nop 0
	v_mul_f32_e32 v136, 0x3f317217, v131
	v_fma_f32 v136, v131, s52, -v136
	v_fmac_f32_e32 v136, 0x3377d1cf, v131
	v_fmac_f32_e32 v136, 0x3f317217, v131
	v_cmp_lt_f32_e64 s[10:11], |v131|, s53
	s_nop 1
	v_cndmask_b32_e64 v131, v131, v136, s[10:11]
	v_cndmask_b32_e64 v136, 0, v216, s[8:9]
	v_sub_f32_e32 v131, v131, v136
	v_cndmask_b32_e32 v131, v137, v131, vcc
	global_store_dwordx4 v[146:147], v[132:135], off offset:512
	global_store_dwordx4 v[146:147], v[128:131], off offset:528
